# gdn_pre forward substitution: A rows read 16 elements per ds_read_b128 (quad lanes read different pieces), element broadcast by DPP quad_perm in v_fmac/v_mul per element (same fma per component); LDS
# speedup vs baseline: 1.0085x; 1.0046x over previous
; DI void gdn_pre(const Params& p, int ch, char* smem) {
;     ...
; #pragma unroll
;   for (int i = 1; i < 64; ++i) {
;     f32x2 sa = {0.f, 0.f}, sb = {0.f, 0.f};
;     const f32x2* arow = (const f32x2*)(Amat + i * 64);
; #pragma unroll
;     for (int k = 0; k < (i >> 1); ++k) {
;       const f32x2 a2 = arow[k];
;       if (k & 1) sb = __builtin_elementwise_fma(a2, c2[k], sb);
;       else sa = __builtin_elementwise_fma(a2, c2[k], sa);
;     }
;     float tot = (sa[0] + sa[1]) + (sb[0] + sb[1]);
;     if (i & 1) tot += Amat[i * 64 + i - 1] * c2[(i - 1) >> 1][0];
;     c2[i >> 1][i & 1] -= tot;
;     __builtin_amdgcn_sched_barrier(0);
;   }
.LBB0_368:
	s_or_b64 exec, exec, s[8:9]
	ds_read_b32 v19, v33 offset:35072
	s_waitcnt lgkmcnt(0)
	v_fma_f32 v19, v19, v0, 0
	v_sub_f32_e32 v1, v1, v19
	v_and_b32_e32 v229, 3, v192
	v_lshl_add_u32 v228, v229, 4, v33
	ds_read_b128 v[196:199], v228 offset:35328
	ds_read_b128 v[212:215], v228 offset:35584
	s_waitcnt lgkmcnt(1)
	v_mul_f32_dpp v126, v196, v0 quad_perm:[0,0,0,0] row_mask:0xf bank_mask:0xf
	v_mul_f32_dpp v127, v197, v1 quad_perm:[0,0,0,0] row_mask:0xf bank_mask:0xf
	s_nop 0
	v_add_f32_e32 v19, v126, v127
	v_add_f32_e32 v19, 0, v19
	v_sub_f32_e32 v6, v6, v19
	ds_read_b128 v[196:199], v228 offset:35840
	s_waitcnt lgkmcnt(1)
	v_mul_f32_dpp v126, v212, v0 quad_perm:[0,0,0,0] row_mask:0xf bank_mask:0xf
	v_mul_f32_dpp v127, v213, v1 quad_perm:[0,0,0,0] row_mask:0xf bank_mask:0xf
	s_nop 0
	v_add_f32_e32 v19, v126, v127
	v_add_f32_e32 v19, 0, v19
	v_fmac_f32_dpp v19, v214, v6 quad_perm:[0,0,0,0] row_mask:0xf bank_mask:0xf
	v_sub_f32_e32 v7, v7, v19
	ds_read_b128 v[212:215], v228 offset:36096
	s_waitcnt lgkmcnt(1)
	v_mul_f32_dpp v126, v196, v0 quad_perm:[0,0,0,0] row_mask:0xf bank_mask:0xf
	v_mul_f32_dpp v127, v197, v1 quad_perm:[0,0,0,0] row_mask:0xf bank_mask:0xf
	v_mul_f32_dpp v128, v198, v6 quad_perm:[0,0,0,0] row_mask:0xf bank_mask:0xf
	v_mul_f32_dpp v129, v199, v7 quad_perm:[0,0,0,0] row_mask:0xf bank_mask:0xf
	v_mov_b32_e32 v144, v126
	v_mov_b32_e32 v145, v128
	v_mov_b32_e32 v128, v127
	v_pk_add_f32 v[126:127], v[144:145], v[128:129]
	s_nop 0
	v_pk_add_f32 v[126:127], v[126:127], v[126:127] op_sel:[0,1] op_sel_hi:[1,0]
	s_nop 0
	v_pk_add_f32 v[8:9], v[8:9], v[126:127] neg_lo:[0,1] neg_hi:[0,1]
	ds_read_b128 v[196:199], v228 offset:36352
	s_waitcnt lgkmcnt(1)
	v_mul_f32_dpp v126, v212, v0 quad_perm:[0,0,0,0] row_mask:0xf bank_mask:0xf
	v_mul_f32_dpp v127, v213, v1 quad_perm:[0,0,0,0] row_mask:0xf bank_mask:0xf
	v_mul_f32_dpp v128, v214, v6 quad_perm:[0,0,0,0] row_mask:0xf bank_mask:0xf
	v_mul_f32_dpp v129, v215, v7 quad_perm:[0,0,0,0] row_mask:0xf bank_mask:0xf
	v_mov_b32_e32 v144, v126
	v_mov_b32_e32 v145, v128
	v_mov_b32_e32 v128, v127
	v_pk_add_f32 v[126:127], v[144:145], v[128:129]
	s_nop 0
	v_add_f32_e32 v19, v126, v127
	v_fmac_f32_dpp v19, v212, v8 quad_perm:[1,1,1,1] row_mask:0xf bank_mask:0xf
	v_sub_f32_e32 v9, v124, v19
	ds_read_b128 v[212:215], v228 offset:36608
	s_waitcnt lgkmcnt(1)
	v_mul_f32_dpp v124, v196, v0 quad_perm:[0,0,0,0] row_mask:0xf bank_mask:0xf
	v_mul_f32_dpp v125, v197, v1 quad_perm:[0,0,0,0] row_mask:0xf bank_mask:0xf
	v_mul_f32_dpp v126, v198, v6 quad_perm:[0,0,0,0] row_mask:0xf bank_mask:0xf
	v_mul_f32_dpp v127, v199, v7 quad_perm:[0,0,0,0] row_mask:0xf bank_mask:0xf
	v_fmac_f32_dpp v124, v196, v8 quad_perm:[1,1,1,1] row_mask:0xf bank_mask:0xf
	v_fmac_f32_dpp v125, v197, v9 quad_perm:[1,1,1,1] row_mask:0xf bank_mask:0xf
	v_mov_b32_e32 v128, v126
	v_mov_b32_e32 v129, v124
	v_mov_b32_e32 v124, v127
	v_pk_add_f32 v[124:125], v[128:129], v[124:125]
	s_nop 0
	v_pk_add_f32 v[124:125], v[124:125], v[124:125] op_sel:[0,1] op_sel_hi:[1,0]
	s_nop 0
	v_pk_add_f32 v[10:11], v[10:11], v[124:125] neg_lo:[0,1] neg_hi:[0,1]
	ds_read_b128 v[196:199], v228 offset:36864
	s_waitcnt lgkmcnt(1)
	v_mul_f32_dpp v124, v212, v0 quad_perm:[0,0,0,0] row_mask:0xf bank_mask:0xf
	v_mul_f32_dpp v125, v213, v1 quad_perm:[0,0,0,0] row_mask:0xf bank_mask:0xf
	v_mul_f32_dpp v126, v214, v6 quad_perm:[0,0,0,0] row_mask:0xf bank_mask:0xf
	v_mul_f32_dpp v127, v215, v7 quad_perm:[0,0,0,0] row_mask:0xf bank_mask:0xf
	v_fmac_f32_dpp v124, v212, v8 quad_perm:[1,1,1,1] row_mask:0xf bank_mask:0xf
	v_fmac_f32_dpp v125, v213, v9 quad_perm:[1,1,1,1] row_mask:0xf bank_mask:0xf
	v_mov_b32_e32 v128, v126
	v_mov_b32_e32 v129, v124
	v_mov_b32_e32 v124, v127
	v_pk_add_f32 v[124:125], v[128:129], v[124:125]
	s_nop 0
	v_add_f32_e32 v11, v124, v125
	v_fmac_f32_dpp v11, v214, v10 quad_perm:[1,1,1,1] row_mask:0xf bank_mask:0xf
	v_sub_f32_e32 v11, v122, v11
	ds_read_b128 v[212:215], v228 offset:37120
	s_waitcnt lgkmcnt(1)
	v_mul_f32_dpp v122, v196, v0 quad_perm:[0,0,0,0] row_mask:0xf bank_mask:0xf
	v_mul_f32_dpp v123, v197, v1 quad_perm:[0,0,0,0] row_mask:0xf bank_mask:0xf
	v_mul_f32_dpp v124, v198, v6 quad_perm:[0,0,0,0] row_mask:0xf bank_mask:0xf
	v_mul_f32_dpp v125, v199, v7 quad_perm:[0,0,0,0] row_mask:0xf bank_mask:0xf
	v_fmac_f32_dpp v122, v196, v8 quad_perm:[1,1,1,1] row_mask:0xf bank_mask:0xf
	v_fmac_f32_dpp v123, v197, v9 quad_perm:[1,1,1,1] row_mask:0xf bank_mask:0xf
	v_fmac_f32_dpp v124, v198, v10 quad_perm:[1,1,1,1] row_mask:0xf bank_mask:0xf
	v_fmac_f32_dpp v125, v199, v11 quad_perm:[1,1,1,1] row_mask:0xf bank_mask:0xf
	v_mov_b32_e32 v126, v122
	v_mov_b32_e32 v127, v124
	v_mov_b32_e32 v124, v123
	v_pk_add_f32 v[122:123], v[126:127], v[124:125]
	s_nop 0
	v_pk_add_f32 v[122:123], v[122:123], v[122:123] op_sel:[0,1] op_sel_hi:[1,0]
	s_nop 0
	v_pk_add_f32 v[12:13], v[12:13], v[122:123] neg_lo:[0,1] neg_hi:[0,1]
	ds_read_b128 v[196:199], v228 offset:37376
	s_waitcnt lgkmcnt(1)
	v_mul_f32_dpp v122, v212, v0 quad_perm:[0,0,0,0] row_mask:0xf bank_mask:0xf
	v_mul_f32_dpp v123, v213, v1 quad_perm:[0,0,0,0] row_mask:0xf bank_mask:0xf
	v_mul_f32_dpp v124, v214, v6 quad_perm:[0,0,0,0] row_mask:0xf bank_mask:0xf
	v_mul_f32_dpp v125, v215, v7 quad_perm:[0,0,0,0] row_mask:0xf bank_mask:0xf
	v_fmac_f32_dpp v122, v212, v8 quad_perm:[1,1,1,1] row_mask:0xf bank_mask:0xf
	v_fmac_f32_dpp v123, v213, v9 quad_perm:[1,1,1,1] row_mask:0xf bank_mask:0xf
	v_fmac_f32_dpp v124, v214, v10 quad_perm:[1,1,1,1] row_mask:0xf bank_mask:0xf
	v_fmac_f32_dpp v125, v215, v11 quad_perm:[1,1,1,1] row_mask:0xf bank_mask:0xf
	v_mov_b32_e32 v126, v122
	v_mov_b32_e32 v127, v124
	v_mov_b32_e32 v124, v123
	v_pk_add_f32 v[122:123], v[126:127], v[124:125]
	s_nop 0
	v_add_f32_e32 v19, v122, v123
	v_fmac_f32_dpp v19, v212, v12 quad_perm:[2,2,2,2] row_mask:0xf bank_mask:0xf
	v_sub_f32_e32 v13, v120, v19
	ds_read_b128 v[212:215], v228 offset:37632
	s_waitcnt lgkmcnt(1)
; DI void gdn_pre(const Params& p, int ch, char* smem) {
;     ...
; #pragma unroll
;   for (int i = 1; i < 64; ++i) {
;     f32x2 sa = {0.f, 0.f}, sb = {0.f, 0.f};
;     const f32x2* arow = (const f32x2*)(Amat + i * 64);
; #pragma unroll
;     for (int k = 0; k < (i >> 1); ++k) {
;       const f32x2 a2 = arow[k];
;       if (k & 1) sb = __builtin_elementwise_fma(a2, c2[k], sb);
;       else sa = __builtin_elementwise_fma(a2, c2[k], sa);
;     }
;     float tot = (sa[0] + sa[1]) + (sb[0] + sb[1]);
;     if (i & 1) tot += Amat[i * 64 + i - 1] * c2[(i - 1) >> 1][0];
;     c2[i >> 1][i & 1] -= tot;
;     __builtin_amdgcn_sched_barrier(0);
;   }
	v_mul_f32_dpp v120, v196, v0 quad_perm:[0,0,0,0] row_mask:0xf bank_mask:0xf
	v_mul_f32_dpp v121, v197, v1 quad_perm:[0,0,0,0] row_mask:0xf bank_mask:0xf
	v_mul_f32_dpp v122, v198, v6 quad_perm:[0,0,0,0] row_mask:0xf bank_mask:0xf
	v_mul_f32_dpp v123, v199, v7 quad_perm:[0,0,0,0] row_mask:0xf bank_mask:0xf
	v_fmac_f32_dpp v120, v196, v8 quad_perm:[1,1,1,1] row_mask:0xf bank_mask:0xf
	v_fmac_f32_dpp v121, v197, v9 quad_perm:[1,1,1,1] row_mask:0xf bank_mask:0xf
	v_fmac_f32_dpp v122, v198, v10 quad_perm:[1,1,1,1] row_mask:0xf bank_mask:0xf
	v_fmac_f32_dpp v123, v199, v11 quad_perm:[1,1,1,1] row_mask:0xf bank_mask:0xf
	v_fmac_f32_dpp v120, v196, v12 quad_perm:[2,2,2,2] row_mask:0xf bank_mask:0xf
	v_fmac_f32_dpp v121, v197, v13 quad_perm:[2,2,2,2] row_mask:0xf bank_mask:0xf
	v_mov_b32_e32 v124, v122
	v_mov_b32_e32 v125, v120
	v_mov_b32_e32 v120, v123
	v_pk_add_f32 v[120:121], v[124:125], v[120:121]
	s_nop 0
	v_pk_add_f32 v[120:121], v[120:121], v[120:121] op_sel:[0,1] op_sel_hi:[1,0]
	s_nop 0
	v_pk_add_f32 v[16:17], v[16:17], v[120:121] neg_lo:[0,1] neg_hi:[0,1]
	ds_read_b128 v[196:199], v228 offset:37888
	s_waitcnt lgkmcnt(1)
	v_mul_f32_dpp v120, v212, v0 quad_perm:[0,0,0,0] row_mask:0xf bank_mask:0xf
	v_mul_f32_dpp v121, v213, v1 quad_perm:[0,0,0,0] row_mask:0xf bank_mask:0xf
	v_mul_f32_dpp v122, v214, v6 quad_perm:[0,0,0,0] row_mask:0xf bank_mask:0xf
	v_mul_f32_dpp v123, v215, v7 quad_perm:[0,0,0,0] row_mask:0xf bank_mask:0xf
	v_fmac_f32_dpp v120, v212, v8 quad_perm:[1,1,1,1] row_mask:0xf bank_mask:0xf
	v_fmac_f32_dpp v121, v213, v9 quad_perm:[1,1,1,1] row_mask:0xf bank_mask:0xf
	v_fmac_f32_dpp v122, v214, v10 quad_perm:[1,1,1,1] row_mask:0xf bank_mask:0xf
	v_fmac_f32_dpp v123, v215, v11 quad_perm:[1,1,1,1] row_mask:0xf bank_mask:0xf
	v_fmac_f32_dpp v120, v212, v12 quad_perm:[2,2,2,2] row_mask:0xf bank_mask:0xf
	v_fmac_f32_dpp v121, v213, v13 quad_perm:[2,2,2,2] row_mask:0xf bank_mask:0xf
	v_mov_b32_e32 v124, v122
	v_mov_b32_e32 v125, v120
	v_mov_b32_e32 v120, v123
	v_pk_add_f32 v[120:121], v[124:125], v[120:121]
	s_nop 0
	v_add_f32_e32 v17, v120, v121
	v_fmac_f32_dpp v17, v214, v16 quad_perm:[2,2,2,2] row_mask:0xf bank_mask:0xf
	v_sub_f32_e32 v17, v118, v17
	ds_read_b128 v[212:215], v228 offset:38144
	s_waitcnt lgkmcnt(1)
	v_mul_f32_dpp v118, v196, v0 quad_perm:[0,0,0,0] row_mask:0xf bank_mask:0xf
	v_mul_f32_dpp v119, v197, v1 quad_perm:[0,0,0,0] row_mask:0xf bank_mask:0xf
	v_mul_f32_dpp v120, v198, v6 quad_perm:[0,0,0,0] row_mask:0xf bank_mask:0xf
	v_mul_f32_dpp v121, v199, v7 quad_perm:[0,0,0,0] row_mask:0xf bank_mask:0xf
	v_fmac_f32_dpp v118, v196, v8 quad_perm:[1,1,1,1] row_mask:0xf bank_mask:0xf
	v_fmac_f32_dpp v119, v197, v9 quad_perm:[1,1,1,1] row_mask:0xf bank_mask:0xf
	v_fmac_f32_dpp v120, v198, v10 quad_perm:[1,1,1,1] row_mask:0xf bank_mask:0xf
	v_fmac_f32_dpp v121, v199, v11 quad_perm:[1,1,1,1] row_mask:0xf bank_mask:0xf
	v_fmac_f32_dpp v118, v196, v12 quad_perm:[2,2,2,2] row_mask:0xf bank_mask:0xf
	v_fmac_f32_dpp v119, v197, v13 quad_perm:[2,2,2,2] row_mask:0xf bank_mask:0xf
	v_fmac_f32_dpp v120, v198, v16 quad_perm:[2,2,2,2] row_mask:0xf bank_mask:0xf
	v_fmac_f32_dpp v121, v199, v17 quad_perm:[2,2,2,2] row_mask:0xf bank_mask:0xf
	v_mov_b32_e32 v122, v118
	v_mov_b32_e32 v123, v120
	v_mov_b32_e32 v120, v119
	v_pk_add_f32 v[118:119], v[122:123], v[120:121]
	s_nop 0
	v_pk_add_f32 v[118:119], v[118:119], v[118:119] op_sel:[0,1] op_sel_hi:[1,0]
	s_nop 0
	v_pk_add_f32 v[20:21], v[20:21], v[118:119] neg_lo:[0,1] neg_hi:[0,1]
	ds_read_b128 v[196:199], v228 offset:38400
	s_waitcnt lgkmcnt(1)
	v_mul_f32_dpp v118, v212, v0 quad_perm:[0,0,0,0] row_mask:0xf bank_mask:0xf
	v_mul_f32_dpp v119, v213, v1 quad_perm:[0,0,0,0] row_mask:0xf bank_mask:0xf
	v_mul_f32_dpp v120, v214, v6 quad_perm:[0,0,0,0] row_mask:0xf bank_mask:0xf
	v_mul_f32_dpp v121, v215, v7 quad_perm:[0,0,0,0] row_mask:0xf bank_mask:0xf
	v_fmac_f32_dpp v118, v212, v8 quad_perm:[1,1,1,1] row_mask:0xf bank_mask:0xf
	v_fmac_f32_dpp v119, v213, v9 quad_perm:[1,1,1,1] row_mask:0xf bank_mask:0xf
	v_fmac_f32_dpp v120, v214, v10 quad_perm:[1,1,1,1] row_mask:0xf bank_mask:0xf
	v_fmac_f32_dpp v121, v215, v11 quad_perm:[1,1,1,1] row_mask:0xf bank_mask:0xf
	v_fmac_f32_dpp v118, v212, v12 quad_perm:[2,2,2,2] row_mask:0xf bank_mask:0xf
	v_fmac_f32_dpp v119, v213, v13 quad_perm:[2,2,2,2] row_mask:0xf bank_mask:0xf
	v_fmac_f32_dpp v120, v214, v16 quad_perm:[2,2,2,2] row_mask:0xf bank_mask:0xf
	v_fmac_f32_dpp v121, v215, v17 quad_perm:[2,2,2,2] row_mask:0xf bank_mask:0xf
	v_mov_b32_e32 v122, v118
	v_mov_b32_e32 v123, v120
	v_mov_b32_e32 v120, v119
	v_pk_add_f32 v[118:119], v[122:123], v[120:121]
	s_nop 0
	v_add_f32_e32 v21, v118, v119
	v_fmac_f32_dpp v21, v212, v20 quad_perm:[3,3,3,3] row_mask:0xf bank_mask:0xf
	v_sub_f32_e32 v21, v116, v21
	ds_read_b128 v[212:215], v228 offset:38656
	s_waitcnt lgkmcnt(1)
	v_mul_f32_dpp v116, v196, v0 quad_perm:[0,0,0,0] row_mask:0xf bank_mask:0xf
	v_mul_f32_dpp v117, v197, v1 quad_perm:[0,0,0,0] row_mask:0xf bank_mask:0xf
	v_mul_f32_dpp v118, v198, v6 quad_perm:[0,0,0,0] row_mask:0xf bank_mask:0xf
	v_mul_f32_dpp v119, v199, v7 quad_perm:[0,0,0,0] row_mask:0xf bank_mask:0xf
	v_fmac_f32_dpp v116, v196, v8 quad_perm:[1,1,1,1] row_mask:0xf bank_mask:0xf
	v_fmac_f32_dpp v117, v197, v9 quad_perm:[1,1,1,1] row_mask:0xf bank_mask:0xf
	v_fmac_f32_dpp v118, v198, v10 quad_perm:[1,1,1,1] row_mask:0xf bank_mask:0xf
	v_fmac_f32_dpp v119, v199, v11 quad_perm:[1,1,1,1] row_mask:0xf bank_mask:0xf
	v_fmac_f32_dpp v116, v196, v12 quad_perm:[2,2,2,2] row_mask:0xf bank_mask:0xf
	v_fmac_f32_dpp v117, v197, v13 quad_perm:[2,2,2,2] row_mask:0xf bank_mask:0xf
	v_fmac_f32_dpp v118, v198, v16 quad_perm:[2,2,2,2] row_mask:0xf bank_mask:0xf
	v_fmac_f32_dpp v119, v199, v17 quad_perm:[2,2,2,2] row_mask:0xf bank_mask:0xf
	v_fmac_f32_dpp v116, v196, v20 quad_perm:[3,3,3,3] row_mask:0xf bank_mask:0xf
	v_fmac_f32_dpp v117, v197, v21 quad_perm:[3,3,3,3] row_mask:0xf bank_mask:0xf
	v_mov_b32_e32 v120, v118
	v_mov_b32_e32 v121, v116
	v_mov_b32_e32 v116, v119
	v_pk_add_f32 v[116:117], v[120:121], v[116:117]
	s_nop 0
	v_pk_add_f32 v[116:117], v[116:117], v[116:117] op_sel:[0,1] op_sel_hi:[1,0]
	s_nop 0
	v_pk_add_f32 v[22:23], v[22:23], v[116:117] neg_lo:[0,1] neg_hi:[0,1]
	ds_read_b128 v[196:199], v228 offset:38912
	s_waitcnt lgkmcnt(1)
; DI void gdn_pre(const Params& p, int ch, char* smem) {
;     ...
; #pragma unroll
;   for (int i = 1; i < 64; ++i) {
;     f32x2 sa = {0.f, 0.f}, sb = {0.f, 0.f};
;     const f32x2* arow = (const f32x2*)(Amat + i * 64);
; #pragma unroll
;     for (int k = 0; k < (i >> 1); ++k) {
;       const f32x2 a2 = arow[k];
;       if (k & 1) sb = __builtin_elementwise_fma(a2, c2[k], sb);
;       else sa = __builtin_elementwise_fma(a2, c2[k], sa);
;     }
;     float tot = (sa[0] + sa[1]) + (sb[0] + sb[1]);
;     if (i & 1) tot += Amat[i * 64 + i - 1] * c2[(i - 1) >> 1][0];
;     c2[i >> 1][i & 1] -= tot;
;     __builtin_amdgcn_sched_barrier(0);
;   }
	v_mul_f32_dpp v116, v212, v0 quad_perm:[0,0,0,0] row_mask:0xf bank_mask:0xf
	v_mul_f32_dpp v117, v213, v1 quad_perm:[0,0,0,0] row_mask:0xf bank_mask:0xf
	v_mul_f32_dpp v118, v214, v6 quad_perm:[0,0,0,0] row_mask:0xf bank_mask:0xf
	v_mul_f32_dpp v119, v215, v7 quad_perm:[0,0,0,0] row_mask:0xf bank_mask:0xf
	v_fmac_f32_dpp v116, v212, v8 quad_perm:[1,1,1,1] row_mask:0xf bank_mask:0xf
	v_fmac_f32_dpp v117, v213, v9 quad_perm:[1,1,1,1] row_mask:0xf bank_mask:0xf
	v_fmac_f32_dpp v118, v214, v10 quad_perm:[1,1,1,1] row_mask:0xf bank_mask:0xf
	v_fmac_f32_dpp v119, v215, v11 quad_perm:[1,1,1,1] row_mask:0xf bank_mask:0xf
	v_fmac_f32_dpp v116, v212, v12 quad_perm:[2,2,2,2] row_mask:0xf bank_mask:0xf
	v_fmac_f32_dpp v117, v213, v13 quad_perm:[2,2,2,2] row_mask:0xf bank_mask:0xf
	v_fmac_f32_dpp v118, v214, v16 quad_perm:[2,2,2,2] row_mask:0xf bank_mask:0xf
	v_fmac_f32_dpp v119, v215, v17 quad_perm:[2,2,2,2] row_mask:0xf bank_mask:0xf
	v_fmac_f32_dpp v116, v212, v20 quad_perm:[3,3,3,3] row_mask:0xf bank_mask:0xf
	v_fmac_f32_dpp v117, v213, v21 quad_perm:[3,3,3,3] row_mask:0xf bank_mask:0xf
	v_mov_b32_e32 v120, v118
	v_mov_b32_e32 v121, v116
	v_mov_b32_e32 v116, v119
	v_pk_add_f32 v[116:117], v[120:121], v[116:117]
	s_nop 0
	v_add_f32_e32 v19, v116, v117
	v_fmac_f32_dpp v19, v214, v22 quad_perm:[3,3,3,3] row_mask:0xf bank_mask:0xf
	v_sub_f32_e32 v23, v114, v19
	ds_read_b128 v[212:215], v228 offset:39168
	ds_read_b128 v[216:219], v228 offset:39232
	s_waitcnt lgkmcnt(2)
	v_mul_f32_dpp v114, v196, v0 quad_perm:[0,0,0,0] row_mask:0xf bank_mask:0xf
	v_mul_f32_dpp v115, v197, v1 quad_perm:[0,0,0,0] row_mask:0xf bank_mask:0xf
	v_mul_f32_dpp v116, v198, v6 quad_perm:[0,0,0,0] row_mask:0xf bank_mask:0xf
	v_mul_f32_dpp v117, v199, v7 quad_perm:[0,0,0,0] row_mask:0xf bank_mask:0xf
	v_fmac_f32_dpp v114, v196, v8 quad_perm:[1,1,1,1] row_mask:0xf bank_mask:0xf
	v_fmac_f32_dpp v115, v197, v9 quad_perm:[1,1,1,1] row_mask:0xf bank_mask:0xf
	v_fmac_f32_dpp v116, v198, v10 quad_perm:[1,1,1,1] row_mask:0xf bank_mask:0xf
	v_fmac_f32_dpp v117, v199, v11 quad_perm:[1,1,1,1] row_mask:0xf bank_mask:0xf
	v_fmac_f32_dpp v114, v196, v12 quad_perm:[2,2,2,2] row_mask:0xf bank_mask:0xf
	v_fmac_f32_dpp v115, v197, v13 quad_perm:[2,2,2,2] row_mask:0xf bank_mask:0xf
	v_fmac_f32_dpp v116, v198, v16 quad_perm:[2,2,2,2] row_mask:0xf bank_mask:0xf
	v_fmac_f32_dpp v117, v199, v17 quad_perm:[2,2,2,2] row_mask:0xf bank_mask:0xf
	v_fmac_f32_dpp v114, v196, v20 quad_perm:[3,3,3,3] row_mask:0xf bank_mask:0xf
	v_fmac_f32_dpp v115, v197, v21 quad_perm:[3,3,3,3] row_mask:0xf bank_mask:0xf
	v_fmac_f32_dpp v116, v198, v22 quad_perm:[3,3,3,3] row_mask:0xf bank_mask:0xf
	v_fmac_f32_dpp v117, v199, v23 quad_perm:[3,3,3,3] row_mask:0xf bank_mask:0xf
	v_mov_b32_e32 v118, v114
	v_mov_b32_e32 v119, v116
	v_mov_b32_e32 v116, v115
	v_pk_add_f32 v[114:115], v[118:119], v[116:117]
	s_nop 0
	v_pk_add_f32 v[114:115], v[114:115], v[114:115] op_sel:[0,1] op_sel_hi:[1,0]
	s_nop 0
	v_pk_add_f32 v[24:25], v[24:25], v[114:115] neg_lo:[0,1] neg_hi:[0,1]
	ds_read_b128 v[196:199], v228 offset:39424
	ds_read_b128 v[200:203], v228 offset:39488
	s_waitcnt lgkmcnt(2)
	v_mul_f32_dpp v114, v212, v0 quad_perm:[0,0,0,0] row_mask:0xf bank_mask:0xf
	v_mul_f32_dpp v115, v213, v1 quad_perm:[0,0,0,0] row_mask:0xf bank_mask:0xf
	v_mul_f32_dpp v116, v214, v6 quad_perm:[0,0,0,0] row_mask:0xf bank_mask:0xf
	v_mul_f32_dpp v117, v215, v7 quad_perm:[0,0,0,0] row_mask:0xf bank_mask:0xf
	v_fmac_f32_dpp v114, v212, v8 quad_perm:[1,1,1,1] row_mask:0xf bank_mask:0xf
	v_fmac_f32_dpp v115, v213, v9 quad_perm:[1,1,1,1] row_mask:0xf bank_mask:0xf
	v_fmac_f32_dpp v116, v214, v10 quad_perm:[1,1,1,1] row_mask:0xf bank_mask:0xf
	v_fmac_f32_dpp v117, v215, v11 quad_perm:[1,1,1,1] row_mask:0xf bank_mask:0xf
	v_fmac_f32_dpp v114, v212, v12 quad_perm:[2,2,2,2] row_mask:0xf bank_mask:0xf
	v_fmac_f32_dpp v115, v213, v13 quad_perm:[2,2,2,2] row_mask:0xf bank_mask:0xf
	v_fmac_f32_dpp v116, v214, v16 quad_perm:[2,2,2,2] row_mask:0xf bank_mask:0xf
	v_fmac_f32_dpp v117, v215, v17 quad_perm:[2,2,2,2] row_mask:0xf bank_mask:0xf
	v_fmac_f32_dpp v114, v212, v20 quad_perm:[3,3,3,3] row_mask:0xf bank_mask:0xf
	v_fmac_f32_dpp v115, v213, v21 quad_perm:[3,3,3,3] row_mask:0xf bank_mask:0xf
	v_fmac_f32_dpp v116, v214, v22 quad_perm:[3,3,3,3] row_mask:0xf bank_mask:0xf
	v_fmac_f32_dpp v117, v215, v23 quad_perm:[3,3,3,3] row_mask:0xf bank_mask:0xf
	v_mov_b32_e32 v118, v114
	v_mov_b32_e32 v119, v116
	v_mov_b32_e32 v116, v115
	v_pk_add_f32 v[114:115], v[118:119], v[116:117]
	s_nop 0
	v_add_f32_e32 v25, v114, v115
	v_fmac_f32_dpp v25, v216, v24 quad_perm:[0,0,0,0] row_mask:0xf bank_mask:0xf
	v_sub_f32_e32 v25, v112, v25
	ds_read_b128 v[212:215], v228 offset:39680
	ds_read_b128 v[216:219], v228 offset:39744
	s_waitcnt lgkmcnt(2)
; DI void gdn_pre(const Params& p, int ch, char* smem) {
;     ...
; #pragma unroll
;   for (int i = 1; i < 64; ++i) {
;     f32x2 sa = {0.f, 0.f}, sb = {0.f, 0.f};
;     const f32x2* arow = (const f32x2*)(Amat + i * 64);
; #pragma unroll
;     for (int k = 0; k < (i >> 1); ++k) {
;       const f32x2 a2 = arow[k];
;       if (k & 1) sb = __builtin_elementwise_fma(a2, c2[k], sb);
;       else sa = __builtin_elementwise_fma(a2, c2[k], sa);
;     }
;     float tot = (sa[0] + sa[1]) + (sb[0] + sb[1]);
;     if (i & 1) tot += Amat[i * 64 + i - 1] * c2[(i - 1) >> 1][0];
;     c2[i >> 1][i & 1] -= tot;
;     __builtin_amdgcn_sched_barrier(0);
;   }
	v_mul_f32_dpp v112, v196, v0 quad_perm:[0,0,0,0] row_mask:0xf bank_mask:0xf
	v_mul_f32_dpp v113, v197, v1 quad_perm:[0,0,0,0] row_mask:0xf bank_mask:0xf
	v_fmac_f32_dpp v112, v196, v8 quad_perm:[1,1,1,1] row_mask:0xf bank_mask:0xf
	v_fmac_f32_dpp v113, v197, v9 quad_perm:[1,1,1,1] row_mask:0xf bank_mask:0xf
	v_mul_f32_dpp v114, v198, v6 quad_perm:[0,0,0,0] row_mask:0xf bank_mask:0xf
	v_mul_f32_dpp v115, v199, v7 quad_perm:[0,0,0,0] row_mask:0xf bank_mask:0xf
	v_fmac_f32_dpp v112, v196, v12 quad_perm:[2,2,2,2] row_mask:0xf bank_mask:0xf
	v_fmac_f32_dpp v113, v197, v13 quad_perm:[2,2,2,2] row_mask:0xf bank_mask:0xf
	v_fmac_f32_dpp v114, v198, v10 quad_perm:[1,1,1,1] row_mask:0xf bank_mask:0xf
	v_fmac_f32_dpp v115, v199, v11 quad_perm:[1,1,1,1] row_mask:0xf bank_mask:0xf
	v_fmac_f32_dpp v112, v196, v20 quad_perm:[3,3,3,3] row_mask:0xf bank_mask:0xf
	v_fmac_f32_dpp v113, v197, v21 quad_perm:[3,3,3,3] row_mask:0xf bank_mask:0xf
	v_fmac_f32_dpp v114, v198, v16 quad_perm:[2,2,2,2] row_mask:0xf bank_mask:0xf
	v_fmac_f32_dpp v115, v199, v17 quad_perm:[2,2,2,2] row_mask:0xf bank_mask:0xf
	v_fmac_f32_dpp v112, v200, v24 quad_perm:[0,0,0,0] row_mask:0xf bank_mask:0xf
	v_fmac_f32_dpp v113, v201, v25 quad_perm:[0,0,0,0] row_mask:0xf bank_mask:0xf
	v_fmac_f32_dpp v114, v198, v22 quad_perm:[3,3,3,3] row_mask:0xf bank_mask:0xf
	v_fmac_f32_dpp v115, v199, v23 quad_perm:[3,3,3,3] row_mask:0xf bank_mask:0xf
	v_mov_b32_e32 v117, v112
	v_mov_b32_e32 v116, v114
	v_mov_b32_e32 v112, v115
	v_pk_add_f32 v[112:113], v[116:117], v[112:113]
	s_nop 0
	v_pk_add_f32 v[112:113], v[112:113], v[112:113] op_sel:[0,1] op_sel_hi:[1,0]
	s_nop 0
	v_pk_add_f32 v[26:27], v[26:27], v[112:113] neg_lo:[0,1] neg_hi:[0,1]
	ds_read_b128 v[196:199], v228 offset:39936
	ds_read_b128 v[200:203], v228 offset:40000
	s_waitcnt lgkmcnt(2)
	v_mul_f32_dpp v112, v212, v0 quad_perm:[0,0,0,0] row_mask:0xf bank_mask:0xf
	v_mul_f32_dpp v113, v213, v1 quad_perm:[0,0,0,0] row_mask:0xf bank_mask:0xf
	v_mul_f32_dpp v114, v214, v6 quad_perm:[0,0,0,0] row_mask:0xf bank_mask:0xf
	v_mul_f32_dpp v115, v215, v7 quad_perm:[0,0,0,0] row_mask:0xf bank_mask:0xf
	v_mov_b32_e32 v116, v112
	v_fmac_f32_dpp v116, v212, v8 quad_perm:[1,1,1,1] row_mask:0xf bank_mask:0xf
	v_mov_b32_e32 v117, v113
	v_fmac_f32_dpp v117, v213, v9 quad_perm:[1,1,1,1] row_mask:0xf bank_mask:0xf
	v_mov_b32_e32 v118, v114
	v_fmac_f32_dpp v118, v214, v10 quad_perm:[1,1,1,1] row_mask:0xf bank_mask:0xf
	v_mov_b32_e32 v119, v115
	v_fmac_f32_dpp v119, v215, v11 quad_perm:[1,1,1,1] row_mask:0xf bank_mask:0xf
	v_fmac_f32_dpp v116, v212, v12 quad_perm:[2,2,2,2] row_mask:0xf bank_mask:0xf
	v_fmac_f32_dpp v117, v213, v13 quad_perm:[2,2,2,2] row_mask:0xf bank_mask:0xf
	v_fmac_f32_dpp v118, v214, v16 quad_perm:[2,2,2,2] row_mask:0xf bank_mask:0xf
	v_fmac_f32_dpp v119, v215, v17 quad_perm:[2,2,2,2] row_mask:0xf bank_mask:0xf
	v_fmac_f32_dpp v116, v212, v20 quad_perm:[3,3,3,3] row_mask:0xf bank_mask:0xf
	v_fmac_f32_dpp v117, v213, v21 quad_perm:[3,3,3,3] row_mask:0xf bank_mask:0xf
	v_fmac_f32_dpp v118, v214, v22 quad_perm:[3,3,3,3] row_mask:0xf bank_mask:0xf
	v_fmac_f32_dpp v119, v215, v23 quad_perm:[3,3,3,3] row_mask:0xf bank_mask:0xf
	v_mov_b32_e32 v112, v116
	v_fmac_f32_dpp v112, v216, v24 quad_perm:[0,0,0,0] row_mask:0xf bank_mask:0xf
	v_mov_b32_e32 v113, v117
	v_fmac_f32_dpp v113, v217, v25 quad_perm:[0,0,0,0] row_mask:0xf bank_mask:0xf
	v_mov_b32_e32 v116, v118
	v_mov_b32_e32 v117, v112
	v_mov_b32_e32 v112, v119
	v_pk_add_f32 v[112:113], v[116:117], v[112:113]
	s_nop 0
	v_add_f32_e32 v19, v112, v113
	v_fmac_f32_dpp v19, v218, v26 quad_perm:[0,0,0,0] row_mask:0xf bank_mask:0xf
	v_sub_f32_e32 v27, v36, v19
	ds_read_b128 v[212:215], v228 offset:40192
	ds_read_b128 v[216:219], v228 offset:40256
	s_waitcnt lgkmcnt(2)
	v_mul_f32_dpp v36, v196, v0 quad_perm:[0,0,0,0] row_mask:0xf bank_mask:0xf
	v_mul_f32_dpp v37, v197, v1 quad_perm:[0,0,0,0] row_mask:0xf bank_mask:0xf
	v_mul_f32_dpp v112, v198, v6 quad_perm:[0,0,0,0] row_mask:0xf bank_mask:0xf
	v_mul_f32_dpp v113, v199, v7 quad_perm:[0,0,0,0] row_mask:0xf bank_mask:0xf
	v_fmac_f32_dpp v36, v196, v8 quad_perm:[1,1,1,1] row_mask:0xf bank_mask:0xf
	v_fmac_f32_dpp v37, v197, v9 quad_perm:[1,1,1,1] row_mask:0xf bank_mask:0xf
	v_mov_b32_e32 v116, v112
	v_fmac_f32_dpp v116, v198, v10 quad_perm:[1,1,1,1] row_mask:0xf bank_mask:0xf
	v_mov_b32_e32 v117, v113
	v_fmac_f32_dpp v117, v199, v11 quad_perm:[1,1,1,1] row_mask:0xf bank_mask:0xf
	v_fmac_f32_dpp v36, v196, v12 quad_perm:[2,2,2,2] row_mask:0xf bank_mask:0xf
	v_fmac_f32_dpp v37, v197, v13 quad_perm:[2,2,2,2] row_mask:0xf bank_mask:0xf
	v_fmac_f32_dpp v116, v198, v16 quad_perm:[2,2,2,2] row_mask:0xf bank_mask:0xf
	v_fmac_f32_dpp v117, v199, v17 quad_perm:[2,2,2,2] row_mask:0xf bank_mask:0xf
	v_fmac_f32_dpp v36, v196, v20 quad_perm:[3,3,3,3] row_mask:0xf bank_mask:0xf
	v_fmac_f32_dpp v37, v197, v21 quad_perm:[3,3,3,3] row_mask:0xf bank_mask:0xf
	v_fmac_f32_dpp v116, v198, v22 quad_perm:[3,3,3,3] row_mask:0xf bank_mask:0xf
	v_fmac_f32_dpp v117, v199, v23 quad_perm:[3,3,3,3] row_mask:0xf bank_mask:0xf
	v_fmac_f32_dpp v36, v200, v24 quad_perm:[0,0,0,0] row_mask:0xf bank_mask:0xf
	v_fmac_f32_dpp v37, v201, v25 quad_perm:[0,0,0,0] row_mask:0xf bank_mask:0xf
	v_mov_b32_e32 v112, v116
	v_fmac_f32_dpp v112, v202, v26 quad_perm:[0,0,0,0] row_mask:0xf bank_mask:0xf
	v_mov_b32_e32 v113, v117
	v_fmac_f32_dpp v113, v203, v27 quad_perm:[0,0,0,0] row_mask:0xf bank_mask:0xf
	v_mov_b32_e32 v114, v36
	v_mov_b32_e32 v115, v112
	v_mov_b32_e32 v112, v37
	v_pk_add_f32 v[36:37], v[114:115], v[112:113]
	s_nop 0
	v_pk_add_f32 v[36:37], v[36:37], v[36:37] op_sel:[0,1] op_sel_hi:[1,0]
	s_nop 0
	v_pk_add_f32 v[36:37], v[108:109], v[36:37] neg_lo:[0,1] neg_hi:[0,1]
	ds_read_b128 v[196:199], v228 offset:40448
	ds_read_b128 v[200:203], v228 offset:40512
	s_waitcnt lgkmcnt(2)
; DI void gdn_pre(const Params& p, int ch, char* smem) {
;     ...
; #pragma unroll
;   for (int i = 1; i < 64; ++i) {
;     f32x2 sa = {0.f, 0.f}, sb = {0.f, 0.f};
;     const f32x2* arow = (const f32x2*)(Amat + i * 64);
; #pragma unroll
;     for (int k = 0; k < (i >> 1); ++k) {
;       const f32x2 a2 = arow[k];
;       if (k & 1) sb = __builtin_elementwise_fma(a2, c2[k], sb);
;       else sa = __builtin_elementwise_fma(a2, c2[k], sa);
;     }
;     float tot = (sa[0] + sa[1]) + (sb[0] + sb[1]);
;     if (i & 1) tot += Amat[i * 64 + i - 1] * c2[(i - 1) >> 1][0];
;     c2[i >> 1][i & 1] -= tot;
;     __builtin_amdgcn_sched_barrier(0);
;   }
	v_mul_f32_dpp v108, v212, v0 quad_perm:[0,0,0,0] row_mask:0xf bank_mask:0xf
	v_mul_f32_dpp v109, v213, v1 quad_perm:[0,0,0,0] row_mask:0xf bank_mask:0xf
	v_mul_f32_dpp v112, v214, v6 quad_perm:[0,0,0,0] row_mask:0xf bank_mask:0xf
	v_mul_f32_dpp v113, v215, v7 quad_perm:[0,0,0,0] row_mask:0xf bank_mask:0xf
	v_fmac_f32_dpp v108, v212, v8 quad_perm:[1,1,1,1] row_mask:0xf bank_mask:0xf
	v_fmac_f32_dpp v109, v213, v9 quad_perm:[1,1,1,1] row_mask:0xf bank_mask:0xf
	v_mov_b32_e32 v116, v112
	v_fmac_f32_dpp v116, v214, v10 quad_perm:[1,1,1,1] row_mask:0xf bank_mask:0xf
	v_mov_b32_e32 v117, v113
	v_fmac_f32_dpp v117, v215, v11 quad_perm:[1,1,1,1] row_mask:0xf bank_mask:0xf
	v_fmac_f32_dpp v108, v212, v12 quad_perm:[2,2,2,2] row_mask:0xf bank_mask:0xf
	v_fmac_f32_dpp v109, v213, v13 quad_perm:[2,2,2,2] row_mask:0xf bank_mask:0xf
	v_fmac_f32_dpp v116, v214, v16 quad_perm:[2,2,2,2] row_mask:0xf bank_mask:0xf
	v_fmac_f32_dpp v117, v215, v17 quad_perm:[2,2,2,2] row_mask:0xf bank_mask:0xf
	v_fmac_f32_dpp v108, v212, v20 quad_perm:[3,3,3,3] row_mask:0xf bank_mask:0xf
	v_fmac_f32_dpp v109, v213, v21 quad_perm:[3,3,3,3] row_mask:0xf bank_mask:0xf
	v_fmac_f32_dpp v116, v214, v22 quad_perm:[3,3,3,3] row_mask:0xf bank_mask:0xf
	v_fmac_f32_dpp v117, v215, v23 quad_perm:[3,3,3,3] row_mask:0xf bank_mask:0xf
	v_fmac_f32_dpp v108, v216, v24 quad_perm:[0,0,0,0] row_mask:0xf bank_mask:0xf
	v_fmac_f32_dpp v109, v217, v25 quad_perm:[0,0,0,0] row_mask:0xf bank_mask:0xf
	v_mov_b32_e32 v112, v116
	v_fmac_f32_dpp v112, v218, v26 quad_perm:[0,0,0,0] row_mask:0xf bank_mask:0xf
	v_mov_b32_e32 v113, v117
	v_fmac_f32_dpp v113, v219, v27 quad_perm:[0,0,0,0] row_mask:0xf bank_mask:0xf
	v_mov_b32_e32 v114, v108
	v_mov_b32_e32 v115, v112
	v_mov_b32_e32 v112, v109
	v_pk_add_f32 v[108:109], v[114:115], v[112:113]
	s_nop 0
	v_add_f32_e32 v31, v108, v109
	v_fmac_f32_dpp v31, v216, v36 quad_perm:[1,1,1,1] row_mask:0xf bank_mask:0xf
	v_sub_f32_e32 v37, v38, v31
	ds_read_b128 v[212:215], v228 offset:40704
	ds_read_b128 v[216:219], v228 offset:40768
	s_waitcnt lgkmcnt(2)
	v_mul_f32_dpp v38, v196, v0 quad_perm:[0,0,0,0] row_mask:0xf bank_mask:0xf
	v_mul_f32_dpp v39, v197, v1 quad_perm:[0,0,0,0] row_mask:0xf bank_mask:0xf
	v_mul_f32_dpp v108, v198, v6 quad_perm:[0,0,0,0] row_mask:0xf bank_mask:0xf
	v_mul_f32_dpp v109, v199, v7 quad_perm:[0,0,0,0] row_mask:0xf bank_mask:0xf
	v_fmac_f32_dpp v38, v196, v8 quad_perm:[1,1,1,1] row_mask:0xf bank_mask:0xf
	v_fmac_f32_dpp v39, v197, v9 quad_perm:[1,1,1,1] row_mask:0xf bank_mask:0xf
	v_fmac_f32_dpp v108, v198, v10 quad_perm:[1,1,1,1] row_mask:0xf bank_mask:0xf
	v_fmac_f32_dpp v109, v199, v11 quad_perm:[1,1,1,1] row_mask:0xf bank_mask:0xf
	v_fmac_f32_dpp v38, v196, v12 quad_perm:[2,2,2,2] row_mask:0xf bank_mask:0xf
	v_fmac_f32_dpp v39, v197, v13 quad_perm:[2,2,2,2] row_mask:0xf bank_mask:0xf
	v_fmac_f32_dpp v108, v198, v16 quad_perm:[2,2,2,2] row_mask:0xf bank_mask:0xf
	v_fmac_f32_dpp v109, v199, v17 quad_perm:[2,2,2,2] row_mask:0xf bank_mask:0xf
	v_fmac_f32_dpp v38, v196, v20 quad_perm:[3,3,3,3] row_mask:0xf bank_mask:0xf
	v_fmac_f32_dpp v39, v197, v21 quad_perm:[3,3,3,3] row_mask:0xf bank_mask:0xf
	v_fmac_f32_dpp v108, v198, v22 quad_perm:[3,3,3,3] row_mask:0xf bank_mask:0xf
	v_fmac_f32_dpp v109, v199, v23 quad_perm:[3,3,3,3] row_mask:0xf bank_mask:0xf
	v_fmac_f32_dpp v38, v200, v24 quad_perm:[0,0,0,0] row_mask:0xf bank_mask:0xf
	v_fmac_f32_dpp v39, v201, v25 quad_perm:[0,0,0,0] row_mask:0xf bank_mask:0xf
	v_fmac_f32_dpp v108, v202, v26 quad_perm:[0,0,0,0] row_mask:0xf bank_mask:0xf
	v_fmac_f32_dpp v109, v203, v27 quad_perm:[0,0,0,0] row_mask:0xf bank_mask:0xf
	v_fmac_f32_dpp v38, v200, v36 quad_perm:[1,1,1,1] row_mask:0xf bank_mask:0xf
	v_fmac_f32_dpp v39, v201, v37 quad_perm:[1,1,1,1] row_mask:0xf bank_mask:0xf
	v_mov_b32_e32 v112, v108
	v_mov_b32_e32 v113, v38
	v_mov_b32_e32 v38, v109
	v_pk_add_f32 v[38:39], v[112:113], v[38:39]
	s_nop 0
	v_pk_add_f32 v[38:39], v[38:39], v[38:39] op_sel:[0,1] op_sel_hi:[1,0]
	s_nop 0
	v_pk_add_f32 v[38:39], v[106:107], v[38:39] neg_lo:[0,1] neg_hi:[0,1]
	ds_read_b128 v[196:199], v228 offset:40960
	ds_read_b128 v[200:203], v228 offset:41024
	s_waitcnt lgkmcnt(2)
	v_mul_f32_dpp v106, v212, v0 quad_perm:[0,0,0,0] row_mask:0xf bank_mask:0xf
	v_mul_f32_dpp v107, v213, v1 quad_perm:[0,0,0,0] row_mask:0xf bank_mask:0xf
	v_mul_f32_dpp v108, v214, v6 quad_perm:[0,0,0,0] row_mask:0xf bank_mask:0xf
	v_mul_f32_dpp v109, v215, v7 quad_perm:[0,0,0,0] row_mask:0xf bank_mask:0xf
	v_fmac_f32_dpp v106, v212, v8 quad_perm:[1,1,1,1] row_mask:0xf bank_mask:0xf
	v_fmac_f32_dpp v107, v213, v9 quad_perm:[1,1,1,1] row_mask:0xf bank_mask:0xf
	v_mov_b32_e32 v112, v108
	v_fmac_f32_dpp v112, v214, v10 quad_perm:[1,1,1,1] row_mask:0xf bank_mask:0xf
	v_mov_b32_e32 v113, v109
	v_fmac_f32_dpp v113, v215, v11 quad_perm:[1,1,1,1] row_mask:0xf bank_mask:0xf
	v_mov_b32_e32 v116, v106
	v_fmac_f32_dpp v116, v212, v12 quad_perm:[2,2,2,2] row_mask:0xf bank_mask:0xf
	v_mov_b32_e32 v117, v107
	v_fmac_f32_dpp v117, v213, v13 quad_perm:[2,2,2,2] row_mask:0xf bank_mask:0xf
	v_mov_b32_e32 v118, v112
	v_fmac_f32_dpp v118, v214, v16 quad_perm:[2,2,2,2] row_mask:0xf bank_mask:0xf
	v_mov_b32_e32 v119, v113
	v_fmac_f32_dpp v119, v215, v17 quad_perm:[2,2,2,2] row_mask:0xf bank_mask:0xf
	v_fmac_f32_dpp v116, v212, v20 quad_perm:[3,3,3,3] row_mask:0xf bank_mask:0xf
	v_fmac_f32_dpp v117, v213, v21 quad_perm:[3,3,3,3] row_mask:0xf bank_mask:0xf
	v_fmac_f32_dpp v118, v214, v22 quad_perm:[3,3,3,3] row_mask:0xf bank_mask:0xf
	v_fmac_f32_dpp v119, v215, v23 quad_perm:[3,3,3,3] row_mask:0xf bank_mask:0xf
	v_mov_b32_e32 v106, v116
	v_fmac_f32_dpp v106, v216, v24 quad_perm:[0,0,0,0] row_mask:0xf bank_mask:0xf
	v_mov_b32_e32 v107, v117
	v_fmac_f32_dpp v107, v217, v25 quad_perm:[0,0,0,0] row_mask:0xf bank_mask:0xf
	v_mov_b32_e32 v108, v118
	v_fmac_f32_dpp v108, v218, v26 quad_perm:[0,0,0,0] row_mask:0xf bank_mask:0xf
	v_mov_b32_e32 v109, v119
	v_fmac_f32_dpp v109, v219, v27 quad_perm:[0,0,0,0] row_mask:0xf bank_mask:0xf
	v_fmac_f32_dpp v106, v216, v36 quad_perm:[1,1,1,1] row_mask:0xf bank_mask:0xf
	v_fmac_f32_dpp v107, v217, v37 quad_perm:[1,1,1,1] row_mask:0xf bank_mask:0xf
	v_mov_b32_e32 v112, v108
	v_mov_b32_e32 v113, v106
	v_mov_b32_e32 v106, v109
	v_pk_add_f32 v[106:107], v[112:113], v[106:107]
	s_nop 0
	v_add_f32_e32 v19, v106, v107
	v_fmac_f32_dpp v19, v218, v38 quad_perm:[1,1,1,1] row_mask:0xf bank_mask:0xf
	v_sub_f32_e32 v39, v110, v19
	ds_read_b128 v[212:215], v228 offset:41216
	ds_read_b128 v[216:219], v228 offset:41280
	s_waitcnt lgkmcnt(2)
; DI void gdn_pre(const Params& p, int ch, char* smem) {
;     ...
;   for (int i = 1; i < 64; ++i) {
;     f32x2 sa = {0.f, 0.f}, sb = {0.f, 0.f};
;     const f32x2* arow = (const f32x2*)(Amat + i * 64);
; #pragma unroll
;     for (int k = 0; k < (i >> 1); ++k) {
;       const f32x2 a2 = arow[k];
;       if (k & 1) sb = __builtin_elementwise_fma(a2, c2[k], sb);
;       else sa = __builtin_elementwise_fma(a2, c2[k], sa);
;     }
;     float tot = (sa[0] + sa[1]) + (sb[0] + sb[1]);
;     if (i & 1) tot += Amat[i * 64 + i - 1] * c2[(i - 1) >> 1][0];
;     c2[i >> 1][i & 1] -= tot;
;     __builtin_amdgcn_sched_barrier(0);
;   }
	v_mul_f32_dpp v106, v196, v0 quad_perm:[0,0,0,0] row_mask:0xf bank_mask:0xf
	v_mul_f32_dpp v107, v197, v1 quad_perm:[0,0,0,0] row_mask:0xf bank_mask:0xf
	v_mul_f32_dpp v108, v198, v6 quad_perm:[0,0,0,0] row_mask:0xf bank_mask:0xf
	v_mul_f32_dpp v109, v199, v7 quad_perm:[0,0,0,0] row_mask:0xf bank_mask:0xf
	v_fmac_f32_dpp v106, v196, v8 quad_perm:[1,1,1,1] row_mask:0xf bank_mask:0xf
	v_fmac_f32_dpp v107, v197, v9 quad_perm:[1,1,1,1] row_mask:0xf bank_mask:0xf
	v_mov_b32_e32 v110, v108
	v_fmac_f32_dpp v110, v198, v10 quad_perm:[1,1,1,1] row_mask:0xf bank_mask:0xf
	v_mov_b32_e32 v111, v109
	v_fmac_f32_dpp v111, v199, v11 quad_perm:[1,1,1,1] row_mask:0xf bank_mask:0xf
	v_mov_b32_e32 v114, v106
	v_fmac_f32_dpp v114, v196, v12 quad_perm:[2,2,2,2] row_mask:0xf bank_mask:0xf
	v_mov_b32_e32 v115, v107
	v_fmac_f32_dpp v115, v197, v13 quad_perm:[2,2,2,2] row_mask:0xf bank_mask:0xf
	v_mov_b32_e32 v116, v110
	v_fmac_f32_dpp v116, v198, v16 quad_perm:[2,2,2,2] row_mask:0xf bank_mask:0xf
	v_mov_b32_e32 v117, v111
	v_fmac_f32_dpp v117, v199, v17 quad_perm:[2,2,2,2] row_mask:0xf bank_mask:0xf
	v_fmac_f32_dpp v114, v196, v20 quad_perm:[3,3,3,3] row_mask:0xf bank_mask:0xf
	v_fmac_f32_dpp v115, v197, v21 quad_perm:[3,3,3,3] row_mask:0xf bank_mask:0xf
	v_fmac_f32_dpp v116, v198, v22 quad_perm:[3,3,3,3] row_mask:0xf bank_mask:0xf
	v_fmac_f32_dpp v117, v199, v23 quad_perm:[3,3,3,3] row_mask:0xf bank_mask:0xf
	v_mov_b32_e32 v106, v114
	v_fmac_f32_dpp v106, v200, v24 quad_perm:[0,0,0,0] row_mask:0xf bank_mask:0xf
	v_mov_b32_e32 v107, v115
	v_fmac_f32_dpp v107, v201, v25 quad_perm:[0,0,0,0] row_mask:0xf bank_mask:0xf
	v_mov_b32_e32 v108, v116
	v_fmac_f32_dpp v108, v202, v26 quad_perm:[0,0,0,0] row_mask:0xf bank_mask:0xf
	v_mov_b32_e32 v109, v117
	v_fmac_f32_dpp v109, v203, v27 quad_perm:[0,0,0,0] row_mask:0xf bank_mask:0xf
	v_fmac_f32_dpp v106, v200, v36 quad_perm:[1,1,1,1] row_mask:0xf bank_mask:0xf
	v_fmac_f32_dpp v107, v201, v37 quad_perm:[1,1,1,1] row_mask:0xf bank_mask:0xf
	v_fmac_f32_dpp v108, v202, v38 quad_perm:[1,1,1,1] row_mask:0xf bank_mask:0xf
	v_fmac_f32_dpp v109, v203, v39 quad_perm:[1,1,1,1] row_mask:0xf bank_mask:0xf
	v_mov_b32_e32 v110, v106
	v_mov_b32_e32 v111, v108
	v_mov_b32_e32 v108, v107
	v_pk_add_f32 v[106:107], v[110:111], v[108:109]
	s_nop 0
	v_pk_add_f32 v[106:107], v[106:107], v[106:107] op_sel:[0,1] op_sel_hi:[1,0]
	s_nop 0
	v_pk_add_f32 v[42:43], v[42:43], v[106:107] neg_lo:[0,1] neg_hi:[0,1]
	ds_read_b128 v[196:199], v228 offset:41472
	ds_read_b128 v[200:203], v228 offset:41536
	s_waitcnt lgkmcnt(2)
	v_mul_f32_dpp v106, v212, v0 quad_perm:[0,0,0,0] row_mask:0xf bank_mask:0xf
	v_mul_f32_dpp v107, v213, v1 quad_perm:[0,0,0,0] row_mask:0xf bank_mask:0xf
	v_mul_f32_dpp v108, v214, v6 quad_perm:[0,0,0,0] row_mask:0xf bank_mask:0xf
	v_mul_f32_dpp v109, v215, v7 quad_perm:[0,0,0,0] row_mask:0xf bank_mask:0xf
	v_fmac_f32_dpp v106, v212, v8 quad_perm:[1,1,1,1] row_mask:0xf bank_mask:0xf
	v_fmac_f32_dpp v107, v213, v9 quad_perm:[1,1,1,1] row_mask:0xf bank_mask:0xf
	v_mov_b32_e32 v110, v108
	v_fmac_f32_dpp v110, v214, v10 quad_perm:[1,1,1,1] row_mask:0xf bank_mask:0xf
	v_mov_b32_e32 v111, v109
	v_fmac_f32_dpp v111, v215, v11 quad_perm:[1,1,1,1] row_mask:0xf bank_mask:0xf
	v_mov_b32_e32 v114, v106
	v_fmac_f32_dpp v114, v212, v12 quad_perm:[2,2,2,2] row_mask:0xf bank_mask:0xf
	v_mov_b32_e32 v115, v107
	v_fmac_f32_dpp v115, v213, v13 quad_perm:[2,2,2,2] row_mask:0xf bank_mask:0xf
	v_mov_b32_e32 v116, v110
	v_fmac_f32_dpp v116, v214, v16 quad_perm:[2,2,2,2] row_mask:0xf bank_mask:0xf
	v_mov_b32_e32 v117, v111
	v_fmac_f32_dpp v117, v215, v17 quad_perm:[2,2,2,2] row_mask:0xf bank_mask:0xf
	v_fmac_f32_dpp v114, v212, v20 quad_perm:[3,3,3,3] row_mask:0xf bank_mask:0xf
	v_fmac_f32_dpp v115, v213, v21 quad_perm:[3,3,3,3] row_mask:0xf bank_mask:0xf
	v_fmac_f32_dpp v116, v214, v22 quad_perm:[3,3,3,3] row_mask:0xf bank_mask:0xf
	v_fmac_f32_dpp v117, v215, v23 quad_perm:[3,3,3,3] row_mask:0xf bank_mask:0xf
	v_mov_b32_e32 v106, v114
	v_fmac_f32_dpp v106, v216, v24 quad_perm:[0,0,0,0] row_mask:0xf bank_mask:0xf
	v_mov_b32_e32 v107, v115
	v_fmac_f32_dpp v107, v217, v25 quad_perm:[0,0,0,0] row_mask:0xf bank_mask:0xf
	v_mov_b32_e32 v108, v116
	v_fmac_f32_dpp v108, v218, v26 quad_perm:[0,0,0,0] row_mask:0xf bank_mask:0xf
	v_mov_b32_e32 v109, v117
	v_fmac_f32_dpp v109, v219, v27 quad_perm:[0,0,0,0] row_mask:0xf bank_mask:0xf
	v_fmac_f32_dpp v106, v216, v36 quad_perm:[1,1,1,1] row_mask:0xf bank_mask:0xf
	v_fmac_f32_dpp v107, v217, v37 quad_perm:[1,1,1,1] row_mask:0xf bank_mask:0xf
	v_fmac_f32_dpp v108, v218, v38 quad_perm:[1,1,1,1] row_mask:0xf bank_mask:0xf
	v_fmac_f32_dpp v109, v219, v39 quad_perm:[1,1,1,1] row_mask:0xf bank_mask:0xf
	v_mov_b32_e32 v110, v106
	v_mov_b32_e32 v111, v108
	v_mov_b32_e32 v108, v107
	v_pk_add_f32 v[106:107], v[110:111], v[108:109]
	s_nop 0
	v_add_f32_e32 v31, v106, v107
	v_fmac_f32_dpp v31, v216, v42 quad_perm:[2,2,2,2] row_mask:0xf bank_mask:0xf
	v_sub_f32_e32 v43, v80, v31
	ds_read_b128 v[212:215], v228 offset:41728
	ds_read_b128 v[216:219], v228 offset:41792
	s_waitcnt lgkmcnt(2)
; DI void gdn_pre(const Params& p, int ch, char* smem) {
;     ...
;   for (int i = 1; i < 64; ++i) {
;     f32x2 sa = {0.f, 0.f}, sb = {0.f, 0.f};
;     const f32x2* arow = (const f32x2*)(Amat + i * 64);
; #pragma unroll
;     for (int k = 0; k < (i >> 1); ++k) {
;       const f32x2 a2 = arow[k];
;       if (k & 1) sb = __builtin_elementwise_fma(a2, c2[k], sb);
;       else sa = __builtin_elementwise_fma(a2, c2[k], sa);
;     }
;     float tot = (sa[0] + sa[1]) + (sb[0] + sb[1]);
;     if (i & 1) tot += Amat[i * 64 + i - 1] * c2[(i - 1) >> 1][0];
;     c2[i >> 1][i & 1] -= tot;
;     __builtin_amdgcn_sched_barrier(0);
;   }
	v_mul_f32_dpp v80, v196, v0 quad_perm:[0,0,0,0] row_mask:0xf bank_mask:0xf
	v_mul_f32_dpp v81, v197, v1 quad_perm:[0,0,0,0] row_mask:0xf bank_mask:0xf
	v_mul_f32_dpp v106, v198, v6 quad_perm:[0,0,0,0] row_mask:0xf bank_mask:0xf
	v_mul_f32_dpp v107, v199, v7 quad_perm:[0,0,0,0] row_mask:0xf bank_mask:0xf
	v_fmac_f32_dpp v80, v196, v8 quad_perm:[1,1,1,1] row_mask:0xf bank_mask:0xf
	v_fmac_f32_dpp v81, v197, v9 quad_perm:[1,1,1,1] row_mask:0xf bank_mask:0xf
	v_fmac_f32_dpp v106, v198, v10 quad_perm:[1,1,1,1] row_mask:0xf bank_mask:0xf
	v_fmac_f32_dpp v107, v199, v11 quad_perm:[1,1,1,1] row_mask:0xf bank_mask:0xf
	v_fmac_f32_dpp v80, v196, v12 quad_perm:[2,2,2,2] row_mask:0xf bank_mask:0xf
	v_fmac_f32_dpp v81, v197, v13 quad_perm:[2,2,2,2] row_mask:0xf bank_mask:0xf
	v_mov_b32_e32 v114, v106
	v_fmac_f32_dpp v114, v198, v16 quad_perm:[2,2,2,2] row_mask:0xf bank_mask:0xf
	v_mov_b32_e32 v115, v107
	v_fmac_f32_dpp v115, v199, v17 quad_perm:[2,2,2,2] row_mask:0xf bank_mask:0xf
	v_fmac_f32_dpp v80, v196, v20 quad_perm:[3,3,3,3] row_mask:0xf bank_mask:0xf
	v_fmac_f32_dpp v81, v197, v21 quad_perm:[3,3,3,3] row_mask:0xf bank_mask:0xf
	v_fmac_f32_dpp v114, v198, v22 quad_perm:[3,3,3,3] row_mask:0xf bank_mask:0xf
	v_fmac_f32_dpp v115, v199, v23 quad_perm:[3,3,3,3] row_mask:0xf bank_mask:0xf
	v_fmac_f32_dpp v80, v200, v24 quad_perm:[0,0,0,0] row_mask:0xf bank_mask:0xf
	v_fmac_f32_dpp v81, v201, v25 quad_perm:[0,0,0,0] row_mask:0xf bank_mask:0xf
	v_mov_b32_e32 v106, v114
	v_fmac_f32_dpp v106, v202, v26 quad_perm:[0,0,0,0] row_mask:0xf bank_mask:0xf
	v_mov_b32_e32 v107, v115
	v_fmac_f32_dpp v107, v203, v27 quad_perm:[0,0,0,0] row_mask:0xf bank_mask:0xf
	v_fmac_f32_dpp v80, v200, v36 quad_perm:[1,1,1,1] row_mask:0xf bank_mask:0xf
	v_fmac_f32_dpp v81, v201, v37 quad_perm:[1,1,1,1] row_mask:0xf bank_mask:0xf
	v_fmac_f32_dpp v106, v202, v38 quad_perm:[1,1,1,1] row_mask:0xf bank_mask:0xf
	v_fmac_f32_dpp v107, v203, v39 quad_perm:[1,1,1,1] row_mask:0xf bank_mask:0xf
	v_fmac_f32_dpp v80, v200, v42 quad_perm:[2,2,2,2] row_mask:0xf bank_mask:0xf
	v_fmac_f32_dpp v81, v201, v43 quad_perm:[2,2,2,2] row_mask:0xf bank_mask:0xf
	v_mov_b32_e32 v108, v106
	v_mov_b32_e32 v109, v80
	v_mov_b32_e32 v80, v107
	v_pk_add_f32 v[80:81], v[108:109], v[80:81]
	s_nop 0
	v_pk_add_f32 v[80:81], v[80:81], v[80:81] op_sel:[0,1] op_sel_hi:[1,0]
	s_nop 0
	v_pk_add_f32 v[46:47], v[46:47], v[80:81] neg_lo:[0,1] neg_hi:[0,1]
	ds_read_b128 v[196:199], v228 offset:41984
	ds_read_b128 v[200:203], v228 offset:42048
	s_waitcnt lgkmcnt(2)
	v_mul_f32_dpp v80, v212, v0 quad_perm:[0,0,0,0] row_mask:0xf bank_mask:0xf
	v_mul_f32_dpp v81, v213, v1 quad_perm:[0,0,0,0] row_mask:0xf bank_mask:0xf
	v_mul_f32_dpp v106, v214, v6 quad_perm:[0,0,0,0] row_mask:0xf bank_mask:0xf
	v_mul_f32_dpp v107, v215, v7 quad_perm:[0,0,0,0] row_mask:0xf bank_mask:0xf
	v_fmac_f32_dpp v80, v212, v8 quad_perm:[1,1,1,1] row_mask:0xf bank_mask:0xf
	v_fmac_f32_dpp v81, v213, v9 quad_perm:[1,1,1,1] row_mask:0xf bank_mask:0xf
	v_fmac_f32_dpp v106, v214, v10 quad_perm:[1,1,1,1] row_mask:0xf bank_mask:0xf
	v_fmac_f32_dpp v107, v215, v11 quad_perm:[1,1,1,1] row_mask:0xf bank_mask:0xf
	v_fmac_f32_dpp v80, v212, v12 quad_perm:[2,2,2,2] row_mask:0xf bank_mask:0xf
	v_fmac_f32_dpp v81, v213, v13 quad_perm:[2,2,2,2] row_mask:0xf bank_mask:0xf
	v_mov_b32_e32 v114, v106
	v_fmac_f32_dpp v114, v214, v16 quad_perm:[2,2,2,2] row_mask:0xf bank_mask:0xf
	v_mov_b32_e32 v115, v107
	v_fmac_f32_dpp v115, v215, v17 quad_perm:[2,2,2,2] row_mask:0xf bank_mask:0xf
	v_fmac_f32_dpp v80, v212, v20 quad_perm:[3,3,3,3] row_mask:0xf bank_mask:0xf
	v_fmac_f32_dpp v81, v213, v21 quad_perm:[3,3,3,3] row_mask:0xf bank_mask:0xf
	v_mov_b32_e32 v118, v114
	v_fmac_f32_dpp v118, v214, v22 quad_perm:[3,3,3,3] row_mask:0xf bank_mask:0xf
	v_mov_b32_e32 v119, v115
	v_fmac_f32_dpp v119, v215, v23 quad_perm:[3,3,3,3] row_mask:0xf bank_mask:0xf
	v_fmac_f32_dpp v80, v216, v24 quad_perm:[0,0,0,0] row_mask:0xf bank_mask:0xf
	v_fmac_f32_dpp v81, v217, v25 quad_perm:[0,0,0,0] row_mask:0xf bank_mask:0xf
	v_mov_b32_e32 v106, v118
	v_fmac_f32_dpp v106, v218, v26 quad_perm:[0,0,0,0] row_mask:0xf bank_mask:0xf
	v_mov_b32_e32 v107, v119
	v_fmac_f32_dpp v107, v219, v27 quad_perm:[0,0,0,0] row_mask:0xf bank_mask:0xf
	v_fmac_f32_dpp v80, v216, v36 quad_perm:[1,1,1,1] row_mask:0xf bank_mask:0xf
	v_fmac_f32_dpp v81, v217, v37 quad_perm:[1,1,1,1] row_mask:0xf bank_mask:0xf
	v_fmac_f32_dpp v106, v218, v38 quad_perm:[1,1,1,1] row_mask:0xf bank_mask:0xf
	v_fmac_f32_dpp v107, v219, v39 quad_perm:[1,1,1,1] row_mask:0xf bank_mask:0xf
	v_fmac_f32_dpp v80, v216, v42 quad_perm:[2,2,2,2] row_mask:0xf bank_mask:0xf
	v_fmac_f32_dpp v81, v217, v43 quad_perm:[2,2,2,2] row_mask:0xf bank_mask:0xf
	v_mov_b32_e32 v108, v106
	v_mov_b32_e32 v109, v80
	v_mov_b32_e32 v80, v107
	v_pk_add_f32 v[80:81], v[108:109], v[80:81]
	s_nop 0
	v_add_f32_e32 v19, v80, v81
	v_fmac_f32_dpp v19, v218, v46 quad_perm:[2,2,2,2] row_mask:0xf bank_mask:0xf
	v_sub_f32_e32 v47, v50, v19
	ds_read_b128 v[212:215], v228 offset:42240
	ds_read_b128 v[216:219], v228 offset:42304
	s_waitcnt lgkmcnt(2)
; DI void gdn_pre(const Params& p, int ch, char* smem) {
;     ...
;   for (int i = 1; i < 64; ++i) {
;     f32x2 sa = {0.f, 0.f}, sb = {0.f, 0.f};
;     const f32x2* arow = (const f32x2*)(Amat + i * 64);
; #pragma unroll
;     for (int k = 0; k < (i >> 1); ++k) {
;       const f32x2 a2 = arow[k];
;       if (k & 1) sb = __builtin_elementwise_fma(a2, c2[k], sb);
;       else sa = __builtin_elementwise_fma(a2, c2[k], sa);
;     }
;     float tot = (sa[0] + sa[1]) + (sb[0] + sb[1]);
;     if (i & 1) tot += Amat[i * 64 + i - 1] * c2[(i - 1) >> 1][0];
;     c2[i >> 1][i & 1] -= tot;
;     __builtin_amdgcn_sched_barrier(0);
;   }
	v_mul_f32_dpp v50, v196, v0 quad_perm:[0,0,0,0] row_mask:0xf bank_mask:0xf
	v_mul_f32_dpp v51, v197, v1 quad_perm:[0,0,0,0] row_mask:0xf bank_mask:0xf
	v_mul_f32_dpp v80, v198, v6 quad_perm:[0,0,0,0] row_mask:0xf bank_mask:0xf
	v_mul_f32_dpp v81, v199, v7 quad_perm:[0,0,0,0] row_mask:0xf bank_mask:0xf
	v_fmac_f32_dpp v50, v196, v8 quad_perm:[1,1,1,1] row_mask:0xf bank_mask:0xf
	v_fmac_f32_dpp v51, v197, v9 quad_perm:[1,1,1,1] row_mask:0xf bank_mask:0xf
	v_fmac_f32_dpp v80, v198, v10 quad_perm:[1,1,1,1] row_mask:0xf bank_mask:0xf
	v_fmac_f32_dpp v81, v199, v11 quad_perm:[1,1,1,1] row_mask:0xf bank_mask:0xf
	v_fmac_f32_dpp v50, v196, v12 quad_perm:[2,2,2,2] row_mask:0xf bank_mask:0xf
	v_fmac_f32_dpp v51, v197, v13 quad_perm:[2,2,2,2] row_mask:0xf bank_mask:0xf
	v_fmac_f32_dpp v80, v198, v16 quad_perm:[2,2,2,2] row_mask:0xf bank_mask:0xf
	v_fmac_f32_dpp v81, v199, v17 quad_perm:[2,2,2,2] row_mask:0xf bank_mask:0xf
	v_fmac_f32_dpp v50, v196, v20 quad_perm:[3,3,3,3] row_mask:0xf bank_mask:0xf
	v_fmac_f32_dpp v51, v197, v21 quad_perm:[3,3,3,3] row_mask:0xf bank_mask:0xf
	v_fmac_f32_dpp v80, v198, v22 quad_perm:[3,3,3,3] row_mask:0xf bank_mask:0xf
	v_fmac_f32_dpp v81, v199, v23 quad_perm:[3,3,3,3] row_mask:0xf bank_mask:0xf
	v_fmac_f32_dpp v50, v200, v24 quad_perm:[0,0,0,0] row_mask:0xf bank_mask:0xf
	v_fmac_f32_dpp v51, v201, v25 quad_perm:[0,0,0,0] row_mask:0xf bank_mask:0xf
	v_fmac_f32_dpp v80, v202, v26 quad_perm:[0,0,0,0] row_mask:0xf bank_mask:0xf
	v_fmac_f32_dpp v81, v203, v27 quad_perm:[0,0,0,0] row_mask:0xf bank_mask:0xf
	v_fmac_f32_dpp v50, v200, v36 quad_perm:[1,1,1,1] row_mask:0xf bank_mask:0xf
	v_fmac_f32_dpp v51, v201, v37 quad_perm:[1,1,1,1] row_mask:0xf bank_mask:0xf
	v_fmac_f32_dpp v80, v202, v38 quad_perm:[1,1,1,1] row_mask:0xf bank_mask:0xf
	v_fmac_f32_dpp v81, v203, v39 quad_perm:[1,1,1,1] row_mask:0xf bank_mask:0xf
	v_fmac_f32_dpp v50, v200, v42 quad_perm:[2,2,2,2] row_mask:0xf bank_mask:0xf
	v_fmac_f32_dpp v51, v201, v43 quad_perm:[2,2,2,2] row_mask:0xf bank_mask:0xf
	v_fmac_f32_dpp v80, v202, v46 quad_perm:[2,2,2,2] row_mask:0xf bank_mask:0xf
	v_fmac_f32_dpp v81, v203, v47 quad_perm:[2,2,2,2] row_mask:0xf bank_mask:0xf
	v_mov_b32_e32 v106, v50
	v_mov_b32_e32 v107, v80
	v_mov_b32_e32 v80, v51
	v_pk_add_f32 v[50:51], v[106:107], v[80:81]
	s_nop 0
	v_pk_add_f32 v[50:51], v[50:51], v[50:51] op_sel:[0,1] op_sel_hi:[1,0]
	s_nop 0
	v_pk_add_f32 v[50:51], v[104:105], v[50:51] neg_lo:[0,1] neg_hi:[0,1]
	ds_read_b128 v[196:199], v228 offset:42496
	ds_read_b128 v[200:203], v228 offset:42560
	s_waitcnt lgkmcnt(2)
	v_mul_f32_dpp v80, v212, v0 quad_perm:[0,0,0,0] row_mask:0xf bank_mask:0xf
	v_mul_f32_dpp v81, v213, v1 quad_perm:[0,0,0,0] row_mask:0xf bank_mask:0xf
	v_mul_f32_dpp v104, v214, v6 quad_perm:[0,0,0,0] row_mask:0xf bank_mask:0xf
	v_mul_f32_dpp v105, v215, v7 quad_perm:[0,0,0,0] row_mask:0xf bank_mask:0xf
	v_fmac_f32_dpp v80, v212, v8 quad_perm:[1,1,1,1] row_mask:0xf bank_mask:0xf
	v_fmac_f32_dpp v81, v213, v9 quad_perm:[1,1,1,1] row_mask:0xf bank_mask:0xf
	v_mov_b32_e32 v108, v104
	v_fmac_f32_dpp v108, v214, v10 quad_perm:[1,1,1,1] row_mask:0xf bank_mask:0xf
	v_mov_b32_e32 v109, v105
	v_fmac_f32_dpp v109, v215, v11 quad_perm:[1,1,1,1] row_mask:0xf bank_mask:0xf
	v_fmac_f32_dpp v80, v212, v12 quad_perm:[2,2,2,2] row_mask:0xf bank_mask:0xf
	v_fmac_f32_dpp v81, v213, v13 quad_perm:[2,2,2,2] row_mask:0xf bank_mask:0xf
	v_mov_b32_e32 v112, v108
	v_fmac_f32_dpp v112, v214, v16 quad_perm:[2,2,2,2] row_mask:0xf bank_mask:0xf
	v_mov_b32_e32 v113, v109
	v_fmac_f32_dpp v113, v215, v17 quad_perm:[2,2,2,2] row_mask:0xf bank_mask:0xf
	v_fmac_f32_dpp v80, v212, v20 quad_perm:[3,3,3,3] row_mask:0xf bank_mask:0xf
	v_fmac_f32_dpp v81, v213, v21 quad_perm:[3,3,3,3] row_mask:0xf bank_mask:0xf
	v_mov_b32_e32 v116, v112
	v_fmac_f32_dpp v116, v214, v22 quad_perm:[3,3,3,3] row_mask:0xf bank_mask:0xf
	v_mov_b32_e32 v117, v113
	v_fmac_f32_dpp v117, v215, v23 quad_perm:[3,3,3,3] row_mask:0xf bank_mask:0xf
	v_fmac_f32_dpp v80, v216, v24 quad_perm:[0,0,0,0] row_mask:0xf bank_mask:0xf
	v_fmac_f32_dpp v81, v217, v25 quad_perm:[0,0,0,0] row_mask:0xf bank_mask:0xf
	v_mov_b32_e32 v104, v116
	v_fmac_f32_dpp v104, v218, v26 quad_perm:[0,0,0,0] row_mask:0xf bank_mask:0xf
	v_mov_b32_e32 v105, v117
	v_fmac_f32_dpp v105, v219, v27 quad_perm:[0,0,0,0] row_mask:0xf bank_mask:0xf
	v_fmac_f32_dpp v80, v216, v36 quad_perm:[1,1,1,1] row_mask:0xf bank_mask:0xf
	v_fmac_f32_dpp v81, v217, v37 quad_perm:[1,1,1,1] row_mask:0xf bank_mask:0xf
	v_fmac_f32_dpp v104, v218, v38 quad_perm:[1,1,1,1] row_mask:0xf bank_mask:0xf
	v_fmac_f32_dpp v105, v219, v39 quad_perm:[1,1,1,1] row_mask:0xf bank_mask:0xf
	v_fmac_f32_dpp v80, v216, v42 quad_perm:[2,2,2,2] row_mask:0xf bank_mask:0xf
	v_fmac_f32_dpp v81, v217, v43 quad_perm:[2,2,2,2] row_mask:0xf bank_mask:0xf
	v_fmac_f32_dpp v104, v218, v46 quad_perm:[2,2,2,2] row_mask:0xf bank_mask:0xf
	v_fmac_f32_dpp v105, v219, v47 quad_perm:[2,2,2,2] row_mask:0xf bank_mask:0xf
	v_mov_b32_e32 v106, v80
	v_mov_b32_e32 v107, v104
	v_mov_b32_e32 v104, v81
	v_pk_add_f32 v[80:81], v[106:107], v[104:105]
	s_nop 0
	v_add_f32_e32 v31, v80, v81
	v_fmac_f32_dpp v31, v216, v50 quad_perm:[3,3,3,3] row_mask:0xf bank_mask:0xf
	v_sub_f32_e32 v51, v54, v31
	ds_read_b128 v[212:215], v228 offset:42752
	ds_read_b128 v[216:219], v228 offset:42816
	s_waitcnt lgkmcnt(2)
; DI void gdn_pre(const Params& p, int ch, char* smem) {
;     ...
;   for (int i = 1; i < 64; ++i) {
;     f32x2 sa = {0.f, 0.f}, sb = {0.f, 0.f};
;     const f32x2* arow = (const f32x2*)(Amat + i * 64);
; #pragma unroll
;     for (int k = 0; k < (i >> 1); ++k) {
;       const f32x2 a2 = arow[k];
;       if (k & 1) sb = __builtin_elementwise_fma(a2, c2[k], sb);
;       else sa = __builtin_elementwise_fma(a2, c2[k], sa);
;     }
;     float tot = (sa[0] + sa[1]) + (sb[0] + sb[1]);
;     if (i & 1) tot += Amat[i * 64 + i - 1] * c2[(i - 1) >> 1][0];
;     c2[i >> 1][i & 1] -= tot;
;     __builtin_amdgcn_sched_barrier(0);
;   }
	v_mul_f32_dpp v54, v196, v0 quad_perm:[0,0,0,0] row_mask:0xf bank_mask:0xf
	v_mul_f32_dpp v55, v197, v1 quad_perm:[0,0,0,0] row_mask:0xf bank_mask:0xf
	v_mul_f32_dpp v80, v198, v6 quad_perm:[0,0,0,0] row_mask:0xf bank_mask:0xf
	v_mul_f32_dpp v81, v199, v7 quad_perm:[0,0,0,0] row_mask:0xf bank_mask:0xf
	v_fmac_f32_dpp v54, v196, v8 quad_perm:[1,1,1,1] row_mask:0xf bank_mask:0xf
	v_fmac_f32_dpp v55, v197, v9 quad_perm:[1,1,1,1] row_mask:0xf bank_mask:0xf
	v_fmac_f32_dpp v80, v198, v10 quad_perm:[1,1,1,1] row_mask:0xf bank_mask:0xf
	v_fmac_f32_dpp v81, v199, v11 quad_perm:[1,1,1,1] row_mask:0xf bank_mask:0xf
	v_fmac_f32_dpp v54, v196, v12 quad_perm:[2,2,2,2] row_mask:0xf bank_mask:0xf
	v_fmac_f32_dpp v55, v197, v13 quad_perm:[2,2,2,2] row_mask:0xf bank_mask:0xf
	v_fmac_f32_dpp v80, v198, v16 quad_perm:[2,2,2,2] row_mask:0xf bank_mask:0xf
	v_fmac_f32_dpp v81, v199, v17 quad_perm:[2,2,2,2] row_mask:0xf bank_mask:0xf
	v_fmac_f32_dpp v54, v196, v20 quad_perm:[3,3,3,3] row_mask:0xf bank_mask:0xf
	v_fmac_f32_dpp v55, v197, v21 quad_perm:[3,3,3,3] row_mask:0xf bank_mask:0xf
	v_fmac_f32_dpp v54, v200, v24 quad_perm:[0,0,0,0] row_mask:0xf bank_mask:0xf
	v_fmac_f32_dpp v55, v201, v25 quad_perm:[0,0,0,0] row_mask:0xf bank_mask:0xf
	v_fmac_f32_dpp v80, v198, v22 quad_perm:[3,3,3,3] row_mask:0xf bank_mask:0xf
	v_fmac_f32_dpp v81, v199, v23 quad_perm:[3,3,3,3] row_mask:0xf bank_mask:0xf
	v_fmac_f32_dpp v54, v200, v36 quad_perm:[1,1,1,1] row_mask:0xf bank_mask:0xf
	v_fmac_f32_dpp v55, v201, v37 quad_perm:[1,1,1,1] row_mask:0xf bank_mask:0xf
	v_fmac_f32_dpp v80, v202, v26 quad_perm:[0,0,0,0] row_mask:0xf bank_mask:0xf
	v_fmac_f32_dpp v81, v203, v27 quad_perm:[0,0,0,0] row_mask:0xf bank_mask:0xf
	v_fmac_f32_dpp v54, v200, v42 quad_perm:[2,2,2,2] row_mask:0xf bank_mask:0xf
	v_fmac_f32_dpp v55, v201, v43 quad_perm:[2,2,2,2] row_mask:0xf bank_mask:0xf
	v_fmac_f32_dpp v80, v202, v38 quad_perm:[1,1,1,1] row_mask:0xf bank_mask:0xf
	v_fmac_f32_dpp v81, v203, v39 quad_perm:[1,1,1,1] row_mask:0xf bank_mask:0xf
	v_fmac_f32_dpp v54, v200, v50 quad_perm:[3,3,3,3] row_mask:0xf bank_mask:0xf
	v_fmac_f32_dpp v55, v201, v51 quad_perm:[3,3,3,3] row_mask:0xf bank_mask:0xf
	v_fmac_f32_dpp v80, v202, v46 quad_perm:[2,2,2,2] row_mask:0xf bank_mask:0xf
	v_fmac_f32_dpp v81, v203, v47 quad_perm:[2,2,2,2] row_mask:0xf bank_mask:0xf
	v_mov_b32_e32 v105, v54
	v_mov_b32_e32 v104, v80
	v_mov_b32_e32 v54, v81
	v_pk_add_f32 v[54:55], v[104:105], v[54:55]
	s_nop 0
	v_pk_add_f32 v[54:55], v[54:55], v[54:55] op_sel:[0,1] op_sel_hi:[1,0]
	s_nop 0
	v_pk_add_f32 v[54:55], v[102:103], v[54:55] neg_lo:[0,1] neg_hi:[0,1]
	ds_read_b128 v[196:199], v228 offset:43008
	ds_read_b128 v[200:203], v228 offset:43072
	s_waitcnt lgkmcnt(2)
	v_mul_f32_dpp v80, v212, v0 quad_perm:[0,0,0,0] row_mask:0xf bank_mask:0xf
	v_mul_f32_dpp v81, v213, v1 quad_perm:[0,0,0,0] row_mask:0xf bank_mask:0xf
	v_mul_f32_dpp v102, v214, v6 quad_perm:[0,0,0,0] row_mask:0xf bank_mask:0xf
	v_mul_f32_dpp v103, v215, v7 quad_perm:[0,0,0,0] row_mask:0xf bank_mask:0xf
	v_fmac_f32_dpp v80, v212, v8 quad_perm:[1,1,1,1] row_mask:0xf bank_mask:0xf
	v_fmac_f32_dpp v81, v213, v9 quad_perm:[1,1,1,1] row_mask:0xf bank_mask:0xf
	v_mov_b32_e32 v106, v102
	v_fmac_f32_dpp v106, v214, v10 quad_perm:[1,1,1,1] row_mask:0xf bank_mask:0xf
	v_mov_b32_e32 v107, v103
	v_fmac_f32_dpp v107, v215, v11 quad_perm:[1,1,1,1] row_mask:0xf bank_mask:0xf
	v_fmac_f32_dpp v80, v212, v12 quad_perm:[2,2,2,2] row_mask:0xf bank_mask:0xf
	v_fmac_f32_dpp v81, v213, v13 quad_perm:[2,2,2,2] row_mask:0xf bank_mask:0xf
	v_fmac_f32_dpp v106, v214, v16 quad_perm:[2,2,2,2] row_mask:0xf bank_mask:0xf
	v_fmac_f32_dpp v107, v215, v17 quad_perm:[2,2,2,2] row_mask:0xf bank_mask:0xf
	v_fmac_f32_dpp v80, v212, v20 quad_perm:[3,3,3,3] row_mask:0xf bank_mask:0xf
	v_fmac_f32_dpp v81, v213, v21 quad_perm:[3,3,3,3] row_mask:0xf bank_mask:0xf
	v_mov_b32_e32 v114, v106
	v_fmac_f32_dpp v114, v214, v22 quad_perm:[3,3,3,3] row_mask:0xf bank_mask:0xf
	v_mov_b32_e32 v115, v107
	v_fmac_f32_dpp v115, v215, v23 quad_perm:[3,3,3,3] row_mask:0xf bank_mask:0xf
	v_fmac_f32_dpp v80, v216, v24 quad_perm:[0,0,0,0] row_mask:0xf bank_mask:0xf
	v_fmac_f32_dpp v81, v217, v25 quad_perm:[0,0,0,0] row_mask:0xf bank_mask:0xf
	v_fmac_f32_dpp v114, v218, v26 quad_perm:[0,0,0,0] row_mask:0xf bank_mask:0xf
	v_fmac_f32_dpp v115, v219, v27 quad_perm:[0,0,0,0] row_mask:0xf bank_mask:0xf
	v_fmac_f32_dpp v80, v216, v36 quad_perm:[1,1,1,1] row_mask:0xf bank_mask:0xf
	v_fmac_f32_dpp v81, v217, v37 quad_perm:[1,1,1,1] row_mask:0xf bank_mask:0xf
	v_mov_b32_e32 v106, v114
	v_fmac_f32_dpp v106, v218, v38 quad_perm:[1,1,1,1] row_mask:0xf bank_mask:0xf
	v_mov_b32_e32 v107, v115
	v_fmac_f32_dpp v107, v219, v39 quad_perm:[1,1,1,1] row_mask:0xf bank_mask:0xf
	v_fmac_f32_dpp v80, v216, v42 quad_perm:[2,2,2,2] row_mask:0xf bank_mask:0xf
	v_fmac_f32_dpp v81, v217, v43 quad_perm:[2,2,2,2] row_mask:0xf bank_mask:0xf
	v_fmac_f32_dpp v106, v218, v46 quad_perm:[2,2,2,2] row_mask:0xf bank_mask:0xf
	v_fmac_f32_dpp v107, v219, v47 quad_perm:[2,2,2,2] row_mask:0xf bank_mask:0xf
	v_fmac_f32_dpp v80, v216, v50 quad_perm:[3,3,3,3] row_mask:0xf bank_mask:0xf
	v_fmac_f32_dpp v81, v217, v51 quad_perm:[3,3,3,3] row_mask:0xf bank_mask:0xf
	v_mov_b32_e32 v102, v106
	v_mov_b32_e32 v103, v80
	v_mov_b32_e32 v80, v107
	v_pk_add_f32 v[80:81], v[102:103], v[80:81]
	s_nop 0
	v_add_f32_e32 v19, v80, v81
	v_fmac_f32_dpp v19, v218, v54 quad_perm:[3,3,3,3] row_mask:0xf bank_mask:0xf
	v_sub_f32_e32 v55, v56, v19
	ds_read_b128 v[212:215], v228 offset:43264
	ds_read_b128 v[216:219], v228 offset:43328
	ds_read_b128 v[220:223], v228 offset:43392
	s_waitcnt lgkmcnt(3)
; DI void gdn_pre(const Params& p, int ch, char* smem) {
;     ...
;   for (int i = 1; i < 64; ++i) {
;     f32x2 sa = {0.f, 0.f}, sb = {0.f, 0.f};
;     const f32x2* arow = (const f32x2*)(Amat + i * 64);
; #pragma unroll
;     for (int k = 0; k < (i >> 1); ++k) {
;       const f32x2 a2 = arow[k];
;       if (k & 1) sb = __builtin_elementwise_fma(a2, c2[k], sb);
;       else sa = __builtin_elementwise_fma(a2, c2[k], sa);
;     }
;     float tot = (sa[0] + sa[1]) + (sb[0] + sb[1]);
;     if (i & 1) tot += Amat[i * 64 + i - 1] * c2[(i - 1) >> 1][0];
;     c2[i >> 1][i & 1] -= tot;
;     __builtin_amdgcn_sched_barrier(0);
;   }
	v_mul_f32_dpp v56, v196, v0 quad_perm:[0,0,0,0] row_mask:0xf bank_mask:0xf
	v_mul_f32_dpp v57, v197, v1 quad_perm:[0,0,0,0] row_mask:0xf bank_mask:0xf
	v_mul_f32_dpp v80, v198, v6 quad_perm:[0,0,0,0] row_mask:0xf bank_mask:0xf
	v_mul_f32_dpp v81, v199, v7 quad_perm:[0,0,0,0] row_mask:0xf bank_mask:0xf
	v_fmac_f32_dpp v56, v196, v8 quad_perm:[1,1,1,1] row_mask:0xf bank_mask:0xf
	v_fmac_f32_dpp v57, v197, v9 quad_perm:[1,1,1,1] row_mask:0xf bank_mask:0xf
	v_fmac_f32_dpp v80, v198, v10 quad_perm:[1,1,1,1] row_mask:0xf bank_mask:0xf
	v_fmac_f32_dpp v81, v199, v11 quad_perm:[1,1,1,1] row_mask:0xf bank_mask:0xf
	v_fmac_f32_dpp v56, v196, v12 quad_perm:[2,2,2,2] row_mask:0xf bank_mask:0xf
	v_fmac_f32_dpp v57, v197, v13 quad_perm:[2,2,2,2] row_mask:0xf bank_mask:0xf
	v_fmac_f32_dpp v80, v198, v16 quad_perm:[2,2,2,2] row_mask:0xf bank_mask:0xf
	v_fmac_f32_dpp v81, v199, v17 quad_perm:[2,2,2,2] row_mask:0xf bank_mask:0xf
	v_fmac_f32_dpp v56, v196, v20 quad_perm:[3,3,3,3] row_mask:0xf bank_mask:0xf
	v_fmac_f32_dpp v57, v197, v21 quad_perm:[3,3,3,3] row_mask:0xf bank_mask:0xf
	v_fmac_f32_dpp v80, v198, v22 quad_perm:[3,3,3,3] row_mask:0xf bank_mask:0xf
	v_fmac_f32_dpp v81, v199, v23 quad_perm:[3,3,3,3] row_mask:0xf bank_mask:0xf
	v_fmac_f32_dpp v56, v200, v24 quad_perm:[0,0,0,0] row_mask:0xf bank_mask:0xf
	v_fmac_f32_dpp v57, v201, v25 quad_perm:[0,0,0,0] row_mask:0xf bank_mask:0xf
	v_fmac_f32_dpp v80, v202, v26 quad_perm:[0,0,0,0] row_mask:0xf bank_mask:0xf
	v_fmac_f32_dpp v81, v203, v27 quad_perm:[0,0,0,0] row_mask:0xf bank_mask:0xf
	v_fmac_f32_dpp v56, v200, v36 quad_perm:[1,1,1,1] row_mask:0xf bank_mask:0xf
	v_fmac_f32_dpp v57, v201, v37 quad_perm:[1,1,1,1] row_mask:0xf bank_mask:0xf
	v_fmac_f32_dpp v80, v202, v38 quad_perm:[1,1,1,1] row_mask:0xf bank_mask:0xf
	v_fmac_f32_dpp v81, v203, v39 quad_perm:[1,1,1,1] row_mask:0xf bank_mask:0xf
	v_fmac_f32_dpp v56, v200, v42 quad_perm:[2,2,2,2] row_mask:0xf bank_mask:0xf
	v_fmac_f32_dpp v57, v201, v43 quad_perm:[2,2,2,2] row_mask:0xf bank_mask:0xf
	v_fmac_f32_dpp v80, v202, v46 quad_perm:[2,2,2,2] row_mask:0xf bank_mask:0xf
	v_fmac_f32_dpp v81, v203, v47 quad_perm:[2,2,2,2] row_mask:0xf bank_mask:0xf
	v_fmac_f32_dpp v56, v200, v50 quad_perm:[3,3,3,3] row_mask:0xf bank_mask:0xf
	v_fmac_f32_dpp v57, v201, v51 quad_perm:[3,3,3,3] row_mask:0xf bank_mask:0xf
	v_fmac_f32_dpp v80, v202, v54 quad_perm:[3,3,3,3] row_mask:0xf bank_mask:0xf
	v_fmac_f32_dpp v81, v203, v55 quad_perm:[3,3,3,3] row_mask:0xf bank_mask:0xf
	v_mov_b32_e32 v102, v56
	v_mov_b32_e32 v103, v80
	v_mov_b32_e32 v80, v57
	v_pk_add_f32 v[56:57], v[102:103], v[80:81]
	s_nop 0
	v_pk_add_f32 v[56:57], v[56:57], v[56:57] op_sel:[0,1] op_sel_hi:[1,0]
	s_nop 0
	v_pk_add_f32 v[56:57], v[100:101], v[56:57] neg_lo:[0,1] neg_hi:[0,1]
	ds_read_b128 v[196:199], v228 offset:43520
	ds_read_b128 v[200:203], v228 offset:43584
	ds_read_b128 v[204:207], v228 offset:43648
	s_waitcnt lgkmcnt(3)
	v_mul_f32_dpp v80, v212, v0 quad_perm:[0,0,0,0] row_mask:0xf bank_mask:0xf
	v_mul_f32_dpp v81, v213, v1 quad_perm:[0,0,0,0] row_mask:0xf bank_mask:0xf
	v_mul_f32_dpp v100, v214, v6 quad_perm:[0,0,0,0] row_mask:0xf bank_mask:0xf
	v_mul_f32_dpp v101, v215, v7 quad_perm:[0,0,0,0] row_mask:0xf bank_mask:0xf
	v_fmac_f32_dpp v80, v212, v8 quad_perm:[1,1,1,1] row_mask:0xf bank_mask:0xf
	v_fmac_f32_dpp v81, v213, v9 quad_perm:[1,1,1,1] row_mask:0xf bank_mask:0xf
	v_mov_b32_e32 v104, v100
	v_fmac_f32_dpp v104, v214, v10 quad_perm:[1,1,1,1] row_mask:0xf bank_mask:0xf
	v_mov_b32_e32 v105, v101
	v_fmac_f32_dpp v105, v215, v11 quad_perm:[1,1,1,1] row_mask:0xf bank_mask:0xf
	v_fmac_f32_dpp v80, v212, v12 quad_perm:[2,2,2,2] row_mask:0xf bank_mask:0xf
	v_fmac_f32_dpp v81, v213, v13 quad_perm:[2,2,2,2] row_mask:0xf bank_mask:0xf
	v_fmac_f32_dpp v104, v214, v16 quad_perm:[2,2,2,2] row_mask:0xf bank_mask:0xf
	v_fmac_f32_dpp v105, v215, v17 quad_perm:[2,2,2,2] row_mask:0xf bank_mask:0xf
	v_fmac_f32_dpp v80, v212, v20 quad_perm:[3,3,3,3] row_mask:0xf bank_mask:0xf
	v_fmac_f32_dpp v81, v213, v21 quad_perm:[3,3,3,3] row_mask:0xf bank_mask:0xf
	v_mov_b32_e32 v112, v104
	v_fmac_f32_dpp v112, v214, v22 quad_perm:[3,3,3,3] row_mask:0xf bank_mask:0xf
	v_mov_b32_e32 v113, v105
	v_fmac_f32_dpp v113, v215, v23 quad_perm:[3,3,3,3] row_mask:0xf bank_mask:0xf
	v_fmac_f32_dpp v80, v216, v24 quad_perm:[0,0,0,0] row_mask:0xf bank_mask:0xf
	v_fmac_f32_dpp v81, v217, v25 quad_perm:[0,0,0,0] row_mask:0xf bank_mask:0xf
	v_fmac_f32_dpp v112, v218, v26 quad_perm:[0,0,0,0] row_mask:0xf bank_mask:0xf
	v_fmac_f32_dpp v113, v219, v27 quad_perm:[0,0,0,0] row_mask:0xf bank_mask:0xf
	v_fmac_f32_dpp v80, v216, v36 quad_perm:[1,1,1,1] row_mask:0xf bank_mask:0xf
	v_fmac_f32_dpp v81, v217, v37 quad_perm:[1,1,1,1] row_mask:0xf bank_mask:0xf
	v_mov_b32_e32 v104, v112
	v_fmac_f32_dpp v104, v218, v38 quad_perm:[1,1,1,1] row_mask:0xf bank_mask:0xf
	v_mov_b32_e32 v105, v113
	v_fmac_f32_dpp v105, v219, v39 quad_perm:[1,1,1,1] row_mask:0xf bank_mask:0xf
	v_fmac_f32_dpp v80, v216, v42 quad_perm:[2,2,2,2] row_mask:0xf bank_mask:0xf
	v_fmac_f32_dpp v81, v217, v43 quad_perm:[2,2,2,2] row_mask:0xf bank_mask:0xf
	v_fmac_f32_dpp v104, v218, v46 quad_perm:[2,2,2,2] row_mask:0xf bank_mask:0xf
	v_fmac_f32_dpp v105, v219, v47 quad_perm:[2,2,2,2] row_mask:0xf bank_mask:0xf
	v_fmac_f32_dpp v80, v216, v50 quad_perm:[3,3,3,3] row_mask:0xf bank_mask:0xf
	v_fmac_f32_dpp v81, v217, v51 quad_perm:[3,3,3,3] row_mask:0xf bank_mask:0xf
	v_mov_b32_e32 v100, v104
	v_fmac_f32_dpp v100, v218, v54 quad_perm:[3,3,3,3] row_mask:0xf bank_mask:0xf
	v_mov_b32_e32 v101, v105
	v_fmac_f32_dpp v101, v219, v55 quad_perm:[3,3,3,3] row_mask:0xf bank_mask:0xf
	v_mov_b32_e32 v102, v80
	v_mov_b32_e32 v103, v100
	v_mov_b32_e32 v100, v81
	v_pk_add_f32 v[80:81], v[102:103], v[100:101]
	s_nop 0
	v_add_f32_e32 v31, v80, v81
	v_fmac_f32_dpp v31, v220, v56 quad_perm:[0,0,0,0] row_mask:0xf bank_mask:0xf
	v_sub_f32_e32 v57, v60, v31
	ds_read_b128 v[212:215], v228 offset:43776
	ds_read_b128 v[216:219], v228 offset:43840
	ds_read_b128 v[220:223], v228 offset:43904
	s_waitcnt lgkmcnt(3)
; DI void gdn_pre(const Params& p, int ch, char* smem) {
;     ...
;   for (int i = 1; i < 64; ++i) {
;     f32x2 sa = {0.f, 0.f}, sb = {0.f, 0.f};
;     const f32x2* arow = (const f32x2*)(Amat + i * 64);
; #pragma unroll
;     for (int k = 0; k < (i >> 1); ++k) {
;       const f32x2 a2 = arow[k];
;       if (k & 1) sb = __builtin_elementwise_fma(a2, c2[k], sb);
;       else sa = __builtin_elementwise_fma(a2, c2[k], sa);
;     }
;     float tot = (sa[0] + sa[1]) + (sb[0] + sb[1]);
;     if (i & 1) tot += Amat[i * 64 + i - 1] * c2[(i - 1) >> 1][0];
;     c2[i >> 1][i & 1] -= tot;
;     __builtin_amdgcn_sched_barrier(0);
;   }
	v_mul_f32_dpp v60, v196, v0 quad_perm:[0,0,0,0] row_mask:0xf bank_mask:0xf
	v_mul_f32_dpp v61, v197, v1 quad_perm:[0,0,0,0] row_mask:0xf bank_mask:0xf
	v_mul_f32_dpp v80, v198, v6 quad_perm:[0,0,0,0] row_mask:0xf bank_mask:0xf
	v_mul_f32_dpp v81, v199, v7 quad_perm:[0,0,0,0] row_mask:0xf bank_mask:0xf
	v_fmac_f32_dpp v60, v196, v8 quad_perm:[1,1,1,1] row_mask:0xf bank_mask:0xf
	v_fmac_f32_dpp v61, v197, v9 quad_perm:[1,1,1,1] row_mask:0xf bank_mask:0xf
	v_fmac_f32_dpp v80, v198, v10 quad_perm:[1,1,1,1] row_mask:0xf bank_mask:0xf
	v_fmac_f32_dpp v81, v199, v11 quad_perm:[1,1,1,1] row_mask:0xf bank_mask:0xf
	v_fmac_f32_dpp v60, v196, v12 quad_perm:[2,2,2,2] row_mask:0xf bank_mask:0xf
	v_fmac_f32_dpp v61, v197, v13 quad_perm:[2,2,2,2] row_mask:0xf bank_mask:0xf
	v_fmac_f32_dpp v80, v198, v16 quad_perm:[2,2,2,2] row_mask:0xf bank_mask:0xf
	v_fmac_f32_dpp v81, v199, v17 quad_perm:[2,2,2,2] row_mask:0xf bank_mask:0xf
	v_fmac_f32_dpp v60, v196, v20 quad_perm:[3,3,3,3] row_mask:0xf bank_mask:0xf
	v_fmac_f32_dpp v61, v197, v21 quad_perm:[3,3,3,3] row_mask:0xf bank_mask:0xf
	v_fmac_f32_dpp v80, v198, v22 quad_perm:[3,3,3,3] row_mask:0xf bank_mask:0xf
	v_fmac_f32_dpp v81, v199, v23 quad_perm:[3,3,3,3] row_mask:0xf bank_mask:0xf
	v_fmac_f32_dpp v60, v200, v24 quad_perm:[0,0,0,0] row_mask:0xf bank_mask:0xf
	v_fmac_f32_dpp v61, v201, v25 quad_perm:[0,0,0,0] row_mask:0xf bank_mask:0xf
	v_fmac_f32_dpp v80, v202, v26 quad_perm:[0,0,0,0] row_mask:0xf bank_mask:0xf
	v_fmac_f32_dpp v81, v203, v27 quad_perm:[0,0,0,0] row_mask:0xf bank_mask:0xf
	v_fmac_f32_dpp v60, v200, v36 quad_perm:[1,1,1,1] row_mask:0xf bank_mask:0xf
	v_fmac_f32_dpp v61, v201, v37 quad_perm:[1,1,1,1] row_mask:0xf bank_mask:0xf
	v_fmac_f32_dpp v80, v202, v38 quad_perm:[1,1,1,1] row_mask:0xf bank_mask:0xf
	v_fmac_f32_dpp v81, v203, v39 quad_perm:[1,1,1,1] row_mask:0xf bank_mask:0xf
	v_fmac_f32_dpp v60, v200, v42 quad_perm:[2,2,2,2] row_mask:0xf bank_mask:0xf
	v_fmac_f32_dpp v61, v201, v43 quad_perm:[2,2,2,2] row_mask:0xf bank_mask:0xf
	v_fmac_f32_dpp v80, v202, v46 quad_perm:[2,2,2,2] row_mask:0xf bank_mask:0xf
	v_fmac_f32_dpp v81, v203, v47 quad_perm:[2,2,2,2] row_mask:0xf bank_mask:0xf
	v_fmac_f32_dpp v60, v200, v50 quad_perm:[3,3,3,3] row_mask:0xf bank_mask:0xf
	v_fmac_f32_dpp v61, v201, v51 quad_perm:[3,3,3,3] row_mask:0xf bank_mask:0xf
	v_fmac_f32_dpp v80, v202, v54 quad_perm:[3,3,3,3] row_mask:0xf bank_mask:0xf
	v_fmac_f32_dpp v81, v203, v55 quad_perm:[3,3,3,3] row_mask:0xf bank_mask:0xf
	v_fmac_f32_dpp v60, v204, v56 quad_perm:[0,0,0,0] row_mask:0xf bank_mask:0xf
	v_fmac_f32_dpp v61, v205, v57 quad_perm:[0,0,0,0] row_mask:0xf bank_mask:0xf
	v_mov_b32_e32 v100, v80
	v_mov_b32_e32 v101, v60
	v_mov_b32_e32 v60, v81
	v_pk_add_f32 v[60:61], v[100:101], v[60:61]
	s_nop 0
	v_pk_add_f32 v[60:61], v[60:61], v[60:61] op_sel:[0,1] op_sel_hi:[1,0]
	s_nop 0
	v_pk_add_f32 v[60:61], v[98:99], v[60:61] neg_lo:[0,1] neg_hi:[0,1]
	ds_read_b128 v[196:199], v228 offset:44032
	ds_read_b128 v[200:203], v228 offset:44096
	ds_read_b128 v[204:207], v228 offset:44160
	s_waitcnt lgkmcnt(3)
	v_mul_f32_dpp v80, v212, v0 quad_perm:[0,0,0,0] row_mask:0xf bank_mask:0xf
	v_mul_f32_dpp v81, v213, v1 quad_perm:[0,0,0,0] row_mask:0xf bank_mask:0xf
	v_mul_f32_dpp v98, v214, v6 quad_perm:[0,0,0,0] row_mask:0xf bank_mask:0xf
	v_mul_f32_dpp v99, v215, v7 quad_perm:[0,0,0,0] row_mask:0xf bank_mask:0xf
	v_fmac_f32_dpp v80, v212, v8 quad_perm:[1,1,1,1] row_mask:0xf bank_mask:0xf
	v_fmac_f32_dpp v81, v213, v9 quad_perm:[1,1,1,1] row_mask:0xf bank_mask:0xf
	v_mov_b32_e32 v102, v98
	v_fmac_f32_dpp v102, v214, v10 quad_perm:[1,1,1,1] row_mask:0xf bank_mask:0xf
	v_mov_b32_e32 v103, v99
	v_fmac_f32_dpp v103, v215, v11 quad_perm:[1,1,1,1] row_mask:0xf bank_mask:0xf
	v_fmac_f32_dpp v80, v212, v12 quad_perm:[2,2,2,2] row_mask:0xf bank_mask:0xf
	v_fmac_f32_dpp v81, v213, v13 quad_perm:[2,2,2,2] row_mask:0xf bank_mask:0xf
	v_mov_b32_e32 v106, v102
	v_fmac_f32_dpp v106, v214, v16 quad_perm:[2,2,2,2] row_mask:0xf bank_mask:0xf
	v_mov_b32_e32 v107, v103
	v_fmac_f32_dpp v107, v215, v17 quad_perm:[2,2,2,2] row_mask:0xf bank_mask:0xf
	v_fmac_f32_dpp v80, v212, v20 quad_perm:[3,3,3,3] row_mask:0xf bank_mask:0xf
	v_fmac_f32_dpp v81, v213, v21 quad_perm:[3,3,3,3] row_mask:0xf bank_mask:0xf
	v_fmac_f32_dpp v106, v214, v22 quad_perm:[3,3,3,3] row_mask:0xf bank_mask:0xf
	v_fmac_f32_dpp v107, v215, v23 quad_perm:[3,3,3,3] row_mask:0xf bank_mask:0xf
	v_fmac_f32_dpp v80, v216, v24 quad_perm:[0,0,0,0] row_mask:0xf bank_mask:0xf
	v_fmac_f32_dpp v81, v217, v25 quad_perm:[0,0,0,0] row_mask:0xf bank_mask:0xf
	v_mov_b32_e32 v110, v106
	v_fmac_f32_dpp v110, v218, v26 quad_perm:[0,0,0,0] row_mask:0xf bank_mask:0xf
	v_mov_b32_e32 v111, v107
	v_fmac_f32_dpp v111, v219, v27 quad_perm:[0,0,0,0] row_mask:0xf bank_mask:0xf
	v_fmac_f32_dpp v80, v216, v36 quad_perm:[1,1,1,1] row_mask:0xf bank_mask:0xf
	v_fmac_f32_dpp v81, v217, v37 quad_perm:[1,1,1,1] row_mask:0xf bank_mask:0xf
	v_fmac_f32_dpp v110, v218, v38 quad_perm:[1,1,1,1] row_mask:0xf bank_mask:0xf
	v_fmac_f32_dpp v111, v219, v39 quad_perm:[1,1,1,1] row_mask:0xf bank_mask:0xf
	v_fmac_f32_dpp v80, v216, v42 quad_perm:[2,2,2,2] row_mask:0xf bank_mask:0xf
	v_fmac_f32_dpp v81, v217, v43 quad_perm:[2,2,2,2] row_mask:0xf bank_mask:0xf
	v_mov_b32_e32 v98, v110
	v_fmac_f32_dpp v98, v218, v46 quad_perm:[2,2,2,2] row_mask:0xf bank_mask:0xf
	v_mov_b32_e32 v99, v111
	v_fmac_f32_dpp v99, v219, v47 quad_perm:[2,2,2,2] row_mask:0xf bank_mask:0xf
	v_fmac_f32_dpp v80, v216, v50 quad_perm:[3,3,3,3] row_mask:0xf bank_mask:0xf
	v_fmac_f32_dpp v81, v217, v51 quad_perm:[3,3,3,3] row_mask:0xf bank_mask:0xf
	v_fmac_f32_dpp v98, v218, v54 quad_perm:[3,3,3,3] row_mask:0xf bank_mask:0xf
	v_fmac_f32_dpp v99, v219, v55 quad_perm:[3,3,3,3] row_mask:0xf bank_mask:0xf
	v_fmac_f32_dpp v80, v220, v56 quad_perm:[0,0,0,0] row_mask:0xf bank_mask:0xf
	v_fmac_f32_dpp v81, v221, v57 quad_perm:[0,0,0,0] row_mask:0xf bank_mask:0xf
	v_mov_b32_e32 v100, v98
	v_mov_b32_e32 v101, v80
	v_mov_b32_e32 v80, v99
	v_pk_add_f32 v[80:81], v[100:101], v[80:81]
	s_nop 0
	v_add_f32_e32 v19, v80, v81
	v_fmac_f32_dpp v19, v222, v60 quad_perm:[0,0,0,0] row_mask:0xf bank_mask:0xf
	v_sub_f32_e32 v61, v64, v19
	ds_read_b128 v[212:215], v228 offset:44288
	ds_read_b128 v[216:219], v228 offset:44352
	ds_read_b128 v[220:223], v228 offset:44416
	s_waitcnt lgkmcnt(3)
; DI void gdn_pre(const Params& p, int ch, char* smem) {
;     ...
;   for (int i = 1; i < 64; ++i) {
;     f32x2 sa = {0.f, 0.f}, sb = {0.f, 0.f};
;     const f32x2* arow = (const f32x2*)(Amat + i * 64);
; #pragma unroll
;     for (int k = 0; k < (i >> 1); ++k) {
;       const f32x2 a2 = arow[k];
;       if (k & 1) sb = __builtin_elementwise_fma(a2, c2[k], sb);
;       else sa = __builtin_elementwise_fma(a2, c2[k], sa);
;     }
;     float tot = (sa[0] + sa[1]) + (sb[0] + sb[1]);
;     if (i & 1) tot += Amat[i * 64 + i - 1] * c2[(i - 1) >> 1][0];
;     c2[i >> 1][i & 1] -= tot;
;     __builtin_amdgcn_sched_barrier(0);
;   }
	v_mul_f32_dpp v64, v196, v0 quad_perm:[0,0,0,0] row_mask:0xf bank_mask:0xf
	v_mul_f32_dpp v65, v197, v1 quad_perm:[0,0,0,0] row_mask:0xf bank_mask:0xf
	v_mul_f32_dpp v80, v198, v6 quad_perm:[0,0,0,0] row_mask:0xf bank_mask:0xf
	v_mul_f32_dpp v81, v199, v7 quad_perm:[0,0,0,0] row_mask:0xf bank_mask:0xf
	v_fmac_f32_dpp v64, v196, v8 quad_perm:[1,1,1,1] row_mask:0xf bank_mask:0xf
	v_fmac_f32_dpp v65, v197, v9 quad_perm:[1,1,1,1] row_mask:0xf bank_mask:0xf
	v_fmac_f32_dpp v80, v198, v10 quad_perm:[1,1,1,1] row_mask:0xf bank_mask:0xf
	v_fmac_f32_dpp v81, v199, v11 quad_perm:[1,1,1,1] row_mask:0xf bank_mask:0xf
	v_fmac_f32_dpp v64, v196, v12 quad_perm:[2,2,2,2] row_mask:0xf bank_mask:0xf
	v_fmac_f32_dpp v65, v197, v13 quad_perm:[2,2,2,2] row_mask:0xf bank_mask:0xf
	v_fmac_f32_dpp v80, v198, v16 quad_perm:[2,2,2,2] row_mask:0xf bank_mask:0xf
	v_fmac_f32_dpp v81, v199, v17 quad_perm:[2,2,2,2] row_mask:0xf bank_mask:0xf
	v_fmac_f32_dpp v64, v196, v20 quad_perm:[3,3,3,3] row_mask:0xf bank_mask:0xf
	v_fmac_f32_dpp v65, v197, v21 quad_perm:[3,3,3,3] row_mask:0xf bank_mask:0xf
	v_fmac_f32_dpp v80, v198, v22 quad_perm:[3,3,3,3] row_mask:0xf bank_mask:0xf
	v_fmac_f32_dpp v81, v199, v23 quad_perm:[3,3,3,3] row_mask:0xf bank_mask:0xf
	v_fmac_f32_dpp v64, v200, v24 quad_perm:[0,0,0,0] row_mask:0xf bank_mask:0xf
	v_fmac_f32_dpp v65, v201, v25 quad_perm:[0,0,0,0] row_mask:0xf bank_mask:0xf
	v_fmac_f32_dpp v80, v202, v26 quad_perm:[0,0,0,0] row_mask:0xf bank_mask:0xf
	v_fmac_f32_dpp v81, v203, v27 quad_perm:[0,0,0,0] row_mask:0xf bank_mask:0xf
	v_fmac_f32_dpp v64, v200, v36 quad_perm:[1,1,1,1] row_mask:0xf bank_mask:0xf
	v_fmac_f32_dpp v65, v201, v37 quad_perm:[1,1,1,1] row_mask:0xf bank_mask:0xf
	v_fmac_f32_dpp v80, v202, v38 quad_perm:[1,1,1,1] row_mask:0xf bank_mask:0xf
	v_fmac_f32_dpp v81, v203, v39 quad_perm:[1,1,1,1] row_mask:0xf bank_mask:0xf
	v_fmac_f32_dpp v64, v200, v42 quad_perm:[2,2,2,2] row_mask:0xf bank_mask:0xf
	v_fmac_f32_dpp v65, v201, v43 quad_perm:[2,2,2,2] row_mask:0xf bank_mask:0xf
	v_fmac_f32_dpp v80, v202, v46 quad_perm:[2,2,2,2] row_mask:0xf bank_mask:0xf
	v_fmac_f32_dpp v81, v203, v47 quad_perm:[2,2,2,2] row_mask:0xf bank_mask:0xf
	v_fmac_f32_dpp v64, v200, v50 quad_perm:[3,3,3,3] row_mask:0xf bank_mask:0xf
	v_fmac_f32_dpp v65, v201, v51 quad_perm:[3,3,3,3] row_mask:0xf bank_mask:0xf
	v_fmac_f32_dpp v80, v202, v54 quad_perm:[3,3,3,3] row_mask:0xf bank_mask:0xf
	v_fmac_f32_dpp v81, v203, v55 quad_perm:[3,3,3,3] row_mask:0xf bank_mask:0xf
	v_fmac_f32_dpp v64, v204, v56 quad_perm:[0,0,0,0] row_mask:0xf bank_mask:0xf
	v_fmac_f32_dpp v65, v205, v57 quad_perm:[0,0,0,0] row_mask:0xf bank_mask:0xf
	v_fmac_f32_dpp v80, v206, v60 quad_perm:[0,0,0,0] row_mask:0xf bank_mask:0xf
	v_fmac_f32_dpp v81, v207, v61 quad_perm:[0,0,0,0] row_mask:0xf bank_mask:0xf
	v_mov_b32_e32 v98, v64
	v_mov_b32_e32 v99, v80
	v_mov_b32_e32 v80, v65
	v_pk_add_f32 v[64:65], v[98:99], v[80:81]
	s_nop 0
	v_pk_add_f32 v[64:65], v[64:65], v[64:65] op_sel:[0,1] op_sel_hi:[1,0]
	s_nop 0
	v_pk_add_f32 v[64:65], v[96:97], v[64:65] neg_lo:[0,1] neg_hi:[0,1]
	ds_read_b128 v[196:199], v228 offset:44544
	ds_read_b128 v[200:203], v228 offset:44608
	ds_read_b128 v[204:207], v228 offset:44672
	s_waitcnt lgkmcnt(3)
	v_mul_f32_dpp v80, v212, v0 quad_perm:[0,0,0,0] row_mask:0xf bank_mask:0xf
	v_mul_f32_dpp v81, v213, v1 quad_perm:[0,0,0,0] row_mask:0xf bank_mask:0xf
	v_mul_f32_dpp v96, v214, v6 quad_perm:[0,0,0,0] row_mask:0xf bank_mask:0xf
	v_mul_f32_dpp v97, v215, v7 quad_perm:[0,0,0,0] row_mask:0xf bank_mask:0xf
	v_fmac_f32_dpp v80, v212, v8 quad_perm:[1,1,1,1] row_mask:0xf bank_mask:0xf
	v_fmac_f32_dpp v81, v213, v9 quad_perm:[1,1,1,1] row_mask:0xf bank_mask:0xf
	v_mov_b32_e32 v100, v96
	v_fmac_f32_dpp v100, v214, v10 quad_perm:[1,1,1,1] row_mask:0xf bank_mask:0xf
	v_mov_b32_e32 v101, v97
	v_fmac_f32_dpp v101, v215, v11 quad_perm:[1,1,1,1] row_mask:0xf bank_mask:0xf
	v_fmac_f32_dpp v80, v212, v12 quad_perm:[2,2,2,2] row_mask:0xf bank_mask:0xf
	v_fmac_f32_dpp v81, v213, v13 quad_perm:[2,2,2,2] row_mask:0xf bank_mask:0xf
	v_mov_b32_e32 v104, v100
	v_fmac_f32_dpp v104, v214, v16 quad_perm:[2,2,2,2] row_mask:0xf bank_mask:0xf
	v_mov_b32_e32 v105, v101
	v_fmac_f32_dpp v105, v215, v17 quad_perm:[2,2,2,2] row_mask:0xf bank_mask:0xf
	v_fmac_f32_dpp v80, v212, v20 quad_perm:[3,3,3,3] row_mask:0xf bank_mask:0xf
	v_fmac_f32_dpp v81, v213, v21 quad_perm:[3,3,3,3] row_mask:0xf bank_mask:0xf
	v_mov_b32_e32 v108, v104
	v_fmac_f32_dpp v108, v214, v22 quad_perm:[3,3,3,3] row_mask:0xf bank_mask:0xf
	v_mov_b32_e32 v109, v105
	v_fmac_f32_dpp v109, v215, v23 quad_perm:[3,3,3,3] row_mask:0xf bank_mask:0xf
	v_fmac_f32_dpp v80, v216, v24 quad_perm:[0,0,0,0] row_mask:0xf bank_mask:0xf
	v_fmac_f32_dpp v81, v217, v25 quad_perm:[0,0,0,0] row_mask:0xf bank_mask:0xf
	v_fmac_f32_dpp v108, v218, v26 quad_perm:[0,0,0,0] row_mask:0xf bank_mask:0xf
	v_fmac_f32_dpp v109, v219, v27 quad_perm:[0,0,0,0] row_mask:0xf bank_mask:0xf
	v_fmac_f32_dpp v80, v216, v36 quad_perm:[1,1,1,1] row_mask:0xf bank_mask:0xf
	v_fmac_f32_dpp v81, v217, v37 quad_perm:[1,1,1,1] row_mask:0xf bank_mask:0xf
	v_fmac_f32_dpp v108, v218, v38 quad_perm:[1,1,1,1] row_mask:0xf bank_mask:0xf
	v_fmac_f32_dpp v109, v219, v39 quad_perm:[1,1,1,1] row_mask:0xf bank_mask:0xf
	v_fmac_f32_dpp v80, v216, v42 quad_perm:[2,2,2,2] row_mask:0xf bank_mask:0xf
	v_fmac_f32_dpp v81, v217, v43 quad_perm:[2,2,2,2] row_mask:0xf bank_mask:0xf
	v_mov_b32_e32 v104, v108
	v_fmac_f32_dpp v104, v218, v46 quad_perm:[2,2,2,2] row_mask:0xf bank_mask:0xf
	v_mov_b32_e32 v105, v109
	v_fmac_f32_dpp v105, v219, v47 quad_perm:[2,2,2,2] row_mask:0xf bank_mask:0xf
	v_fmac_f32_dpp v80, v216, v50 quad_perm:[3,3,3,3] row_mask:0xf bank_mask:0xf
	v_fmac_f32_dpp v81, v217, v51 quad_perm:[3,3,3,3] row_mask:0xf bank_mask:0xf
	v_mov_b32_e32 v96, v104
	v_fmac_f32_dpp v96, v218, v54 quad_perm:[3,3,3,3] row_mask:0xf bank_mask:0xf
	v_mov_b32_e32 v97, v105
	v_fmac_f32_dpp v97, v219, v55 quad_perm:[3,3,3,3] row_mask:0xf bank_mask:0xf
	v_fmac_f32_dpp v80, v220, v56 quad_perm:[0,0,0,0] row_mask:0xf bank_mask:0xf
	v_fmac_f32_dpp v81, v221, v57 quad_perm:[0,0,0,0] row_mask:0xf bank_mask:0xf
	v_fmac_f32_dpp v96, v222, v60 quad_perm:[0,0,0,0] row_mask:0xf bank_mask:0xf
	v_fmac_f32_dpp v97, v223, v61 quad_perm:[0,0,0,0] row_mask:0xf bank_mask:0xf
	v_mov_b32_e32 v98, v80
	v_mov_b32_e32 v99, v96
	v_mov_b32_e32 v96, v81
	v_pk_add_f32 v[80:81], v[98:99], v[96:97]
	s_nop 0
	v_add_f32_e32 v31, v80, v81
	v_fmac_f32_dpp v31, v220, v64 quad_perm:[1,1,1,1] row_mask:0xf bank_mask:0xf
	v_sub_f32_e32 v65, v68, v31
	ds_read_b128 v[212:215], v228 offset:44800
	ds_read_b128 v[216:219], v228 offset:44864
	ds_read_b128 v[220:223], v228 offset:44928
	s_waitcnt lgkmcnt(3)
; DI void gdn_pre(const Params& p, int ch, char* smem) {
;     ...
;   for (int i = 1; i < 64; ++i) {
;     f32x2 sa = {0.f, 0.f}, sb = {0.f, 0.f};
;     const f32x2* arow = (const f32x2*)(Amat + i * 64);
; #pragma unroll
;     for (int k = 0; k < (i >> 1); ++k) {
;       const f32x2 a2 = arow[k];
;       if (k & 1) sb = __builtin_elementwise_fma(a2, c2[k], sb);
;       else sa = __builtin_elementwise_fma(a2, c2[k], sa);
;     }
;     float tot = (sa[0] + sa[1]) + (sb[0] + sb[1]);
;     if (i & 1) tot += Amat[i * 64 + i - 1] * c2[(i - 1) >> 1][0];
;     c2[i >> 1][i & 1] -= tot;
;     __builtin_amdgcn_sched_barrier(0);
;   }
	v_mul_f32_dpp v68, v196, v0 quad_perm:[0,0,0,0] row_mask:0xf bank_mask:0xf
	v_mul_f32_dpp v69, v197, v1 quad_perm:[0,0,0,0] row_mask:0xf bank_mask:0xf
	v_mul_f32_dpp v80, v198, v6 quad_perm:[0,0,0,0] row_mask:0xf bank_mask:0xf
	v_mul_f32_dpp v81, v199, v7 quad_perm:[0,0,0,0] row_mask:0xf bank_mask:0xf
	v_fmac_f32_dpp v68, v196, v8 quad_perm:[1,1,1,1] row_mask:0xf bank_mask:0xf
	v_fmac_f32_dpp v69, v197, v9 quad_perm:[1,1,1,1] row_mask:0xf bank_mask:0xf
	v_fmac_f32_dpp v80, v198, v10 quad_perm:[1,1,1,1] row_mask:0xf bank_mask:0xf
	v_fmac_f32_dpp v81, v199, v11 quad_perm:[1,1,1,1] row_mask:0xf bank_mask:0xf
	v_fmac_f32_dpp v68, v196, v12 quad_perm:[2,2,2,2] row_mask:0xf bank_mask:0xf
	v_fmac_f32_dpp v69, v197, v13 quad_perm:[2,2,2,2] row_mask:0xf bank_mask:0xf
	v_fmac_f32_dpp v80, v198, v16 quad_perm:[2,2,2,2] row_mask:0xf bank_mask:0xf
	v_fmac_f32_dpp v81, v199, v17 quad_perm:[2,2,2,2] row_mask:0xf bank_mask:0xf
	v_fmac_f32_dpp v68, v196, v20 quad_perm:[3,3,3,3] row_mask:0xf bank_mask:0xf
	v_fmac_f32_dpp v69, v197, v21 quad_perm:[3,3,3,3] row_mask:0xf bank_mask:0xf
	v_fmac_f32_dpp v80, v198, v22 quad_perm:[3,3,3,3] row_mask:0xf bank_mask:0xf
	v_fmac_f32_dpp v81, v199, v23 quad_perm:[3,3,3,3] row_mask:0xf bank_mask:0xf
	v_fmac_f32_dpp v68, v200, v24 quad_perm:[0,0,0,0] row_mask:0xf bank_mask:0xf
	v_fmac_f32_dpp v69, v201, v25 quad_perm:[0,0,0,0] row_mask:0xf bank_mask:0xf
	v_fmac_f32_dpp v80, v202, v26 quad_perm:[0,0,0,0] row_mask:0xf bank_mask:0xf
	v_fmac_f32_dpp v81, v203, v27 quad_perm:[0,0,0,0] row_mask:0xf bank_mask:0xf
	v_fmac_f32_dpp v68, v200, v36 quad_perm:[1,1,1,1] row_mask:0xf bank_mask:0xf
	v_fmac_f32_dpp v69, v201, v37 quad_perm:[1,1,1,1] row_mask:0xf bank_mask:0xf
	v_fmac_f32_dpp v80, v202, v38 quad_perm:[1,1,1,1] row_mask:0xf bank_mask:0xf
	v_fmac_f32_dpp v81, v203, v39 quad_perm:[1,1,1,1] row_mask:0xf bank_mask:0xf
	v_fmac_f32_dpp v68, v200, v42 quad_perm:[2,2,2,2] row_mask:0xf bank_mask:0xf
	v_fmac_f32_dpp v69, v201, v43 quad_perm:[2,2,2,2] row_mask:0xf bank_mask:0xf
	v_fmac_f32_dpp v80, v202, v46 quad_perm:[2,2,2,2] row_mask:0xf bank_mask:0xf
	v_fmac_f32_dpp v81, v203, v47 quad_perm:[2,2,2,2] row_mask:0xf bank_mask:0xf
	v_fmac_f32_dpp v68, v200, v50 quad_perm:[3,3,3,3] row_mask:0xf bank_mask:0xf
	v_fmac_f32_dpp v69, v201, v51 quad_perm:[3,3,3,3] row_mask:0xf bank_mask:0xf
	v_fmac_f32_dpp v80, v202, v54 quad_perm:[3,3,3,3] row_mask:0xf bank_mask:0xf
	v_fmac_f32_dpp v81, v203, v55 quad_perm:[3,3,3,3] row_mask:0xf bank_mask:0xf
	v_fmac_f32_dpp v68, v204, v56 quad_perm:[0,0,0,0] row_mask:0xf bank_mask:0xf
	v_fmac_f32_dpp v69, v205, v57 quad_perm:[0,0,0,0] row_mask:0xf bank_mask:0xf
	v_fmac_f32_dpp v80, v206, v60 quad_perm:[0,0,0,0] row_mask:0xf bank_mask:0xf
	v_fmac_f32_dpp v81, v207, v61 quad_perm:[0,0,0,0] row_mask:0xf bank_mask:0xf
	v_fmac_f32_dpp v68, v204, v64 quad_perm:[1,1,1,1] row_mask:0xf bank_mask:0xf
	v_fmac_f32_dpp v69, v205, v65 quad_perm:[1,1,1,1] row_mask:0xf bank_mask:0xf
	v_mov_b32_e32 v96, v80
	v_mov_b32_e32 v97, v68
	v_mov_b32_e32 v68, v81
	v_pk_add_f32 v[68:69], v[96:97], v[68:69]
	s_nop 0
	v_pk_add_f32 v[68:69], v[68:69], v[68:69] op_sel:[0,1] op_sel_hi:[1,0]
	s_nop 0
	v_pk_add_f32 v[68:69], v[94:95], v[68:69] neg_lo:[0,1] neg_hi:[0,1]
	ds_read_b128 v[196:199], v228 offset:45056
	ds_read_b128 v[200:203], v228 offset:45120
	ds_read_b128 v[204:207], v228 offset:45184
	s_waitcnt lgkmcnt(3)
	v_mul_f32_dpp v80, v212, v0 quad_perm:[0,0,0,0] row_mask:0xf bank_mask:0xf
	v_mul_f32_dpp v81, v213, v1 quad_perm:[0,0,0,0] row_mask:0xf bank_mask:0xf
	v_mul_f32_dpp v94, v214, v6 quad_perm:[0,0,0,0] row_mask:0xf bank_mask:0xf
	v_mul_f32_dpp v95, v215, v7 quad_perm:[0,0,0,0] row_mask:0xf bank_mask:0xf
	v_fmac_f32_dpp v80, v212, v8 quad_perm:[1,1,1,1] row_mask:0xf bank_mask:0xf
	v_fmac_f32_dpp v81, v213, v9 quad_perm:[1,1,1,1] row_mask:0xf bank_mask:0xf
	v_mov_b32_e32 v98, v94
	v_fmac_f32_dpp v98, v214, v10 quad_perm:[1,1,1,1] row_mask:0xf bank_mask:0xf
	v_mov_b32_e32 v99, v95
	v_fmac_f32_dpp v99, v215, v11 quad_perm:[1,1,1,1] row_mask:0xf bank_mask:0xf
	v_fmac_f32_dpp v80, v212, v12 quad_perm:[2,2,2,2] row_mask:0xf bank_mask:0xf
	v_fmac_f32_dpp v81, v213, v13 quad_perm:[2,2,2,2] row_mask:0xf bank_mask:0xf
	v_mov_b32_e32 v102, v98
	v_fmac_f32_dpp v102, v214, v16 quad_perm:[2,2,2,2] row_mask:0xf bank_mask:0xf
	v_mov_b32_e32 v103, v99
	v_fmac_f32_dpp v103, v215, v17 quad_perm:[2,2,2,2] row_mask:0xf bank_mask:0xf
	v_fmac_f32_dpp v80, v212, v20 quad_perm:[3,3,3,3] row_mask:0xf bank_mask:0xf
	v_fmac_f32_dpp v81, v213, v21 quad_perm:[3,3,3,3] row_mask:0xf bank_mask:0xf
	v_mov_b32_e32 v106, v102
	v_fmac_f32_dpp v106, v214, v22 quad_perm:[3,3,3,3] row_mask:0xf bank_mask:0xf
	v_mov_b32_e32 v107, v103
	v_fmac_f32_dpp v107, v215, v23 quad_perm:[3,3,3,3] row_mask:0xf bank_mask:0xf
	v_fmac_f32_dpp v80, v216, v24 quad_perm:[0,0,0,0] row_mask:0xf bank_mask:0xf
	v_fmac_f32_dpp v81, v217, v25 quad_perm:[0,0,0,0] row_mask:0xf bank_mask:0xf
	v_mov_b32_e32 v94, v106
	v_fmac_f32_dpp v94, v218, v26 quad_perm:[0,0,0,0] row_mask:0xf bank_mask:0xf
	v_mov_b32_e32 v95, v107
	v_fmac_f32_dpp v95, v219, v27 quad_perm:[0,0,0,0] row_mask:0xf bank_mask:0xf
	v_fmac_f32_dpp v80, v216, v36 quad_perm:[1,1,1,1] row_mask:0xf bank_mask:0xf
	v_fmac_f32_dpp v81, v217, v37 quad_perm:[1,1,1,1] row_mask:0xf bank_mask:0xf
	v_mov_b32_e32 v106, v94
	v_fmac_f32_dpp v106, v218, v38 quad_perm:[1,1,1,1] row_mask:0xf bank_mask:0xf
	v_mov_b32_e32 v107, v95
	v_fmac_f32_dpp v107, v219, v39 quad_perm:[1,1,1,1] row_mask:0xf bank_mask:0xf
	v_fmac_f32_dpp v80, v216, v42 quad_perm:[2,2,2,2] row_mask:0xf bank_mask:0xf
	v_fmac_f32_dpp v81, v217, v43 quad_perm:[2,2,2,2] row_mask:0xf bank_mask:0xf
; DI void gdn_pre(const Params& p, int ch, char* smem) {
;     ...
;   for (int i = 1; i < 64; ++i) {
;     f32x2 sa = {0.f, 0.f}, sb = {0.f, 0.f};
;     const f32x2* arow = (const f32x2*)(Amat + i * 64);
; #pragma unroll
;     for (int k = 0; k < (i >> 1); ++k) {
;       const f32x2 a2 = arow[k];
;       if (k & 1) sb = __builtin_elementwise_fma(a2, c2[k], sb);
;       else sa = __builtin_elementwise_fma(a2, c2[k], sa);
;     }
;     float tot = (sa[0] + sa[1]) + (sb[0] + sb[1]);
;     if (i & 1) tot += Amat[i * 64 + i - 1] * c2[(i - 1) >> 1][0];
;     c2[i >> 1][i & 1] -= tot;
;     __builtin_amdgcn_sched_barrier(0);
;   }
	v_fmac_f32_dpp v106, v218, v46 quad_perm:[2,2,2,2] row_mask:0xf bank_mask:0xf
	v_fmac_f32_dpp v107, v219, v47 quad_perm:[2,2,2,2] row_mask:0xf bank_mask:0xf
	v_fmac_f32_dpp v80, v216, v50 quad_perm:[3,3,3,3] row_mask:0xf bank_mask:0xf
	v_fmac_f32_dpp v81, v217, v51 quad_perm:[3,3,3,3] row_mask:0xf bank_mask:0xf
	v_mov_b32_e32 v94, v106
	v_fmac_f32_dpp v94, v218, v54 quad_perm:[3,3,3,3] row_mask:0xf bank_mask:0xf
	v_mov_b32_e32 v95, v107
	v_fmac_f32_dpp v95, v219, v55 quad_perm:[3,3,3,3] row_mask:0xf bank_mask:0xf
	v_fmac_f32_dpp v80, v220, v56 quad_perm:[0,0,0,0] row_mask:0xf bank_mask:0xf
	v_fmac_f32_dpp v81, v221, v57 quad_perm:[0,0,0,0] row_mask:0xf bank_mask:0xf
	v_fmac_f32_dpp v94, v222, v60 quad_perm:[0,0,0,0] row_mask:0xf bank_mask:0xf
	v_fmac_f32_dpp v95, v223, v61 quad_perm:[0,0,0,0] row_mask:0xf bank_mask:0xf
	v_fmac_f32_dpp v80, v220, v64 quad_perm:[1,1,1,1] row_mask:0xf bank_mask:0xf
	v_fmac_f32_dpp v81, v221, v65 quad_perm:[1,1,1,1] row_mask:0xf bank_mask:0xf
	v_mov_b32_e32 v96, v94
	v_mov_b32_e32 v97, v80
	v_mov_b32_e32 v80, v95
	v_pk_add_f32 v[80:81], v[96:97], v[80:81]
	s_nop 0
	v_add_f32_e32 v19, v80, v81
	v_fmac_f32_dpp v19, v222, v68 quad_perm:[1,1,1,1] row_mask:0xf bank_mask:0xf
	v_sub_f32_e32 v69, v70, v19
	ds_read_b128 v[212:215], v228 offset:45312
	ds_read_b128 v[216:219], v228 offset:45376
	ds_read_b128 v[220:223], v228 offset:45440
	s_waitcnt lgkmcnt(3)
	v_mul_f32_dpp v70, v196, v0 quad_perm:[0,0,0,0] row_mask:0xf bank_mask:0xf
	v_mul_f32_dpp v71, v197, v1 quad_perm:[0,0,0,0] row_mask:0xf bank_mask:0xf
	v_mul_f32_dpp v80, v198, v6 quad_perm:[0,0,0,0] row_mask:0xf bank_mask:0xf
	v_mul_f32_dpp v81, v199, v7 quad_perm:[0,0,0,0] row_mask:0xf bank_mask:0xf
	v_fmac_f32_dpp v70, v196, v8 quad_perm:[1,1,1,1] row_mask:0xf bank_mask:0xf
	v_fmac_f32_dpp v71, v197, v9 quad_perm:[1,1,1,1] row_mask:0xf bank_mask:0xf
	v_fmac_f32_dpp v80, v198, v10 quad_perm:[1,1,1,1] row_mask:0xf bank_mask:0xf
	v_fmac_f32_dpp v81, v199, v11 quad_perm:[1,1,1,1] row_mask:0xf bank_mask:0xf
	v_fmac_f32_dpp v70, v196, v12 quad_perm:[2,2,2,2] row_mask:0xf bank_mask:0xf
	v_fmac_f32_dpp v71, v197, v13 quad_perm:[2,2,2,2] row_mask:0xf bank_mask:0xf
	v_fmac_f32_dpp v80, v198, v16 quad_perm:[2,2,2,2] row_mask:0xf bank_mask:0xf
	v_fmac_f32_dpp v81, v199, v17 quad_perm:[2,2,2,2] row_mask:0xf bank_mask:0xf
	v_fmac_f32_dpp v70, v196, v20 quad_perm:[3,3,3,3] row_mask:0xf bank_mask:0xf
	v_fmac_f32_dpp v71, v197, v21 quad_perm:[3,3,3,3] row_mask:0xf bank_mask:0xf
	v_fmac_f32_dpp v80, v198, v22 quad_perm:[3,3,3,3] row_mask:0xf bank_mask:0xf
	v_fmac_f32_dpp v81, v199, v23 quad_perm:[3,3,3,3] row_mask:0xf bank_mask:0xf
	v_fmac_f32_dpp v70, v200, v24 quad_perm:[0,0,0,0] row_mask:0xf bank_mask:0xf
	v_fmac_f32_dpp v71, v201, v25 quad_perm:[0,0,0,0] row_mask:0xf bank_mask:0xf
	v_fmac_f32_dpp v80, v202, v26 quad_perm:[0,0,0,0] row_mask:0xf bank_mask:0xf
	v_fmac_f32_dpp v81, v203, v27 quad_perm:[0,0,0,0] row_mask:0xf bank_mask:0xf
	v_fmac_f32_dpp v70, v200, v36 quad_perm:[1,1,1,1] row_mask:0xf bank_mask:0xf
	v_fmac_f32_dpp v71, v201, v37 quad_perm:[1,1,1,1] row_mask:0xf bank_mask:0xf
	v_fmac_f32_dpp v80, v202, v38 quad_perm:[1,1,1,1] row_mask:0xf bank_mask:0xf
	v_fmac_f32_dpp v81, v203, v39 quad_perm:[1,1,1,1] row_mask:0xf bank_mask:0xf
	v_fmac_f32_dpp v70, v200, v42 quad_perm:[2,2,2,2] row_mask:0xf bank_mask:0xf
	v_fmac_f32_dpp v71, v201, v43 quad_perm:[2,2,2,2] row_mask:0xf bank_mask:0xf
	v_fmac_f32_dpp v80, v202, v46 quad_perm:[2,2,2,2] row_mask:0xf bank_mask:0xf
	v_fmac_f32_dpp v81, v203, v47 quad_perm:[2,2,2,2] row_mask:0xf bank_mask:0xf
	v_fmac_f32_dpp v70, v200, v50 quad_perm:[3,3,3,3] row_mask:0xf bank_mask:0xf
	v_fmac_f32_dpp v71, v201, v51 quad_perm:[3,3,3,3] row_mask:0xf bank_mask:0xf
	v_fmac_f32_dpp v80, v202, v54 quad_perm:[3,3,3,3] row_mask:0xf bank_mask:0xf
	v_fmac_f32_dpp v81, v203, v55 quad_perm:[3,3,3,3] row_mask:0xf bank_mask:0xf
	v_fmac_f32_dpp v70, v204, v56 quad_perm:[0,0,0,0] row_mask:0xf bank_mask:0xf
	v_fmac_f32_dpp v71, v205, v57 quad_perm:[0,0,0,0] row_mask:0xf bank_mask:0xf
	v_fmac_f32_dpp v80, v206, v60 quad_perm:[0,0,0,0] row_mask:0xf bank_mask:0xf
	v_fmac_f32_dpp v81, v207, v61 quad_perm:[0,0,0,0] row_mask:0xf bank_mask:0xf
	v_fmac_f32_dpp v70, v204, v64 quad_perm:[1,1,1,1] row_mask:0xf bank_mask:0xf
	v_fmac_f32_dpp v71, v205, v65 quad_perm:[1,1,1,1] row_mask:0xf bank_mask:0xf
	v_fmac_f32_dpp v80, v206, v68 quad_perm:[1,1,1,1] row_mask:0xf bank_mask:0xf
	v_fmac_f32_dpp v81, v207, v69 quad_perm:[1,1,1,1] row_mask:0xf bank_mask:0xf
	v_mov_b32_e32 v94, v70
	v_mov_b32_e32 v95, v80
	v_mov_b32_e32 v80, v71
	v_pk_add_f32 v[70:71], v[94:95], v[80:81]
	s_nop 0
	v_pk_add_f32 v[70:71], v[70:71], v[70:71] op_sel:[0,1] op_sel_hi:[1,0]
	s_nop 0
	v_pk_add_f32 v[70:71], v[92:93], v[70:71] neg_lo:[0,1] neg_hi:[0,1]
	ds_read_b128 v[196:199], v228 offset:45568
	ds_read_b128 v[200:203], v228 offset:45632
	ds_read_b128 v[204:207], v228 offset:45696
	s_waitcnt lgkmcnt(3)
; DI void gdn_pre(const Params& p, int ch, char* smem) {
;     ...
;   for (int i = 1; i < 64; ++i) {
;     f32x2 sa = {0.f, 0.f}, sb = {0.f, 0.f};
;     const f32x2* arow = (const f32x2*)(Amat + i * 64);
; #pragma unroll
;     for (int k = 0; k < (i >> 1); ++k) {
;       const f32x2 a2 = arow[k];
;       if (k & 1) sb = __builtin_elementwise_fma(a2, c2[k], sb);
;       else sa = __builtin_elementwise_fma(a2, c2[k], sa);
;     }
;     float tot = (sa[0] + sa[1]) + (sb[0] + sb[1]);
;     if (i & 1) tot += Amat[i * 64 + i - 1] * c2[(i - 1) >> 1][0];
;     c2[i >> 1][i & 1] -= tot;
;     __builtin_amdgcn_sched_barrier(0);
;   }
	v_mul_f32_dpp v80, v212, v0 quad_perm:[0,0,0,0] row_mask:0xf bank_mask:0xf
	v_mul_f32_dpp v81, v213, v1 quad_perm:[0,0,0,0] row_mask:0xf bank_mask:0xf
	v_mul_f32_dpp v92, v214, v6 quad_perm:[0,0,0,0] row_mask:0xf bank_mask:0xf
	v_mul_f32_dpp v93, v215, v7 quad_perm:[0,0,0,0] row_mask:0xf bank_mask:0xf
	v_fmac_f32_dpp v80, v212, v8 quad_perm:[1,1,1,1] row_mask:0xf bank_mask:0xf
	v_fmac_f32_dpp v81, v213, v9 quad_perm:[1,1,1,1] row_mask:0xf bank_mask:0xf
	v_mov_b32_e32 v96, v92
	v_fmac_f32_dpp v96, v214, v10 quad_perm:[1,1,1,1] row_mask:0xf bank_mask:0xf
	v_mov_b32_e32 v97, v93
	v_fmac_f32_dpp v97, v215, v11 quad_perm:[1,1,1,1] row_mask:0xf bank_mask:0xf
	v_fmac_f32_dpp v80, v212, v12 quad_perm:[2,2,2,2] row_mask:0xf bank_mask:0xf
	v_fmac_f32_dpp v81, v213, v13 quad_perm:[2,2,2,2] row_mask:0xf bank_mask:0xf
	v_mov_b32_e32 v100, v96
	v_fmac_f32_dpp v100, v214, v16 quad_perm:[2,2,2,2] row_mask:0xf bank_mask:0xf
	v_mov_b32_e32 v101, v97
	v_fmac_f32_dpp v101, v215, v17 quad_perm:[2,2,2,2] row_mask:0xf bank_mask:0xf
	v_fmac_f32_dpp v80, v212, v20 quad_perm:[3,3,3,3] row_mask:0xf bank_mask:0xf
	v_fmac_f32_dpp v81, v213, v21 quad_perm:[3,3,3,3] row_mask:0xf bank_mask:0xf
	v_mov_b32_e32 v104, v100
	v_fmac_f32_dpp v104, v214, v22 quad_perm:[3,3,3,3] row_mask:0xf bank_mask:0xf
	v_mov_b32_e32 v105, v101
	v_fmac_f32_dpp v105, v215, v23 quad_perm:[3,3,3,3] row_mask:0xf bank_mask:0xf
	v_fmac_f32_dpp v80, v216, v24 quad_perm:[0,0,0,0] row_mask:0xf bank_mask:0xf
	v_fmac_f32_dpp v81, v217, v25 quad_perm:[0,0,0,0] row_mask:0xf bank_mask:0xf
	v_mov_b32_e32 v92, v104
	v_fmac_f32_dpp v92, v218, v26 quad_perm:[0,0,0,0] row_mask:0xf bank_mask:0xf
	v_mov_b32_e32 v93, v105
	v_fmac_f32_dpp v93, v219, v27 quad_perm:[0,0,0,0] row_mask:0xf bank_mask:0xf
	v_fmac_f32_dpp v80, v216, v36 quad_perm:[1,1,1,1] row_mask:0xf bank_mask:0xf
	v_fmac_f32_dpp v81, v217, v37 quad_perm:[1,1,1,1] row_mask:0xf bank_mask:0xf
	v_mov_b32_e32 v104, v92
	v_fmac_f32_dpp v104, v218, v38 quad_perm:[1,1,1,1] row_mask:0xf bank_mask:0xf
	v_mov_b32_e32 v105, v93
	v_fmac_f32_dpp v105, v219, v39 quad_perm:[1,1,1,1] row_mask:0xf bank_mask:0xf
	v_fmac_f32_dpp v80, v216, v42 quad_perm:[2,2,2,2] row_mask:0xf bank_mask:0xf
	v_fmac_f32_dpp v81, v217, v43 quad_perm:[2,2,2,2] row_mask:0xf bank_mask:0xf
	v_fmac_f32_dpp v104, v218, v46 quad_perm:[2,2,2,2] row_mask:0xf bank_mask:0xf
	v_fmac_f32_dpp v105, v219, v47 quad_perm:[2,2,2,2] row_mask:0xf bank_mask:0xf
	v_fmac_f32_dpp v80, v216, v50 quad_perm:[3,3,3,3] row_mask:0xf bank_mask:0xf
	v_fmac_f32_dpp v81, v217, v51 quad_perm:[3,3,3,3] row_mask:0xf bank_mask:0xf
	v_mov_b32_e32 v92, v104
	v_fmac_f32_dpp v92, v218, v54 quad_perm:[3,3,3,3] row_mask:0xf bank_mask:0xf
	v_mov_b32_e32 v93, v105
	v_fmac_f32_dpp v93, v219, v55 quad_perm:[3,3,3,3] row_mask:0xf bank_mask:0xf
	v_fmac_f32_dpp v80, v220, v56 quad_perm:[0,0,0,0] row_mask:0xf bank_mask:0xf
	v_fmac_f32_dpp v81, v221, v57 quad_perm:[0,0,0,0] row_mask:0xf bank_mask:0xf
	v_fmac_f32_dpp v92, v222, v60 quad_perm:[0,0,0,0] row_mask:0xf bank_mask:0xf
	v_fmac_f32_dpp v93, v223, v61 quad_perm:[0,0,0,0] row_mask:0xf bank_mask:0xf
	v_fmac_f32_dpp v80, v220, v64 quad_perm:[1,1,1,1] row_mask:0xf bank_mask:0xf
	v_fmac_f32_dpp v81, v221, v65 quad_perm:[1,1,1,1] row_mask:0xf bank_mask:0xf
	v_fmac_f32_dpp v92, v222, v68 quad_perm:[1,1,1,1] row_mask:0xf bank_mask:0xf
	v_fmac_f32_dpp v93, v223, v69 quad_perm:[1,1,1,1] row_mask:0xf bank_mask:0xf
	v_mov_b32_e32 v94, v80
	v_mov_b32_e32 v95, v92
	v_mov_b32_e32 v92, v81
	v_pk_add_f32 v[80:81], v[94:95], v[92:93]
	s_nop 0
	v_add_f32_e32 v31, v80, v81
	v_fmac_f32_dpp v31, v220, v70 quad_perm:[2,2,2,2] row_mask:0xf bank_mask:0xf
	v_sub_f32_e32 v71, v74, v31
	ds_read_b128 v[212:215], v228 offset:45824
	ds_read_b128 v[216:219], v228 offset:45888
	ds_read_b128 v[220:223], v228 offset:45952
	s_waitcnt lgkmcnt(3)
	v_mul_f32_dpp v74, v196, v0 quad_perm:[0,0,0,0] row_mask:0xf bank_mask:0xf
	v_mul_f32_dpp v75, v197, v1 quad_perm:[0,0,0,0] row_mask:0xf bank_mask:0xf
	v_mul_f32_dpp v80, v198, v6 quad_perm:[0,0,0,0] row_mask:0xf bank_mask:0xf
	v_mul_f32_dpp v81, v199, v7 quad_perm:[0,0,0,0] row_mask:0xf bank_mask:0xf
	v_fmac_f32_dpp v74, v196, v8 quad_perm:[1,1,1,1] row_mask:0xf bank_mask:0xf
	v_fmac_f32_dpp v75, v197, v9 quad_perm:[1,1,1,1] row_mask:0xf bank_mask:0xf
	v_fmac_f32_dpp v80, v198, v10 quad_perm:[1,1,1,1] row_mask:0xf bank_mask:0xf
	v_fmac_f32_dpp v81, v199, v11 quad_perm:[1,1,1,1] row_mask:0xf bank_mask:0xf
	v_fmac_f32_dpp v74, v196, v12 quad_perm:[2,2,2,2] row_mask:0xf bank_mask:0xf
	v_fmac_f32_dpp v75, v197, v13 quad_perm:[2,2,2,2] row_mask:0xf bank_mask:0xf
	v_fmac_f32_dpp v80, v198, v16 quad_perm:[2,2,2,2] row_mask:0xf bank_mask:0xf
	v_fmac_f32_dpp v81, v199, v17 quad_perm:[2,2,2,2] row_mask:0xf bank_mask:0xf
	v_fmac_f32_dpp v74, v196, v20 quad_perm:[3,3,3,3] row_mask:0xf bank_mask:0xf
	v_fmac_f32_dpp v75, v197, v21 quad_perm:[3,3,3,3] row_mask:0xf bank_mask:0xf
	v_fmac_f32_dpp v80, v198, v22 quad_perm:[3,3,3,3] row_mask:0xf bank_mask:0xf
	v_fmac_f32_dpp v81, v199, v23 quad_perm:[3,3,3,3] row_mask:0xf bank_mask:0xf
	v_fmac_f32_dpp v74, v200, v24 quad_perm:[0,0,0,0] row_mask:0xf bank_mask:0xf
	v_fmac_f32_dpp v75, v201, v25 quad_perm:[0,0,0,0] row_mask:0xf bank_mask:0xf
	v_fmac_f32_dpp v80, v202, v26 quad_perm:[0,0,0,0] row_mask:0xf bank_mask:0xf
	v_fmac_f32_dpp v81, v203, v27 quad_perm:[0,0,0,0] row_mask:0xf bank_mask:0xf
	v_fmac_f32_dpp v74, v200, v36 quad_perm:[1,1,1,1] row_mask:0xf bank_mask:0xf
	v_fmac_f32_dpp v75, v201, v37 quad_perm:[1,1,1,1] row_mask:0xf bank_mask:0xf
	v_fmac_f32_dpp v80, v202, v38 quad_perm:[1,1,1,1] row_mask:0xf bank_mask:0xf
; DI void gdn_pre(const Params& p, int ch, char* smem) {
;     ...
;   for (int i = 1; i < 64; ++i) {
;     f32x2 sa = {0.f, 0.f}, sb = {0.f, 0.f};
;     const f32x2* arow = (const f32x2*)(Amat + i * 64);
; #pragma unroll
;     for (int k = 0; k < (i >> 1); ++k) {
;       const f32x2 a2 = arow[k];
;       if (k & 1) sb = __builtin_elementwise_fma(a2, c2[k], sb);
;       else sa = __builtin_elementwise_fma(a2, c2[k], sa);
;     }
;     float tot = (sa[0] + sa[1]) + (sb[0] + sb[1]);
;     if (i & 1) tot += Amat[i * 64 + i - 1] * c2[(i - 1) >> 1][0];
;     c2[i >> 1][i & 1] -= tot;
;     __builtin_amdgcn_sched_barrier(0);
;   }
	v_fmac_f32_dpp v81, v203, v39 quad_perm:[1,1,1,1] row_mask:0xf bank_mask:0xf
	v_fmac_f32_dpp v74, v200, v42 quad_perm:[2,2,2,2] row_mask:0xf bank_mask:0xf
	v_fmac_f32_dpp v75, v201, v43 quad_perm:[2,2,2,2] row_mask:0xf bank_mask:0xf
	v_fmac_f32_dpp v80, v202, v46 quad_perm:[2,2,2,2] row_mask:0xf bank_mask:0xf
	v_fmac_f32_dpp v81, v203, v47 quad_perm:[2,2,2,2] row_mask:0xf bank_mask:0xf
	v_fmac_f32_dpp v74, v200, v50 quad_perm:[3,3,3,3] row_mask:0xf bank_mask:0xf
	v_fmac_f32_dpp v75, v201, v51 quad_perm:[3,3,3,3] row_mask:0xf bank_mask:0xf
	v_fmac_f32_dpp v80, v202, v54 quad_perm:[3,3,3,3] row_mask:0xf bank_mask:0xf
	v_fmac_f32_dpp v81, v203, v55 quad_perm:[3,3,3,3] row_mask:0xf bank_mask:0xf
	v_fmac_f32_dpp v74, v204, v56 quad_perm:[0,0,0,0] row_mask:0xf bank_mask:0xf
	v_fmac_f32_dpp v75, v205, v57 quad_perm:[0,0,0,0] row_mask:0xf bank_mask:0xf
	v_fmac_f32_dpp v80, v206, v60 quad_perm:[0,0,0,0] row_mask:0xf bank_mask:0xf
	v_fmac_f32_dpp v81, v207, v61 quad_perm:[0,0,0,0] row_mask:0xf bank_mask:0xf
	v_fmac_f32_dpp v74, v204, v64 quad_perm:[1,1,1,1] row_mask:0xf bank_mask:0xf
	v_fmac_f32_dpp v75, v205, v65 quad_perm:[1,1,1,1] row_mask:0xf bank_mask:0xf
	v_fmac_f32_dpp v80, v206, v68 quad_perm:[1,1,1,1] row_mask:0xf bank_mask:0xf
	v_fmac_f32_dpp v81, v207, v69 quad_perm:[1,1,1,1] row_mask:0xf bank_mask:0xf
	v_fmac_f32_dpp v74, v204, v70 quad_perm:[2,2,2,2] row_mask:0xf bank_mask:0xf
	v_fmac_f32_dpp v75, v205, v71 quad_perm:[2,2,2,2] row_mask:0xf bank_mask:0xf
	v_mov_b32_e32 v92, v80
	v_mov_b32_e32 v93, v74
	v_mov_b32_e32 v74, v81
	v_pk_add_f32 v[74:75], v[92:93], v[74:75]
	s_nop 0
	v_pk_add_f32 v[74:75], v[74:75], v[74:75] op_sel:[0,1] op_sel_hi:[1,0]
	s_nop 0
	v_pk_add_f32 v[74:75], v[90:91], v[74:75] neg_lo:[0,1] neg_hi:[0,1]
	ds_read_b128 v[196:199], v228 offset:46080
	ds_read_b128 v[200:203], v228 offset:46144
	ds_read_b128 v[204:207], v228 offset:46208
	s_waitcnt lgkmcnt(3)
	v_mul_f32_dpp v80, v212, v0 quad_perm:[0,0,0,0] row_mask:0xf bank_mask:0xf
	v_mul_f32_dpp v81, v213, v1 quad_perm:[0,0,0,0] row_mask:0xf bank_mask:0xf
	v_mul_f32_dpp v90, v214, v6 quad_perm:[0,0,0,0] row_mask:0xf bank_mask:0xf
	v_mul_f32_dpp v91, v215, v7 quad_perm:[0,0,0,0] row_mask:0xf bank_mask:0xf
	v_fmac_f32_dpp v80, v212, v8 quad_perm:[1,1,1,1] row_mask:0xf bank_mask:0xf
	v_fmac_f32_dpp v81, v213, v9 quad_perm:[1,1,1,1] row_mask:0xf bank_mask:0xf
	v_mov_b32_e32 v94, v90
	v_fmac_f32_dpp v94, v214, v10 quad_perm:[1,1,1,1] row_mask:0xf bank_mask:0xf
	v_mov_b32_e32 v95, v91
	v_fmac_f32_dpp v95, v215, v11 quad_perm:[1,1,1,1] row_mask:0xf bank_mask:0xf
	v_fmac_f32_dpp v80, v212, v12 quad_perm:[2,2,2,2] row_mask:0xf bank_mask:0xf
	v_fmac_f32_dpp v81, v213, v13 quad_perm:[2,2,2,2] row_mask:0xf bank_mask:0xf
	v_mov_b32_e32 v98, v94
	v_fmac_f32_dpp v98, v214, v16 quad_perm:[2,2,2,2] row_mask:0xf bank_mask:0xf
	v_mov_b32_e32 v99, v95
	v_fmac_f32_dpp v99, v215, v17 quad_perm:[2,2,2,2] row_mask:0xf bank_mask:0xf
	v_fmac_f32_dpp v80, v212, v20 quad_perm:[3,3,3,3] row_mask:0xf bank_mask:0xf
	v_fmac_f32_dpp v81, v213, v21 quad_perm:[3,3,3,3] row_mask:0xf bank_mask:0xf
	v_mov_b32_e32 v102, v98
	v_fmac_f32_dpp v102, v214, v22 quad_perm:[3,3,3,3] row_mask:0xf bank_mask:0xf
	v_mov_b32_e32 v103, v99
	v_fmac_f32_dpp v103, v215, v23 quad_perm:[3,3,3,3] row_mask:0xf bank_mask:0xf
	v_fmac_f32_dpp v80, v216, v24 quad_perm:[0,0,0,0] row_mask:0xf bank_mask:0xf
	v_fmac_f32_dpp v81, v217, v25 quad_perm:[0,0,0,0] row_mask:0xf bank_mask:0xf
	v_fmac_f32_dpp v102, v218, v26 quad_perm:[0,0,0,0] row_mask:0xf bank_mask:0xf
	v_fmac_f32_dpp v103, v219, v27 quad_perm:[0,0,0,0] row_mask:0xf bank_mask:0xf
	v_fmac_f32_dpp v80, v216, v36 quad_perm:[1,1,1,1] row_mask:0xf bank_mask:0xf
	v_fmac_f32_dpp v81, v217, v37 quad_perm:[1,1,1,1] row_mask:0xf bank_mask:0xf
	v_mov_b32_e32 v94, v102
	v_fmac_f32_dpp v94, v218, v38 quad_perm:[1,1,1,1] row_mask:0xf bank_mask:0xf
	v_mov_b32_e32 v95, v103
	v_fmac_f32_dpp v95, v219, v39 quad_perm:[1,1,1,1] row_mask:0xf bank_mask:0xf
	v_fmac_f32_dpp v80, v216, v42 quad_perm:[2,2,2,2] row_mask:0xf bank_mask:0xf
	v_fmac_f32_dpp v81, v217, v43 quad_perm:[2,2,2,2] row_mask:0xf bank_mask:0xf
	v_mov_b32_e32 v102, v94
	v_fmac_f32_dpp v102, v218, v46 quad_perm:[2,2,2,2] row_mask:0xf bank_mask:0xf
	v_mov_b32_e32 v103, v95
	v_fmac_f32_dpp v103, v219, v47 quad_perm:[2,2,2,2] row_mask:0xf bank_mask:0xf
	v_fmac_f32_dpp v80, v216, v50 quad_perm:[3,3,3,3] row_mask:0xf bank_mask:0xf
	v_fmac_f32_dpp v81, v217, v51 quad_perm:[3,3,3,3] row_mask:0xf bank_mask:0xf
	v_fmac_f32_dpp v102, v218, v54 quad_perm:[3,3,3,3] row_mask:0xf bank_mask:0xf
	v_fmac_f32_dpp v103, v219, v55 quad_perm:[3,3,3,3] row_mask:0xf bank_mask:0xf
	v_fmac_f32_dpp v80, v220, v56 quad_perm:[0,0,0,0] row_mask:0xf bank_mask:0xf
	v_fmac_f32_dpp v81, v221, v57 quad_perm:[0,0,0,0] row_mask:0xf bank_mask:0xf
	v_mov_b32_e32 v94, v102
	v_fmac_f32_dpp v94, v222, v60 quad_perm:[0,0,0,0] row_mask:0xf bank_mask:0xf
	v_mov_b32_e32 v95, v103
	v_fmac_f32_dpp v95, v223, v61 quad_perm:[0,0,0,0] row_mask:0xf bank_mask:0xf
	v_fmac_f32_dpp v80, v220, v64 quad_perm:[1,1,1,1] row_mask:0xf bank_mask:0xf
	v_fmac_f32_dpp v81, v221, v65 quad_perm:[1,1,1,1] row_mask:0xf bank_mask:0xf
	v_fmac_f32_dpp v94, v222, v68 quad_perm:[1,1,1,1] row_mask:0xf bank_mask:0xf
	v_fmac_f32_dpp v95, v223, v69 quad_perm:[1,1,1,1] row_mask:0xf bank_mask:0xf
	v_fmac_f32_dpp v80, v220, v70 quad_perm:[2,2,2,2] row_mask:0xf bank_mask:0xf
	v_fmac_f32_dpp v81, v221, v71 quad_perm:[2,2,2,2] row_mask:0xf bank_mask:0xf
	v_mov_b32_e32 v90, v94
	v_mov_b32_e32 v91, v80
	v_mov_b32_e32 v80, v95
	v_pk_add_f32 v[80:81], v[90:91], v[80:81]
	s_nop 0
	v_add_f32_e32 v19, v80, v81
	v_fmac_f32_dpp v19, v222, v74 quad_perm:[2,2,2,2] row_mask:0xf bank_mask:0xf
	v_sub_f32_e32 v75, v78, v19
	ds_read_b128 v[212:215], v228 offset:46336
	ds_read_b128 v[216:219], v228 offset:46400
	ds_read_b128 v[220:223], v228 offset:46464
	s_waitcnt lgkmcnt(3)
; DI void gdn_pre(const Params& p, int ch, char* smem) {
;     ...
;   for (int i = 1; i < 64; ++i) {
;     f32x2 sa = {0.f, 0.f}, sb = {0.f, 0.f};
;     const f32x2* arow = (const f32x2*)(Amat + i * 64);
; #pragma unroll
;     for (int k = 0; k < (i >> 1); ++k) {
;       const f32x2 a2 = arow[k];
;       if (k & 1) sb = __builtin_elementwise_fma(a2, c2[k], sb);
;       else sa = __builtin_elementwise_fma(a2, c2[k], sa);
;     }
;     float tot = (sa[0] + sa[1]) + (sb[0] + sb[1]);
;     if (i & 1) tot += Amat[i * 64 + i - 1] * c2[(i - 1) >> 1][0];
;     c2[i >> 1][i & 1] -= tot;
;     __builtin_amdgcn_sched_barrier(0);
;   }
	v_mul_f32_dpp v78, v196, v0 quad_perm:[0,0,0,0] row_mask:0xf bank_mask:0xf
	v_mul_f32_dpp v79, v197, v1 quad_perm:[0,0,0,0] row_mask:0xf bank_mask:0xf
	v_mul_f32_dpp v80, v198, v6 quad_perm:[0,0,0,0] row_mask:0xf bank_mask:0xf
	v_mul_f32_dpp v81, v199, v7 quad_perm:[0,0,0,0] row_mask:0xf bank_mask:0xf
	v_fmac_f32_dpp v78, v196, v8 quad_perm:[1,1,1,1] row_mask:0xf bank_mask:0xf
	v_fmac_f32_dpp v79, v197, v9 quad_perm:[1,1,1,1] row_mask:0xf bank_mask:0xf
	v_mov_b32_e32 v90, v80
	v_fmac_f32_dpp v90, v198, v10 quad_perm:[1,1,1,1] row_mask:0xf bank_mask:0xf
	v_mov_b32_e32 v91, v81
	v_fmac_f32_dpp v91, v199, v11 quad_perm:[1,1,1,1] row_mask:0xf bank_mask:0xf
	v_mov_b32_e32 v92, v78
	v_fmac_f32_dpp v92, v196, v12 quad_perm:[2,2,2,2] row_mask:0xf bank_mask:0xf
	v_mov_b32_e32 v93, v79
	v_fmac_f32_dpp v93, v197, v13 quad_perm:[2,2,2,2] row_mask:0xf bank_mask:0xf
	v_mov_b32_e32 v94, v90
	v_fmac_f32_dpp v94, v198, v16 quad_perm:[2,2,2,2] row_mask:0xf bank_mask:0xf
	v_mov_b32_e32 v95, v91
	v_fmac_f32_dpp v95, v199, v17 quad_perm:[2,2,2,2] row_mask:0xf bank_mask:0xf
	v_mov_b32_e32 v96, v92
	v_fmac_f32_dpp v96, v196, v20 quad_perm:[3,3,3,3] row_mask:0xf bank_mask:0xf
	v_mov_b32_e32 v97, v93
	v_fmac_f32_dpp v97, v197, v21 quad_perm:[3,3,3,3] row_mask:0xf bank_mask:0xf
	v_mov_b32_e32 v98, v94
	v_fmac_f32_dpp v98, v198, v22 quad_perm:[3,3,3,3] row_mask:0xf bank_mask:0xf
	v_mov_b32_e32 v99, v95
	v_fmac_f32_dpp v99, v199, v23 quad_perm:[3,3,3,3] row_mask:0xf bank_mask:0xf
	v_mov_b32_e32 v78, v96
	v_fmac_f32_dpp v78, v200, v24 quad_perm:[0,0,0,0] row_mask:0xf bank_mask:0xf
	v_mov_b32_e32 v79, v97
	v_fmac_f32_dpp v79, v201, v25 quad_perm:[0,0,0,0] row_mask:0xf bank_mask:0xf
	v_fmac_f32_dpp v98, v202, v26 quad_perm:[0,0,0,0] row_mask:0xf bank_mask:0xf
	v_fmac_f32_dpp v99, v203, v27 quad_perm:[0,0,0,0] row_mask:0xf bank_mask:0xf
	v_mov_b32_e32 v90, v78
	v_fmac_f32_dpp v90, v200, v36 quad_perm:[1,1,1,1] row_mask:0xf bank_mask:0xf
	v_mov_b32_e32 v91, v79
	v_fmac_f32_dpp v91, v201, v37 quad_perm:[1,1,1,1] row_mask:0xf bank_mask:0xf
	v_mov_b32_e32 v92, v98
	v_fmac_f32_dpp v92, v202, v38 quad_perm:[1,1,1,1] row_mask:0xf bank_mask:0xf
	v_mov_b32_e32 v93, v99
	v_fmac_f32_dpp v93, v203, v39 quad_perm:[1,1,1,1] row_mask:0xf bank_mask:0xf
	v_mov_b32_e32 v94, v90
	v_fmac_f32_dpp v94, v200, v42 quad_perm:[2,2,2,2] row_mask:0xf bank_mask:0xf
	v_mov_b32_e32 v95, v91
	v_fmac_f32_dpp v95, v201, v43 quad_perm:[2,2,2,2] row_mask:0xf bank_mask:0xf
	v_mov_b32_e32 v98, v92
	v_fmac_f32_dpp v98, v202, v46 quad_perm:[2,2,2,2] row_mask:0xf bank_mask:0xf
	v_mov_b32_e32 v99, v93
	v_fmac_f32_dpp v99, v203, v47 quad_perm:[2,2,2,2] row_mask:0xf bank_mask:0xf
	v_mov_b32_e32 v100, v94
	v_fmac_f32_dpp v100, v200, v50 quad_perm:[3,3,3,3] row_mask:0xf bank_mask:0xf
	v_mov_b32_e32 v101, v95
	v_fmac_f32_dpp v101, v201, v51 quad_perm:[3,3,3,3] row_mask:0xf bank_mask:0xf
	v_fmac_f32_dpp v98, v202, v54 quad_perm:[3,3,3,3] row_mask:0xf bank_mask:0xf
	v_fmac_f32_dpp v99, v203, v55 quad_perm:[3,3,3,3] row_mask:0xf bank_mask:0xf
	v_mov_b32_e32 v90, v100
	v_fmac_f32_dpp v90, v204, v56 quad_perm:[0,0,0,0] row_mask:0xf bank_mask:0xf
	v_mov_b32_e32 v91, v101
	v_fmac_f32_dpp v91, v205, v57 quad_perm:[0,0,0,0] row_mask:0xf bank_mask:0xf
	v_mov_b32_e32 v92, v98
	v_fmac_f32_dpp v92, v206, v60 quad_perm:[0,0,0,0] row_mask:0xf bank_mask:0xf
	v_mov_b32_e32 v93, v99
	v_fmac_f32_dpp v93, v207, v61 quad_perm:[0,0,0,0] row_mask:0xf bank_mask:0xf
	v_fmac_f32_dpp v90, v204, v64 quad_perm:[1,1,1,1] row_mask:0xf bank_mask:0xf
	v_fmac_f32_dpp v91, v205, v65 quad_perm:[1,1,1,1] row_mask:0xf bank_mask:0xf
	v_fmac_f32_dpp v92, v206, v68 quad_perm:[1,1,1,1] row_mask:0xf bank_mask:0xf
	v_fmac_f32_dpp v93, v207, v69 quad_perm:[1,1,1,1] row_mask:0xf bank_mask:0xf
	v_mov_b32_e32 v78, v90
	v_fmac_f32_dpp v78, v204, v70 quad_perm:[2,2,2,2] row_mask:0xf bank_mask:0xf
	v_mov_b32_e32 v79, v91
	v_fmac_f32_dpp v79, v205, v71 quad_perm:[2,2,2,2] row_mask:0xf bank_mask:0xf
	v_mov_b32_e32 v80, v92
	v_fmac_f32_dpp v80, v206, v74 quad_perm:[2,2,2,2] row_mask:0xf bank_mask:0xf
	v_mov_b32_e32 v81, v93
	v_fmac_f32_dpp v81, v207, v75 quad_perm:[2,2,2,2] row_mask:0xf bank_mask:0xf
	v_mov_b32_e32 v90, v78
	v_mov_b32_e32 v91, v80
	v_mov_b32_e32 v80, v79
	v_pk_add_f32 v[78:79], v[90:91], v[80:81]
	s_nop 0
	v_pk_add_f32 v[78:79], v[78:79], v[78:79] op_sel:[0,1] op_sel_hi:[1,0]
	s_nop 0
	v_pk_add_f32 v[78:79], v[88:89], v[78:79] neg_lo:[0,1] neg_hi:[0,1]
	ds_read_b128 v[196:199], v228 offset:46592
	ds_read_b128 v[200:203], v228 offset:46656
	ds_read_b128 v[204:207], v228 offset:46720
	s_waitcnt lgkmcnt(3)
; DI void gdn_pre(const Params& p, int ch, char* smem) {
;     ...
;   for (int i = 1; i < 64; ++i) {
;     f32x2 sa = {0.f, 0.f}, sb = {0.f, 0.f};
;     const f32x2* arow = (const f32x2*)(Amat + i * 64);
; #pragma unroll
;     for (int k = 0; k < (i >> 1); ++k) {
;       const f32x2 a2 = arow[k];
;       if (k & 1) sb = __builtin_elementwise_fma(a2, c2[k], sb);
;       else sa = __builtin_elementwise_fma(a2, c2[k], sa);
;     }
;     float tot = (sa[0] + sa[1]) + (sb[0] + sb[1]);
;     if (i & 1) tot += Amat[i * 64 + i - 1] * c2[(i - 1) >> 1][0];
;     c2[i >> 1][i & 1] -= tot;
;     __builtin_amdgcn_sched_barrier(0);
;   }
	v_mul_f32_dpp v80, v212, v0 quad_perm:[0,0,0,0] row_mask:0xf bank_mask:0xf
	v_mul_f32_dpp v81, v213, v1 quad_perm:[0,0,0,0] row_mask:0xf bank_mask:0xf
	v_mul_f32_dpp v88, v214, v6 quad_perm:[0,0,0,0] row_mask:0xf bank_mask:0xf
	v_mul_f32_dpp v89, v215, v7 quad_perm:[0,0,0,0] row_mask:0xf bank_mask:0xf
	v_fmac_f32_dpp v80, v212, v8 quad_perm:[1,1,1,1] row_mask:0xf bank_mask:0xf
	v_fmac_f32_dpp v81, v213, v9 quad_perm:[1,1,1,1] row_mask:0xf bank_mask:0xf
	v_mov_b32_e32 v92, v88
	v_fmac_f32_dpp v92, v214, v10 quad_perm:[1,1,1,1] row_mask:0xf bank_mask:0xf
	v_mov_b32_e32 v93, v89
	v_fmac_f32_dpp v93, v215, v11 quad_perm:[1,1,1,1] row_mask:0xf bank_mask:0xf
	v_fmac_f32_dpp v80, v212, v12 quad_perm:[2,2,2,2] row_mask:0xf bank_mask:0xf
	v_fmac_f32_dpp v81, v213, v13 quad_perm:[2,2,2,2] row_mask:0xf bank_mask:0xf
	v_mov_b32_e32 v96, v92
	v_fmac_f32_dpp v96, v214, v16 quad_perm:[2,2,2,2] row_mask:0xf bank_mask:0xf
	v_mov_b32_e32 v97, v93
	v_fmac_f32_dpp v97, v215, v17 quad_perm:[2,2,2,2] row_mask:0xf bank_mask:0xf
	v_fmac_f32_dpp v80, v212, v20 quad_perm:[3,3,3,3] row_mask:0xf bank_mask:0xf
	v_fmac_f32_dpp v81, v213, v21 quad_perm:[3,3,3,3] row_mask:0xf bank_mask:0xf
	v_mov_b32_e32 v100, v96
	v_fmac_f32_dpp v100, v214, v22 quad_perm:[3,3,3,3] row_mask:0xf bank_mask:0xf
	v_mov_b32_e32 v101, v97
	v_fmac_f32_dpp v101, v215, v23 quad_perm:[3,3,3,3] row_mask:0xf bank_mask:0xf
	v_fmac_f32_dpp v80, v216, v24 quad_perm:[0,0,0,0] row_mask:0xf bank_mask:0xf
	v_fmac_f32_dpp v81, v217, v25 quad_perm:[0,0,0,0] row_mask:0xf bank_mask:0xf
	v_fmac_f32_dpp v100, v218, v26 quad_perm:[0,0,0,0] row_mask:0xf bank_mask:0xf
	v_fmac_f32_dpp v101, v219, v27 quad_perm:[0,0,0,0] row_mask:0xf bank_mask:0xf
	v_fmac_f32_dpp v80, v216, v36 quad_perm:[1,1,1,1] row_mask:0xf bank_mask:0xf
	v_fmac_f32_dpp v81, v217, v37 quad_perm:[1,1,1,1] row_mask:0xf bank_mask:0xf
	v_fmac_f32_dpp v100, v218, v38 quad_perm:[1,1,1,1] row_mask:0xf bank_mask:0xf
	v_fmac_f32_dpp v101, v219, v39 quad_perm:[1,1,1,1] row_mask:0xf bank_mask:0xf
	v_fmac_f32_dpp v80, v216, v42 quad_perm:[2,2,2,2] row_mask:0xf bank_mask:0xf
	v_fmac_f32_dpp v81, v217, v43 quad_perm:[2,2,2,2] row_mask:0xf bank_mask:0xf
	v_fmac_f32_dpp v100, v218, v46 quad_perm:[2,2,2,2] row_mask:0xf bank_mask:0xf
	v_fmac_f32_dpp v101, v219, v47 quad_perm:[2,2,2,2] row_mask:0xf bank_mask:0xf
	v_fmac_f32_dpp v80, v216, v50 quad_perm:[3,3,3,3] row_mask:0xf bank_mask:0xf
	v_fmac_f32_dpp v81, v217, v51 quad_perm:[3,3,3,3] row_mask:0xf bank_mask:0xf
	v_fmac_f32_dpp v100, v218, v54 quad_perm:[3,3,3,3] row_mask:0xf bank_mask:0xf
	v_fmac_f32_dpp v101, v219, v55 quad_perm:[3,3,3,3] row_mask:0xf bank_mask:0xf
	v_fmac_f32_dpp v80, v220, v56 quad_perm:[0,0,0,0] row_mask:0xf bank_mask:0xf
	v_fmac_f32_dpp v81, v221, v57 quad_perm:[0,0,0,0] row_mask:0xf bank_mask:0xf
	v_mov_b32_e32 v92, v100
	v_fmac_f32_dpp v92, v222, v60 quad_perm:[0,0,0,0] row_mask:0xf bank_mask:0xf
	v_mov_b32_e32 v93, v101
	v_fmac_f32_dpp v93, v223, v61 quad_perm:[0,0,0,0] row_mask:0xf bank_mask:0xf
	v_fmac_f32_dpp v80, v220, v64 quad_perm:[1,1,1,1] row_mask:0xf bank_mask:0xf
	v_fmac_f32_dpp v81, v221, v65 quad_perm:[1,1,1,1] row_mask:0xf bank_mask:0xf
	v_fmac_f32_dpp v92, v222, v68 quad_perm:[1,1,1,1] row_mask:0xf bank_mask:0xf
	v_fmac_f32_dpp v93, v223, v69 quad_perm:[1,1,1,1] row_mask:0xf bank_mask:0xf
	v_fmac_f32_dpp v80, v220, v70 quad_perm:[2,2,2,2] row_mask:0xf bank_mask:0xf
	v_fmac_f32_dpp v81, v221, v71 quad_perm:[2,2,2,2] row_mask:0xf bank_mask:0xf
	v_mov_b32_e32 v88, v92
	v_fmac_f32_dpp v88, v222, v74 quad_perm:[2,2,2,2] row_mask:0xf bank_mask:0xf
	v_mov_b32_e32 v89, v93
	v_fmac_f32_dpp v89, v223, v75 quad_perm:[2,2,2,2] row_mask:0xf bank_mask:0xf
	v_mov_b32_e32 v90, v80
	v_mov_b32_e32 v91, v88
	v_mov_b32_e32 v88, v81
	v_pk_add_f32 v[80:81], v[90:91], v[88:89]
	s_nop 0
	v_add_f32_e32 v31, v80, v81
	v_fmac_f32_dpp v31, v220, v78 quad_perm:[3,3,3,3] row_mask:0xf bank_mask:0xf
	v_sub_f32_e32 v79, v76, v31
	ds_read_b128 v[212:215], v228 offset:46848
	ds_read_b128 v[216:219], v228 offset:46912
	ds_read_b128 v[220:223], v228 offset:46976
	s_waitcnt lgkmcnt(3)
	v_mul_f32_dpp v76, v196, v0 quad_perm:[0,0,0,0] row_mask:0xf bank_mask:0xf
	v_mul_f32_dpp v77, v197, v1 quad_perm:[0,0,0,0] row_mask:0xf bank_mask:0xf
	v_mul_f32_dpp v80, v198, v6 quad_perm:[0,0,0,0] row_mask:0xf bank_mask:0xf
	v_mul_f32_dpp v81, v199, v7 quad_perm:[0,0,0,0] row_mask:0xf bank_mask:0xf
	v_fmac_f32_dpp v76, v196, v8 quad_perm:[1,1,1,1] row_mask:0xf bank_mask:0xf
	v_fmac_f32_dpp v77, v197, v9 quad_perm:[1,1,1,1] row_mask:0xf bank_mask:0xf
	v_fmac_f32_dpp v80, v198, v10 quad_perm:[1,1,1,1] row_mask:0xf bank_mask:0xf
	v_fmac_f32_dpp v81, v199, v11 quad_perm:[1,1,1,1] row_mask:0xf bank_mask:0xf
	v_fmac_f32_dpp v76, v196, v12 quad_perm:[2,2,2,2] row_mask:0xf bank_mask:0xf
	v_fmac_f32_dpp v77, v197, v13 quad_perm:[2,2,2,2] row_mask:0xf bank_mask:0xf
	v_fmac_f32_dpp v80, v198, v16 quad_perm:[2,2,2,2] row_mask:0xf bank_mask:0xf
	v_fmac_f32_dpp v81, v199, v17 quad_perm:[2,2,2,2] row_mask:0xf bank_mask:0xf
	v_fmac_f32_dpp v76, v196, v20 quad_perm:[3,3,3,3] row_mask:0xf bank_mask:0xf
	v_fmac_f32_dpp v77, v197, v21 quad_perm:[3,3,3,3] row_mask:0xf bank_mask:0xf
	v_fmac_f32_dpp v80, v198, v22 quad_perm:[3,3,3,3] row_mask:0xf bank_mask:0xf
	v_fmac_f32_dpp v81, v199, v23 quad_perm:[3,3,3,3] row_mask:0xf bank_mask:0xf
	v_fmac_f32_dpp v76, v200, v24 quad_perm:[0,0,0,0] row_mask:0xf bank_mask:0xf
	v_fmac_f32_dpp v77, v201, v25 quad_perm:[0,0,0,0] row_mask:0xf bank_mask:0xf
	v_fmac_f32_dpp v80, v202, v26 quad_perm:[0,0,0,0] row_mask:0xf bank_mask:0xf
	v_fmac_f32_dpp v81, v203, v27 quad_perm:[0,0,0,0] row_mask:0xf bank_mask:0xf
; DI void gdn_pre(const Params& p, int ch, char* smem) {
;     ...
;   for (int i = 1; i < 64; ++i) {
;     f32x2 sa = {0.f, 0.f}, sb = {0.f, 0.f};
;     const f32x2* arow = (const f32x2*)(Amat + i * 64);
; #pragma unroll
;     for (int k = 0; k < (i >> 1); ++k) {
;       const f32x2 a2 = arow[k];
;       if (k & 1) sb = __builtin_elementwise_fma(a2, c2[k], sb);
;       else sa = __builtin_elementwise_fma(a2, c2[k], sa);
;     }
;     float tot = (sa[0] + sa[1]) + (sb[0] + sb[1]);
;     if (i & 1) tot += Amat[i * 64 + i - 1] * c2[(i - 1) >> 1][0];
;     c2[i >> 1][i & 1] -= tot;
;     __builtin_amdgcn_sched_barrier(0);
;   }
	v_fmac_f32_dpp v76, v200, v36 quad_perm:[1,1,1,1] row_mask:0xf bank_mask:0xf
	v_fmac_f32_dpp v77, v201, v37 quad_perm:[1,1,1,1] row_mask:0xf bank_mask:0xf
	v_fmac_f32_dpp v80, v202, v38 quad_perm:[1,1,1,1] row_mask:0xf bank_mask:0xf
	v_fmac_f32_dpp v81, v203, v39 quad_perm:[1,1,1,1] row_mask:0xf bank_mask:0xf
	v_fmac_f32_dpp v76, v200, v42 quad_perm:[2,2,2,2] row_mask:0xf bank_mask:0xf
	v_fmac_f32_dpp v77, v201, v43 quad_perm:[2,2,2,2] row_mask:0xf bank_mask:0xf
	v_fmac_f32_dpp v80, v202, v46 quad_perm:[2,2,2,2] row_mask:0xf bank_mask:0xf
	v_fmac_f32_dpp v81, v203, v47 quad_perm:[2,2,2,2] row_mask:0xf bank_mask:0xf
	v_fmac_f32_dpp v76, v200, v50 quad_perm:[3,3,3,3] row_mask:0xf bank_mask:0xf
	v_fmac_f32_dpp v77, v201, v51 quad_perm:[3,3,3,3] row_mask:0xf bank_mask:0xf
	v_fmac_f32_dpp v80, v202, v54 quad_perm:[3,3,3,3] row_mask:0xf bank_mask:0xf
	v_fmac_f32_dpp v81, v203, v55 quad_perm:[3,3,3,3] row_mask:0xf bank_mask:0xf
	v_fmac_f32_dpp v76, v204, v56 quad_perm:[0,0,0,0] row_mask:0xf bank_mask:0xf
	v_fmac_f32_dpp v77, v205, v57 quad_perm:[0,0,0,0] row_mask:0xf bank_mask:0xf
	v_fmac_f32_dpp v80, v206, v60 quad_perm:[0,0,0,0] row_mask:0xf bank_mask:0xf
	v_fmac_f32_dpp v81, v207, v61 quad_perm:[0,0,0,0] row_mask:0xf bank_mask:0xf
	v_fmac_f32_dpp v76, v204, v64 quad_perm:[1,1,1,1] row_mask:0xf bank_mask:0xf
	v_fmac_f32_dpp v77, v205, v65 quad_perm:[1,1,1,1] row_mask:0xf bank_mask:0xf
	v_fmac_f32_dpp v80, v206, v68 quad_perm:[1,1,1,1] row_mask:0xf bank_mask:0xf
	v_fmac_f32_dpp v81, v207, v69 quad_perm:[1,1,1,1] row_mask:0xf bank_mask:0xf
	v_fmac_f32_dpp v76, v204, v70 quad_perm:[2,2,2,2] row_mask:0xf bank_mask:0xf
	v_fmac_f32_dpp v77, v205, v71 quad_perm:[2,2,2,2] row_mask:0xf bank_mask:0xf
	v_fmac_f32_dpp v80, v206, v74 quad_perm:[2,2,2,2] row_mask:0xf bank_mask:0xf
	v_fmac_f32_dpp v81, v207, v75 quad_perm:[2,2,2,2] row_mask:0xf bank_mask:0xf
	v_fmac_f32_dpp v76, v204, v78 quad_perm:[3,3,3,3] row_mask:0xf bank_mask:0xf
	v_fmac_f32_dpp v77, v205, v79 quad_perm:[3,3,3,3] row_mask:0xf bank_mask:0xf
	v_mov_b32_e32 v88, v80
	v_mov_b32_e32 v89, v76
	v_mov_b32_e32 v76, v81
	v_pk_add_f32 v[76:77], v[88:89], v[76:77]
	s_nop 0
	v_pk_add_f32 v[76:77], v[76:77], v[76:77] op_sel:[0,1] op_sel_hi:[1,0]
	s_nop 0
	v_pk_add_f32 v[76:77], v[86:87], v[76:77] neg_lo:[0,1] neg_hi:[0,1]
	ds_read_b128 v[196:199], v228 offset:47104
	ds_read_b128 v[200:203], v228 offset:47168
	ds_read_b128 v[204:207], v228 offset:47232
	s_waitcnt lgkmcnt(3)
	v_mul_f32_dpp v80, v212, v0 quad_perm:[0,0,0,0] row_mask:0xf bank_mask:0xf
	v_mul_f32_dpp v81, v213, v1 quad_perm:[0,0,0,0] row_mask:0xf bank_mask:0xf
	v_mul_f32_dpp v86, v214, v6 quad_perm:[0,0,0,0] row_mask:0xf bank_mask:0xf
	v_mul_f32_dpp v87, v215, v7 quad_perm:[0,0,0,0] row_mask:0xf bank_mask:0xf
	v_fmac_f32_dpp v80, v212, v8 quad_perm:[1,1,1,1] row_mask:0xf bank_mask:0xf
	v_fmac_f32_dpp v81, v213, v9 quad_perm:[1,1,1,1] row_mask:0xf bank_mask:0xf
	v_mov_b32_e32 v90, v86
	v_fmac_f32_dpp v90, v214, v10 quad_perm:[1,1,1,1] row_mask:0xf bank_mask:0xf
	v_mov_b32_e32 v91, v87
	v_fmac_f32_dpp v91, v215, v11 quad_perm:[1,1,1,1] row_mask:0xf bank_mask:0xf
	v_fmac_f32_dpp v80, v212, v12 quad_perm:[2,2,2,2] row_mask:0xf bank_mask:0xf
	v_fmac_f32_dpp v81, v213, v13 quad_perm:[2,2,2,2] row_mask:0xf bank_mask:0xf
	v_mov_b32_e32 v94, v90
	v_fmac_f32_dpp v94, v214, v16 quad_perm:[2,2,2,2] row_mask:0xf bank_mask:0xf
	v_mov_b32_e32 v95, v91
	v_fmac_f32_dpp v95, v215, v17 quad_perm:[2,2,2,2] row_mask:0xf bank_mask:0xf
	v_fmac_f32_dpp v80, v212, v20 quad_perm:[3,3,3,3] row_mask:0xf bank_mask:0xf
	v_fmac_f32_dpp v81, v213, v21 quad_perm:[3,3,3,3] row_mask:0xf bank_mask:0xf
	v_mov_b32_e32 v98, v94
	v_fmac_f32_dpp v98, v214, v22 quad_perm:[3,3,3,3] row_mask:0xf bank_mask:0xf
	v_mov_b32_e32 v99, v95
	v_fmac_f32_dpp v99, v215, v23 quad_perm:[3,3,3,3] row_mask:0xf bank_mask:0xf
	v_fmac_f32_dpp v80, v216, v24 quad_perm:[0,0,0,0] row_mask:0xf bank_mask:0xf
	v_fmac_f32_dpp v81, v217, v25 quad_perm:[0,0,0,0] row_mask:0xf bank_mask:0xf
	v_fmac_f32_dpp v98, v218, v26 quad_perm:[0,0,0,0] row_mask:0xf bank_mask:0xf
	v_fmac_f32_dpp v99, v219, v27 quad_perm:[0,0,0,0] row_mask:0xf bank_mask:0xf
	v_fmac_f32_dpp v80, v216, v36 quad_perm:[1,1,1,1] row_mask:0xf bank_mask:0xf
	v_fmac_f32_dpp v81, v217, v37 quad_perm:[1,1,1,1] row_mask:0xf bank_mask:0xf
	v_fmac_f32_dpp v98, v218, v38 quad_perm:[1,1,1,1] row_mask:0xf bank_mask:0xf
	v_fmac_f32_dpp v99, v219, v39 quad_perm:[1,1,1,1] row_mask:0xf bank_mask:0xf
	v_fmac_f32_dpp v80, v216, v42 quad_perm:[2,2,2,2] row_mask:0xf bank_mask:0xf
	v_fmac_f32_dpp v81, v217, v43 quad_perm:[2,2,2,2] row_mask:0xf bank_mask:0xf
	v_mov_b32_e32 v94, v98
	v_fmac_f32_dpp v94, v218, v46 quad_perm:[2,2,2,2] row_mask:0xf bank_mask:0xf
	v_mov_b32_e32 v95, v99
	v_fmac_f32_dpp v95, v219, v47 quad_perm:[2,2,2,2] row_mask:0xf bank_mask:0xf
	v_fmac_f32_dpp v80, v216, v50 quad_perm:[3,3,3,3] row_mask:0xf bank_mask:0xf
	v_fmac_f32_dpp v81, v217, v51 quad_perm:[3,3,3,3] row_mask:0xf bank_mask:0xf
	v_mov_b32_e32 v98, v94
	v_fmac_f32_dpp v98, v218, v54 quad_perm:[3,3,3,3] row_mask:0xf bank_mask:0xf
	v_mov_b32_e32 v99, v95
	v_fmac_f32_dpp v99, v219, v55 quad_perm:[3,3,3,3] row_mask:0xf bank_mask:0xf
	v_fmac_f32_dpp v80, v220, v56 quad_perm:[0,0,0,0] row_mask:0xf bank_mask:0xf
	v_fmac_f32_dpp v81, v221, v57 quad_perm:[0,0,0,0] row_mask:0xf bank_mask:0xf
	v_fmac_f32_dpp v98, v222, v60 quad_perm:[0,0,0,0] row_mask:0xf bank_mask:0xf
	v_fmac_f32_dpp v99, v223, v61 quad_perm:[0,0,0,0] row_mask:0xf bank_mask:0xf
	v_fmac_f32_dpp v80, v220, v64 quad_perm:[1,1,1,1] row_mask:0xf bank_mask:0xf
	v_fmac_f32_dpp v81, v221, v65 quad_perm:[1,1,1,1] row_mask:0xf bank_mask:0xf
	v_mov_b32_e32 v86, v98
	v_fmac_f32_dpp v86, v222, v68 quad_perm:[1,1,1,1] row_mask:0xf bank_mask:0xf
	v_mov_b32_e32 v87, v99
	v_fmac_f32_dpp v87, v223, v69 quad_perm:[1,1,1,1] row_mask:0xf bank_mask:0xf
	v_fmac_f32_dpp v80, v220, v70 quad_perm:[2,2,2,2] row_mask:0xf bank_mask:0xf
	v_fmac_f32_dpp v81, v221, v71 quad_perm:[2,2,2,2] row_mask:0xf bank_mask:0xf
	v_fmac_f32_dpp v86, v222, v74 quad_perm:[2,2,2,2] row_mask:0xf bank_mask:0xf
	v_fmac_f32_dpp v87, v223, v75 quad_perm:[2,2,2,2] row_mask:0xf bank_mask:0xf
	v_fmac_f32_dpp v80, v220, v78 quad_perm:[3,3,3,3] row_mask:0xf bank_mask:0xf
	v_fmac_f32_dpp v81, v221, v79 quad_perm:[3,3,3,3] row_mask:0xf bank_mask:0xf
	v_mov_b32_e32 v88, v86
	v_mov_b32_e32 v89, v80
	v_mov_b32_e32 v80, v87
	v_pk_add_f32 v[80:81], v[88:89], v[80:81]
	s_nop 0
	v_add_f32_e32 v19, v80, v81
	v_fmac_f32_dpp v19, v222, v76 quad_perm:[3,3,3,3] row_mask:0xf bank_mask:0xf
	v_sub_f32_e32 v77, v72, v19
	ds_read_b128 v[212:215], v228 offset:47360
	ds_read_b128 v[216:219], v228 offset:47424
	ds_read_b128 v[220:223], v228 offset:47488
	ds_read_b128 v[224:227], v228 offset:47552
	s_waitcnt lgkmcnt(4)
; DI void gdn_pre(const Params& p, int ch, char* smem) {
;     ...
;   for (int i = 1; i < 64; ++i) {
;     f32x2 sa = {0.f, 0.f}, sb = {0.f, 0.f};
;     const f32x2* arow = (const f32x2*)(Amat + i * 64);
; #pragma unroll
;     for (int k = 0; k < (i >> 1); ++k) {
;       const f32x2 a2 = arow[k];
;       if (k & 1) sb = __builtin_elementwise_fma(a2, c2[k], sb);
;       else sa = __builtin_elementwise_fma(a2, c2[k], sa);
;     }
;     float tot = (sa[0] + sa[1]) + (sb[0] + sb[1]);
;     if (i & 1) tot += Amat[i * 64 + i - 1] * c2[(i - 1) >> 1][0];
;     c2[i >> 1][i & 1] -= tot;
;     __builtin_amdgcn_sched_barrier(0);
;   }
	v_mul_f32_dpp v72, v196, v0 quad_perm:[0,0,0,0] row_mask:0xf bank_mask:0xf
	v_mul_f32_dpp v73, v197, v1 quad_perm:[0,0,0,0] row_mask:0xf bank_mask:0xf
	v_mul_f32_dpp v80, v198, v6 quad_perm:[0,0,0,0] row_mask:0xf bank_mask:0xf
	v_mul_f32_dpp v81, v199, v7 quad_perm:[0,0,0,0] row_mask:0xf bank_mask:0xf
	v_fmac_f32_dpp v72, v196, v8 quad_perm:[1,1,1,1] row_mask:0xf bank_mask:0xf
	v_fmac_f32_dpp v73, v197, v9 quad_perm:[1,1,1,1] row_mask:0xf bank_mask:0xf
	v_fmac_f32_dpp v80, v198, v10 quad_perm:[1,1,1,1] row_mask:0xf bank_mask:0xf
	v_fmac_f32_dpp v81, v199, v11 quad_perm:[1,1,1,1] row_mask:0xf bank_mask:0xf
	v_fmac_f32_dpp v72, v196, v12 quad_perm:[2,2,2,2] row_mask:0xf bank_mask:0xf
	v_fmac_f32_dpp v73, v197, v13 quad_perm:[2,2,2,2] row_mask:0xf bank_mask:0xf
	v_fmac_f32_dpp v80, v198, v16 quad_perm:[2,2,2,2] row_mask:0xf bank_mask:0xf
	v_fmac_f32_dpp v81, v199, v17 quad_perm:[2,2,2,2] row_mask:0xf bank_mask:0xf
	v_fmac_f32_dpp v72, v196, v20 quad_perm:[3,3,3,3] row_mask:0xf bank_mask:0xf
	v_fmac_f32_dpp v73, v197, v21 quad_perm:[3,3,3,3] row_mask:0xf bank_mask:0xf
	v_fmac_f32_dpp v80, v198, v22 quad_perm:[3,3,3,3] row_mask:0xf bank_mask:0xf
	v_fmac_f32_dpp v81, v199, v23 quad_perm:[3,3,3,3] row_mask:0xf bank_mask:0xf
	v_fmac_f32_dpp v72, v200, v24 quad_perm:[0,0,0,0] row_mask:0xf bank_mask:0xf
	v_fmac_f32_dpp v73, v201, v25 quad_perm:[0,0,0,0] row_mask:0xf bank_mask:0xf
	v_fmac_f32_dpp v80, v202, v26 quad_perm:[0,0,0,0] row_mask:0xf bank_mask:0xf
	v_fmac_f32_dpp v81, v203, v27 quad_perm:[0,0,0,0] row_mask:0xf bank_mask:0xf
	v_fmac_f32_dpp v72, v200, v36 quad_perm:[1,1,1,1] row_mask:0xf bank_mask:0xf
	v_fmac_f32_dpp v73, v201, v37 quad_perm:[1,1,1,1] row_mask:0xf bank_mask:0xf
	v_fmac_f32_dpp v80, v202, v38 quad_perm:[1,1,1,1] row_mask:0xf bank_mask:0xf
	v_fmac_f32_dpp v81, v203, v39 quad_perm:[1,1,1,1] row_mask:0xf bank_mask:0xf
	v_fmac_f32_dpp v72, v200, v42 quad_perm:[2,2,2,2] row_mask:0xf bank_mask:0xf
	v_fmac_f32_dpp v73, v201, v43 quad_perm:[2,2,2,2] row_mask:0xf bank_mask:0xf
	v_fmac_f32_dpp v80, v202, v46 quad_perm:[2,2,2,2] row_mask:0xf bank_mask:0xf
	v_fmac_f32_dpp v81, v203, v47 quad_perm:[2,2,2,2] row_mask:0xf bank_mask:0xf
	v_fmac_f32_dpp v72, v200, v50 quad_perm:[3,3,3,3] row_mask:0xf bank_mask:0xf
	v_fmac_f32_dpp v73, v201, v51 quad_perm:[3,3,3,3] row_mask:0xf bank_mask:0xf
	v_fmac_f32_dpp v80, v202, v54 quad_perm:[3,3,3,3] row_mask:0xf bank_mask:0xf
	v_fmac_f32_dpp v81, v203, v55 quad_perm:[3,3,3,3] row_mask:0xf bank_mask:0xf
	v_fmac_f32_dpp v72, v204, v56 quad_perm:[0,0,0,0] row_mask:0xf bank_mask:0xf
	v_fmac_f32_dpp v73, v205, v57 quad_perm:[0,0,0,0] row_mask:0xf bank_mask:0xf
	v_fmac_f32_dpp v80, v206, v60 quad_perm:[0,0,0,0] row_mask:0xf bank_mask:0xf
	v_fmac_f32_dpp v81, v207, v61 quad_perm:[0,0,0,0] row_mask:0xf bank_mask:0xf
	v_fmac_f32_dpp v72, v204, v64 quad_perm:[1,1,1,1] row_mask:0xf bank_mask:0xf
	v_fmac_f32_dpp v73, v205, v65 quad_perm:[1,1,1,1] row_mask:0xf bank_mask:0xf
	v_fmac_f32_dpp v80, v206, v68 quad_perm:[1,1,1,1] row_mask:0xf bank_mask:0xf
	v_fmac_f32_dpp v81, v207, v69 quad_perm:[1,1,1,1] row_mask:0xf bank_mask:0xf
	v_fmac_f32_dpp v72, v204, v70 quad_perm:[2,2,2,2] row_mask:0xf bank_mask:0xf
	v_fmac_f32_dpp v73, v205, v71 quad_perm:[2,2,2,2] row_mask:0xf bank_mask:0xf
	v_fmac_f32_dpp v80, v206, v74 quad_perm:[2,2,2,2] row_mask:0xf bank_mask:0xf
	v_fmac_f32_dpp v81, v207, v75 quad_perm:[2,2,2,2] row_mask:0xf bank_mask:0xf
	v_fmac_f32_dpp v72, v204, v78 quad_perm:[3,3,3,3] row_mask:0xf bank_mask:0xf
	v_fmac_f32_dpp v73, v205, v79 quad_perm:[3,3,3,3] row_mask:0xf bank_mask:0xf
	v_fmac_f32_dpp v80, v206, v76 quad_perm:[3,3,3,3] row_mask:0xf bank_mask:0xf
	v_fmac_f32_dpp v81, v207, v77 quad_perm:[3,3,3,3] row_mask:0xf bank_mask:0xf
	v_mov_b32_e32 v86, v72
	v_mov_b32_e32 v87, v80
	v_mov_b32_e32 v80, v73
	v_pk_add_f32 v[72:73], v[86:87], v[80:81]
	s_nop 0
	v_pk_add_f32 v[72:73], v[72:73], v[72:73] op_sel:[0,1] op_sel_hi:[1,0]
	s_nop 0
	v_pk_add_f32 v[72:73], v[84:85], v[72:73] neg_lo:[0,1] neg_hi:[0,1]
	ds_read_b128 v[196:199], v228 offset:47616
	ds_read_b128 v[200:203], v228 offset:47680
	ds_read_b128 v[204:207], v228 offset:47744
	ds_read_b128 v[208:211], v228 offset:47808
	s_waitcnt lgkmcnt(4)
	v_mul_f32_dpp v80, v212, v0 quad_perm:[0,0,0,0] row_mask:0xf bank_mask:0xf
	v_mul_f32_dpp v81, v213, v1 quad_perm:[0,0,0,0] row_mask:0xf bank_mask:0xf
	v_mul_f32_dpp v84, v214, v6 quad_perm:[0,0,0,0] row_mask:0xf bank_mask:0xf
	v_mul_f32_dpp v85, v215, v7 quad_perm:[0,0,0,0] row_mask:0xf bank_mask:0xf
	v_fmac_f32_dpp v80, v212, v8 quad_perm:[1,1,1,1] row_mask:0xf bank_mask:0xf
	v_fmac_f32_dpp v81, v213, v9 quad_perm:[1,1,1,1] row_mask:0xf bank_mask:0xf
	v_mov_b32_e32 v88, v84
	v_fmac_f32_dpp v88, v214, v10 quad_perm:[1,1,1,1] row_mask:0xf bank_mask:0xf
	v_mov_b32_e32 v89, v85
	v_fmac_f32_dpp v89, v215, v11 quad_perm:[1,1,1,1] row_mask:0xf bank_mask:0xf
	v_fmac_f32_dpp v80, v212, v12 quad_perm:[2,2,2,2] row_mask:0xf bank_mask:0xf
	v_fmac_f32_dpp v81, v213, v13 quad_perm:[2,2,2,2] row_mask:0xf bank_mask:0xf
	v_mov_b32_e32 v92, v88
	v_fmac_f32_dpp v92, v214, v16 quad_perm:[2,2,2,2] row_mask:0xf bank_mask:0xf
	v_mov_b32_e32 v93, v89
	v_fmac_f32_dpp v93, v215, v17 quad_perm:[2,2,2,2] row_mask:0xf bank_mask:0xf
	v_fmac_f32_dpp v80, v212, v20 quad_perm:[3,3,3,3] row_mask:0xf bank_mask:0xf
	v_fmac_f32_dpp v81, v213, v21 quad_perm:[3,3,3,3] row_mask:0xf bank_mask:0xf
	v_mov_b32_e32 v96, v92
	v_fmac_f32_dpp v96, v214, v22 quad_perm:[3,3,3,3] row_mask:0xf bank_mask:0xf
	v_mov_b32_e32 v97, v93
	v_fmac_f32_dpp v97, v215, v23 quad_perm:[3,3,3,3] row_mask:0xf bank_mask:0xf
	v_fmac_f32_dpp v80, v216, v24 quad_perm:[0,0,0,0] row_mask:0xf bank_mask:0xf
; DI void gdn_pre(const Params& p, int ch, char* smem) {
;     ...
; #pragma unroll
;   for (int i = 1; i < 64; ++i) {
;     f32x2 sa = {0.f, 0.f}, sb = {0.f, 0.f};
;     const f32x2* arow = (const f32x2*)(Amat + i * 64);
; #pragma unroll
;     for (int k = 0; k < (i >> 1); ++k) {
;       const f32x2 a2 = arow[k];
;       if (k & 1) sb = __builtin_elementwise_fma(a2, c2[k], sb);
;       else sa = __builtin_elementwise_fma(a2, c2[k], sa);
;     }
;     float tot = (sa[0] + sa[1]) + (sb[0] + sb[1]);
;     if (i & 1) tot += Amat[i * 64 + i - 1] * c2[(i - 1) >> 1][0];
;     c2[i >> 1][i & 1] -= tot;
;     __builtin_amdgcn_sched_barrier(0);
;   }
	v_fmac_f32_dpp v81, v217, v25 quad_perm:[0,0,0,0] row_mask:0xf bank_mask:0xf
	v_fmac_f32_dpp v96, v218, v26 quad_perm:[0,0,0,0] row_mask:0xf bank_mask:0xf
	v_fmac_f32_dpp v97, v219, v27 quad_perm:[0,0,0,0] row_mask:0xf bank_mask:0xf
	v_fmac_f32_dpp v80, v216, v36 quad_perm:[1,1,1,1] row_mask:0xf bank_mask:0xf
	v_fmac_f32_dpp v81, v217, v37 quad_perm:[1,1,1,1] row_mask:0xf bank_mask:0xf
	v_fmac_f32_dpp v96, v218, v38 quad_perm:[1,1,1,1] row_mask:0xf bank_mask:0xf
	v_fmac_f32_dpp v97, v219, v39 quad_perm:[1,1,1,1] row_mask:0xf bank_mask:0xf
	v_fmac_f32_dpp v80, v216, v42 quad_perm:[2,2,2,2] row_mask:0xf bank_mask:0xf
	v_fmac_f32_dpp v81, v217, v43 quad_perm:[2,2,2,2] row_mask:0xf bank_mask:0xf
	v_mov_b32_e32 v92, v96
	v_fmac_f32_dpp v92, v218, v46 quad_perm:[2,2,2,2] row_mask:0xf bank_mask:0xf
	v_mov_b32_e32 v93, v97
	v_fmac_f32_dpp v93, v219, v47 quad_perm:[2,2,2,2] row_mask:0xf bank_mask:0xf
	v_fmac_f32_dpp v80, v216, v50 quad_perm:[3,3,3,3] row_mask:0xf bank_mask:0xf
	v_fmac_f32_dpp v81, v217, v51 quad_perm:[3,3,3,3] row_mask:0xf bank_mask:0xf
	v_mov_b32_e32 v96, v92
	v_fmac_f32_dpp v96, v218, v54 quad_perm:[3,3,3,3] row_mask:0xf bank_mask:0xf
	v_mov_b32_e32 v97, v93
	v_fmac_f32_dpp v97, v219, v55 quad_perm:[3,3,3,3] row_mask:0xf bank_mask:0xf
	v_fmac_f32_dpp v80, v220, v56 quad_perm:[0,0,0,0] row_mask:0xf bank_mask:0xf
	v_fmac_f32_dpp v81, v221, v57 quad_perm:[0,0,0,0] row_mask:0xf bank_mask:0xf
	v_fmac_f32_dpp v96, v222, v60 quad_perm:[0,0,0,0] row_mask:0xf bank_mask:0xf
	v_fmac_f32_dpp v97, v223, v61 quad_perm:[0,0,0,0] row_mask:0xf bank_mask:0xf
	v_fmac_f32_dpp v80, v220, v64 quad_perm:[1,1,1,1] row_mask:0xf bank_mask:0xf
	v_fmac_f32_dpp v81, v221, v65 quad_perm:[1,1,1,1] row_mask:0xf bank_mask:0xf
	v_mov_b32_e32 v84, v96
	v_fmac_f32_dpp v84, v222, v68 quad_perm:[1,1,1,1] row_mask:0xf bank_mask:0xf
	v_mov_b32_e32 v85, v97
	v_fmac_f32_dpp v85, v223, v69 quad_perm:[1,1,1,1] row_mask:0xf bank_mask:0xf
	v_fmac_f32_dpp v80, v220, v70 quad_perm:[2,2,2,2] row_mask:0xf bank_mask:0xf
	v_fmac_f32_dpp v81, v221, v71 quad_perm:[2,2,2,2] row_mask:0xf bank_mask:0xf
	v_fmac_f32_dpp v84, v222, v74 quad_perm:[2,2,2,2] row_mask:0xf bank_mask:0xf
	v_fmac_f32_dpp v85, v223, v75 quad_perm:[2,2,2,2] row_mask:0xf bank_mask:0xf
	v_fmac_f32_dpp v80, v220, v78 quad_perm:[3,3,3,3] row_mask:0xf bank_mask:0xf
	v_fmac_f32_dpp v81, v221, v79 quad_perm:[3,3,3,3] row_mask:0xf bank_mask:0xf
	v_fmac_f32_dpp v84, v222, v76 quad_perm:[3,3,3,3] row_mask:0xf bank_mask:0xf
	v_fmac_f32_dpp v85, v223, v77 quad_perm:[3,3,3,3] row_mask:0xf bank_mask:0xf
	v_mov_b32_e32 v86, v80
	v_mov_b32_e32 v87, v84
	v_mov_b32_e32 v84, v81
	v_pk_add_f32 v[80:81], v[86:87], v[84:85]
	s_nop 0
	v_add_f32_e32 v31, v80, v81
	v_fmac_f32_dpp v31, v224, v72 quad_perm:[0,0,0,0] row_mask:0xf bank_mask:0xf
	v_sub_f32_e32 v73, v66, v31
	ds_read_b128 v[212:215], v228 offset:47872
	ds_read_b128 v[216:219], v228 offset:47936
	ds_read_b128 v[220:223], v228 offset:48000
	ds_read_b128 v[224:227], v228 offset:48064
	s_waitcnt lgkmcnt(4)
	v_mul_f32_dpp v66, v196, v0 quad_perm:[0,0,0,0] row_mask:0xf bank_mask:0xf
	v_mul_f32_dpp v67, v197, v1 quad_perm:[0,0,0,0] row_mask:0xf bank_mask:0xf
	v_mul_f32_dpp v80, v198, v6 quad_perm:[0,0,0,0] row_mask:0xf bank_mask:0xf
	v_mul_f32_dpp v81, v199, v7 quad_perm:[0,0,0,0] row_mask:0xf bank_mask:0xf
	v_fmac_f32_dpp v66, v196, v8 quad_perm:[1,1,1,1] row_mask:0xf bank_mask:0xf
	v_fmac_f32_dpp v67, v197, v9 quad_perm:[1,1,1,1] row_mask:0xf bank_mask:0xf
	v_fmac_f32_dpp v80, v198, v10 quad_perm:[1,1,1,1] row_mask:0xf bank_mask:0xf
	v_fmac_f32_dpp v81, v199, v11 quad_perm:[1,1,1,1] row_mask:0xf bank_mask:0xf
	v_fmac_f32_dpp v66, v196, v12 quad_perm:[2,2,2,2] row_mask:0xf bank_mask:0xf
	v_fmac_f32_dpp v67, v197, v13 quad_perm:[2,2,2,2] row_mask:0xf bank_mask:0xf
	v_fmac_f32_dpp v80, v198, v16 quad_perm:[2,2,2,2] row_mask:0xf bank_mask:0xf
	v_fmac_f32_dpp v81, v199, v17 quad_perm:[2,2,2,2] row_mask:0xf bank_mask:0xf
	v_fmac_f32_dpp v66, v196, v20 quad_perm:[3,3,3,3] row_mask:0xf bank_mask:0xf
	v_fmac_f32_dpp v67, v197, v21 quad_perm:[3,3,3,3] row_mask:0xf bank_mask:0xf
	v_fmac_f32_dpp v80, v198, v22 quad_perm:[3,3,3,3] row_mask:0xf bank_mask:0xf
	v_fmac_f32_dpp v81, v199, v23 quad_perm:[3,3,3,3] row_mask:0xf bank_mask:0xf
	v_fmac_f32_dpp v66, v200, v24 quad_perm:[0,0,0,0] row_mask:0xf bank_mask:0xf
	v_fmac_f32_dpp v67, v201, v25 quad_perm:[0,0,0,0] row_mask:0xf bank_mask:0xf
	v_fmac_f32_dpp v80, v202, v26 quad_perm:[0,0,0,0] row_mask:0xf bank_mask:0xf
	v_fmac_f32_dpp v81, v203, v27 quad_perm:[0,0,0,0] row_mask:0xf bank_mask:0xf
	v_fmac_f32_dpp v66, v200, v36 quad_perm:[1,1,1,1] row_mask:0xf bank_mask:0xf
	v_fmac_f32_dpp v67, v201, v37 quad_perm:[1,1,1,1] row_mask:0xf bank_mask:0xf
	v_fmac_f32_dpp v80, v202, v38 quad_perm:[1,1,1,1] row_mask:0xf bank_mask:0xf
	v_fmac_f32_dpp v81, v203, v39 quad_perm:[1,1,1,1] row_mask:0xf bank_mask:0xf
	v_fmac_f32_dpp v66, v200, v42 quad_perm:[2,2,2,2] row_mask:0xf bank_mask:0xf
	v_fmac_f32_dpp v67, v201, v43 quad_perm:[2,2,2,2] row_mask:0xf bank_mask:0xf
	v_fmac_f32_dpp v80, v202, v46 quad_perm:[2,2,2,2] row_mask:0xf bank_mask:0xf
	v_fmac_f32_dpp v81, v203, v47 quad_perm:[2,2,2,2] row_mask:0xf bank_mask:0xf
	v_fmac_f32_dpp v66, v200, v50 quad_perm:[3,3,3,3] row_mask:0xf bank_mask:0xf
	v_fmac_f32_dpp v67, v201, v51 quad_perm:[3,3,3,3] row_mask:0xf bank_mask:0xf
	v_fmac_f32_dpp v80, v202, v54 quad_perm:[3,3,3,3] row_mask:0xf bank_mask:0xf
	v_fmac_f32_dpp v81, v203, v55 quad_perm:[3,3,3,3] row_mask:0xf bank_mask:0xf
	v_fmac_f32_dpp v66, v204, v56 quad_perm:[0,0,0,0] row_mask:0xf bank_mask:0xf
	v_fmac_f32_dpp v67, v205, v57 quad_perm:[0,0,0,0] row_mask:0xf bank_mask:0xf
; DI void gdn_pre(const Params& p, int ch, char* smem) {
;     ...
; #pragma unroll
;   for (int i = 1; i < 64; ++i) {
;     f32x2 sa = {0.f, 0.f}, sb = {0.f, 0.f};
;     const f32x2* arow = (const f32x2*)(Amat + i * 64);
; #pragma unroll
;     for (int k = 0; k < (i >> 1); ++k) {
;       const f32x2 a2 = arow[k];
;       if (k & 1) sb = __builtin_elementwise_fma(a2, c2[k], sb);
;       else sa = __builtin_elementwise_fma(a2, c2[k], sa);
;     }
;     float tot = (sa[0] + sa[1]) + (sb[0] + sb[1]);
;     if (i & 1) tot += Amat[i * 64 + i - 1] * c2[(i - 1) >> 1][0];
;     c2[i >> 1][i & 1] -= tot;
;     __builtin_amdgcn_sched_barrier(0);
;   }
	v_fmac_f32_dpp v80, v206, v60 quad_perm:[0,0,0,0] row_mask:0xf bank_mask:0xf
	v_fmac_f32_dpp v81, v207, v61 quad_perm:[0,0,0,0] row_mask:0xf bank_mask:0xf
	v_fmac_f32_dpp v66, v204, v64 quad_perm:[1,1,1,1] row_mask:0xf bank_mask:0xf
	v_fmac_f32_dpp v67, v205, v65 quad_perm:[1,1,1,1] row_mask:0xf bank_mask:0xf
	v_fmac_f32_dpp v80, v206, v68 quad_perm:[1,1,1,1] row_mask:0xf bank_mask:0xf
	v_fmac_f32_dpp v81, v207, v69 quad_perm:[1,1,1,1] row_mask:0xf bank_mask:0xf
	v_fmac_f32_dpp v66, v204, v70 quad_perm:[2,2,2,2] row_mask:0xf bank_mask:0xf
	v_fmac_f32_dpp v67, v205, v71 quad_perm:[2,2,2,2] row_mask:0xf bank_mask:0xf
	v_fmac_f32_dpp v80, v206, v74 quad_perm:[2,2,2,2] row_mask:0xf bank_mask:0xf
	v_fmac_f32_dpp v81, v207, v75 quad_perm:[2,2,2,2] row_mask:0xf bank_mask:0xf
	v_fmac_f32_dpp v66, v204, v78 quad_perm:[3,3,3,3] row_mask:0xf bank_mask:0xf
	v_fmac_f32_dpp v67, v205, v79 quad_perm:[3,3,3,3] row_mask:0xf bank_mask:0xf
	v_fmac_f32_dpp v80, v206, v76 quad_perm:[3,3,3,3] row_mask:0xf bank_mask:0xf
	v_fmac_f32_dpp v81, v207, v77 quad_perm:[3,3,3,3] row_mask:0xf bank_mask:0xf
	v_fmac_f32_dpp v66, v208, v72 quad_perm:[0,0,0,0] row_mask:0xf bank_mask:0xf
	v_fmac_f32_dpp v67, v209, v73 quad_perm:[0,0,0,0] row_mask:0xf bank_mask:0xf
	v_mov_b32_e32 v84, v80
	v_mov_b32_e32 v85, v66
	v_mov_b32_e32 v66, v81
	v_pk_add_f32 v[66:67], v[84:85], v[66:67]
	s_nop 0
	v_pk_add_f32 v[66:67], v[66:67], v[66:67] op_sel:[0,1] op_sel_hi:[1,0]
	s_nop 0
	v_pk_add_f32 v[66:67], v[82:83], v[66:67] neg_lo:[0,1] neg_hi:[0,1]
	ds_read_b128 v[196:199], v228 offset:48128
	ds_read_b128 v[200:203], v228 offset:48192
	ds_read_b128 v[204:207], v228 offset:48256
	ds_read_b128 v[208:211], v228 offset:48320
	s_waitcnt lgkmcnt(4)
	v_mul_f32_dpp v80, v212, v0 quad_perm:[0,0,0,0] row_mask:0xf bank_mask:0xf
	v_mul_f32_dpp v81, v213, v1 quad_perm:[0,0,0,0] row_mask:0xf bank_mask:0xf
	v_mul_f32_dpp v82, v214, v6 quad_perm:[0,0,0,0] row_mask:0xf bank_mask:0xf
	v_mul_f32_dpp v83, v215, v7 quad_perm:[0,0,0,0] row_mask:0xf bank_mask:0xf
	v_fmac_f32_dpp v80, v212, v8 quad_perm:[1,1,1,1] row_mask:0xf bank_mask:0xf
	v_fmac_f32_dpp v81, v213, v9 quad_perm:[1,1,1,1] row_mask:0xf bank_mask:0xf
	v_mov_b32_e32 v84, v82
	v_fmac_f32_dpp v84, v214, v10 quad_perm:[1,1,1,1] row_mask:0xf bank_mask:0xf
	v_mov_b32_e32 v85, v83
	v_fmac_f32_dpp v85, v215, v11 quad_perm:[1,1,1,1] row_mask:0xf bank_mask:0xf
	v_mov_b32_e32 v86, v80
	v_fmac_f32_dpp v86, v212, v12 quad_perm:[2,2,2,2] row_mask:0xf bank_mask:0xf
	v_mov_b32_e32 v87, v81
	v_fmac_f32_dpp v87, v213, v13 quad_perm:[2,2,2,2] row_mask:0xf bank_mask:0xf
	v_mov_b32_e32 v88, v84
	v_fmac_f32_dpp v88, v214, v16 quad_perm:[2,2,2,2] row_mask:0xf bank_mask:0xf
	v_mov_b32_e32 v89, v85
	v_fmac_f32_dpp v89, v215, v17 quad_perm:[2,2,2,2] row_mask:0xf bank_mask:0xf
	v_mov_b32_e32 v90, v86
	v_fmac_f32_dpp v90, v212, v20 quad_perm:[3,3,3,3] row_mask:0xf bank_mask:0xf
	v_mov_b32_e32 v91, v87
	v_fmac_f32_dpp v91, v213, v21 quad_perm:[3,3,3,3] row_mask:0xf bank_mask:0xf
	v_mov_b32_e32 v92, v88
	v_fmac_f32_dpp v92, v214, v22 quad_perm:[3,3,3,3] row_mask:0xf bank_mask:0xf
	v_mov_b32_e32 v93, v89
	v_fmac_f32_dpp v93, v215, v23 quad_perm:[3,3,3,3] row_mask:0xf bank_mask:0xf
	v_mov_b32_e32 v80, v90
	v_fmac_f32_dpp v80, v216, v24 quad_perm:[0,0,0,0] row_mask:0xf bank_mask:0xf
	v_mov_b32_e32 v81, v91
	v_fmac_f32_dpp v81, v217, v25 quad_perm:[0,0,0,0] row_mask:0xf bank_mask:0xf
	v_fmac_f32_dpp v92, v218, v26 quad_perm:[0,0,0,0] row_mask:0xf bank_mask:0xf
	v_fmac_f32_dpp v93, v219, v27 quad_perm:[0,0,0,0] row_mask:0xf bank_mask:0xf
	v_mov_b32_e32 v84, v80
	v_fmac_f32_dpp v84, v216, v36 quad_perm:[1,1,1,1] row_mask:0xf bank_mask:0xf
	v_mov_b32_e32 v85, v81
	v_fmac_f32_dpp v85, v217, v37 quad_perm:[1,1,1,1] row_mask:0xf bank_mask:0xf
	v_fmac_f32_dpp v92, v218, v38 quad_perm:[1,1,1,1] row_mask:0xf bank_mask:0xf
	v_fmac_f32_dpp v93, v219, v39 quad_perm:[1,1,1,1] row_mask:0xf bank_mask:0xf
	v_mov_b32_e32 v88, v84
	v_fmac_f32_dpp v88, v216, v42 quad_perm:[2,2,2,2] row_mask:0xf bank_mask:0xf
	v_mov_b32_e32 v89, v85
	v_fmac_f32_dpp v89, v217, v43 quad_perm:[2,2,2,2] row_mask:0xf bank_mask:0xf
	v_fmac_f32_dpp v92, v218, v46 quad_perm:[2,2,2,2] row_mask:0xf bank_mask:0xf
	v_fmac_f32_dpp v93, v219, v47 quad_perm:[2,2,2,2] row_mask:0xf bank_mask:0xf
	v_mov_b32_e32 v80, v88
	v_fmac_f32_dpp v80, v216, v50 quad_perm:[3,3,3,3] row_mask:0xf bank_mask:0xf
	v_mov_b32_e32 v81, v89
	v_fmac_f32_dpp v81, v217, v51 quad_perm:[3,3,3,3] row_mask:0xf bank_mask:0xf
	v_mov_b32_e32 v82, v92
	v_fmac_f32_dpp v82, v218, v54 quad_perm:[3,3,3,3] row_mask:0xf bank_mask:0xf
	v_mov_b32_e32 v83, v93
	v_fmac_f32_dpp v83, v219, v55 quad_perm:[3,3,3,3] row_mask:0xf bank_mask:0xf
	v_mov_b32_e32 v84, v80
	v_fmac_f32_dpp v84, v220, v56 quad_perm:[0,0,0,0] row_mask:0xf bank_mask:0xf
	v_mov_b32_e32 v85, v81
	v_fmac_f32_dpp v85, v221, v57 quad_perm:[0,0,0,0] row_mask:0xf bank_mask:0xf
	v_mov_b32_e32 v92, v82
	v_fmac_f32_dpp v92, v222, v60 quad_perm:[0,0,0,0] row_mask:0xf bank_mask:0xf
	v_mov_b32_e32 v93, v83
	v_fmac_f32_dpp v93, v223, v61 quad_perm:[0,0,0,0] row_mask:0xf bank_mask:0xf
	v_mov_b32_e32 v94, v84
	v_fmac_f32_dpp v94, v220, v64 quad_perm:[1,1,1,1] row_mask:0xf bank_mask:0xf
	v_mov_b32_e32 v95, v85
	v_fmac_f32_dpp v95, v221, v65 quad_perm:[1,1,1,1] row_mask:0xf bank_mask:0xf
	v_fmac_f32_dpp v92, v222, v68 quad_perm:[1,1,1,1] row_mask:0xf bank_mask:0xf
	v_fmac_f32_dpp v93, v223, v69 quad_perm:[1,1,1,1] row_mask:0xf bank_mask:0xf
	v_mov_b32_e32 v80, v94
	v_fmac_f32_dpp v80, v220, v70 quad_perm:[2,2,2,2] row_mask:0xf bank_mask:0xf
	v_mov_b32_e32 v81, v95
	v_fmac_f32_dpp v81, v221, v71 quad_perm:[2,2,2,2] row_mask:0xf bank_mask:0xf
	v_mov_b32_e32 v82, v92
	v_fmac_f32_dpp v82, v222, v74 quad_perm:[2,2,2,2] row_mask:0xf bank_mask:0xf
	v_mov_b32_e32 v83, v93
	v_fmac_f32_dpp v83, v223, v75 quad_perm:[2,2,2,2] row_mask:0xf bank_mask:0xf
	v_fmac_f32_dpp v80, v220, v78 quad_perm:[3,3,3,3] row_mask:0xf bank_mask:0xf
	v_fmac_f32_dpp v81, v221, v79 quad_perm:[3,3,3,3] row_mask:0xf bank_mask:0xf
	v_fmac_f32_dpp v82, v222, v76 quad_perm:[3,3,3,3] row_mask:0xf bank_mask:0xf
	v_fmac_f32_dpp v83, v223, v77 quad_perm:[3,3,3,3] row_mask:0xf bank_mask:0xf
	v_fmac_f32_dpp v80, v224, v72 quad_perm:[0,0,0,0] row_mask:0xf bank_mask:0xf
	v_fmac_f32_dpp v81, v225, v73 quad_perm:[0,0,0,0] row_mask:0xf bank_mask:0xf
	v_mov_b32_e32 v84, v82
	v_mov_b32_e32 v85, v80
	v_mov_b32_e32 v80, v83
	v_pk_add_f32 v[80:81], v[84:85], v[80:81]
	s_nop 0
	v_add_f32_e32 v19, v80, v81
	v_fmac_f32_dpp v19, v226, v66 quad_perm:[0,0,0,0] row_mask:0xf bank_mask:0xf
	v_sub_f32_e32 v67, v62, v19
	ds_read_b128 v[212:215], v228 offset:48384
	ds_read_b128 v[216:219], v228 offset:48448
	ds_read_b128 v[220:223], v228 offset:48512
	ds_read_b128 v[224:227], v228 offset:48576
	s_waitcnt lgkmcnt(4)
; DI void gdn_pre(const Params& p, int ch, char* smem) {
;     ...
; #pragma unroll
;   for (int i = 1; i < 64; ++i) {
;     f32x2 sa = {0.f, 0.f}, sb = {0.f, 0.f};
;     const f32x2* arow = (const f32x2*)(Amat + i * 64);
; #pragma unroll
;     for (int k = 0; k < (i >> 1); ++k) {
;       const f32x2 a2 = arow[k];
;       if (k & 1) sb = __builtin_elementwise_fma(a2, c2[k], sb);
;       else sa = __builtin_elementwise_fma(a2, c2[k], sa);
;     }
;     float tot = (sa[0] + sa[1]) + (sb[0] + sb[1]);
;     if (i & 1) tot += Amat[i * 64 + i - 1] * c2[(i - 1) >> 1][0];
;     c2[i >> 1][i & 1] -= tot;
;     __builtin_amdgcn_sched_barrier(0);
;   }
	v_mul_f32_dpp v62, v196, v0 quad_perm:[0,0,0,0] row_mask:0xf bank_mask:0xf
	v_mul_f32_dpp v63, v197, v1 quad_perm:[0,0,0,0] row_mask:0xf bank_mask:0xf
	v_mul_f32_dpp v80, v198, v6 quad_perm:[0,0,0,0] row_mask:0xf bank_mask:0xf
	v_mul_f32_dpp v81, v199, v7 quad_perm:[0,0,0,0] row_mask:0xf bank_mask:0xf
	v_fmac_f32_dpp v62, v196, v8 quad_perm:[1,1,1,1] row_mask:0xf bank_mask:0xf
	v_fmac_f32_dpp v63, v197, v9 quad_perm:[1,1,1,1] row_mask:0xf bank_mask:0xf
	v_mov_b32_e32 v84, v80
	v_fmac_f32_dpp v84, v198, v10 quad_perm:[1,1,1,1] row_mask:0xf bank_mask:0xf
	v_mov_b32_e32 v85, v81
	v_fmac_f32_dpp v85, v199, v11 quad_perm:[1,1,1,1] row_mask:0xf bank_mask:0xf
	v_fmac_f32_dpp v62, v196, v12 quad_perm:[2,2,2,2] row_mask:0xf bank_mask:0xf
	v_fmac_f32_dpp v63, v197, v13 quad_perm:[2,2,2,2] row_mask:0xf bank_mask:0xf
	v_mov_b32_e32 v88, v84
	v_fmac_f32_dpp v88, v198, v16 quad_perm:[2,2,2,2] row_mask:0xf bank_mask:0xf
	v_mov_b32_e32 v89, v85
	v_fmac_f32_dpp v89, v199, v17 quad_perm:[2,2,2,2] row_mask:0xf bank_mask:0xf
	v_fmac_f32_dpp v62, v196, v20 quad_perm:[3,3,3,3] row_mask:0xf bank_mask:0xf
	v_fmac_f32_dpp v63, v197, v21 quad_perm:[3,3,3,3] row_mask:0xf bank_mask:0xf
	v_mov_b32_e32 v92, v88
	v_fmac_f32_dpp v92, v198, v22 quad_perm:[3,3,3,3] row_mask:0xf bank_mask:0xf
	v_mov_b32_e32 v93, v89
	v_fmac_f32_dpp v93, v199, v23 quad_perm:[3,3,3,3] row_mask:0xf bank_mask:0xf
	v_fmac_f32_dpp v62, v200, v24 quad_perm:[0,0,0,0] row_mask:0xf bank_mask:0xf
	v_fmac_f32_dpp v63, v201, v25 quad_perm:[0,0,0,0] row_mask:0xf bank_mask:0xf
	v_fmac_f32_dpp v92, v202, v26 quad_perm:[0,0,0,0] row_mask:0xf bank_mask:0xf
	v_fmac_f32_dpp v93, v203, v27 quad_perm:[0,0,0,0] row_mask:0xf bank_mask:0xf
	v_fmac_f32_dpp v62, v200, v36 quad_perm:[1,1,1,1] row_mask:0xf bank_mask:0xf
	v_fmac_f32_dpp v63, v201, v37 quad_perm:[1,1,1,1] row_mask:0xf bank_mask:0xf
	v_fmac_f32_dpp v92, v202, v38 quad_perm:[1,1,1,1] row_mask:0xf bank_mask:0xf
	v_fmac_f32_dpp v93, v203, v39 quad_perm:[1,1,1,1] row_mask:0xf bank_mask:0xf
	v_fmac_f32_dpp v62, v200, v42 quad_perm:[2,2,2,2] row_mask:0xf bank_mask:0xf
	v_fmac_f32_dpp v63, v201, v43 quad_perm:[2,2,2,2] row_mask:0xf bank_mask:0xf
	v_fmac_f32_dpp v92, v202, v46 quad_perm:[2,2,2,2] row_mask:0xf bank_mask:0xf
	v_fmac_f32_dpp v93, v203, v47 quad_perm:[2,2,2,2] row_mask:0xf bank_mask:0xf
	v_fmac_f32_dpp v62, v200, v50 quad_perm:[3,3,3,3] row_mask:0xf bank_mask:0xf
	v_fmac_f32_dpp v63, v201, v51 quad_perm:[3,3,3,3] row_mask:0xf bank_mask:0xf
	v_mov_b32_e32 v80, v92
	v_fmac_f32_dpp v80, v202, v54 quad_perm:[3,3,3,3] row_mask:0xf bank_mask:0xf
	v_mov_b32_e32 v81, v93
	v_fmac_f32_dpp v81, v203, v55 quad_perm:[3,3,3,3] row_mask:0xf bank_mask:0xf
	v_fmac_f32_dpp v62, v204, v56 quad_perm:[0,0,0,0] row_mask:0xf bank_mask:0xf
	v_fmac_f32_dpp v63, v205, v57 quad_perm:[0,0,0,0] row_mask:0xf bank_mask:0xf
	v_mov_b32_e32 v92, v80
	v_fmac_f32_dpp v92, v206, v60 quad_perm:[0,0,0,0] row_mask:0xf bank_mask:0xf
	v_mov_b32_e32 v93, v81
	v_fmac_f32_dpp v93, v207, v61 quad_perm:[0,0,0,0] row_mask:0xf bank_mask:0xf
	v_fmac_f32_dpp v62, v204, v64 quad_perm:[1,1,1,1] row_mask:0xf bank_mask:0xf
	v_fmac_f32_dpp v63, v205, v65 quad_perm:[1,1,1,1] row_mask:0xf bank_mask:0xf
	v_fmac_f32_dpp v92, v206, v68 quad_perm:[1,1,1,1] row_mask:0xf bank_mask:0xf
	v_fmac_f32_dpp v93, v207, v69 quad_perm:[1,1,1,1] row_mask:0xf bank_mask:0xf
	v_fmac_f32_dpp v62, v204, v70 quad_perm:[2,2,2,2] row_mask:0xf bank_mask:0xf
	v_fmac_f32_dpp v63, v205, v71 quad_perm:[2,2,2,2] row_mask:0xf bank_mask:0xf
	v_mov_b32_e32 v80, v92
	v_fmac_f32_dpp v80, v206, v74 quad_perm:[2,2,2,2] row_mask:0xf bank_mask:0xf
	v_mov_b32_e32 v81, v93
	v_fmac_f32_dpp v81, v207, v75 quad_perm:[2,2,2,2] row_mask:0xf bank_mask:0xf
	v_fmac_f32_dpp v62, v204, v78 quad_perm:[3,3,3,3] row_mask:0xf bank_mask:0xf
	v_fmac_f32_dpp v63, v205, v79 quad_perm:[3,3,3,3] row_mask:0xf bank_mask:0xf
	v_fmac_f32_dpp v80, v206, v76 quad_perm:[3,3,3,3] row_mask:0xf bank_mask:0xf
	v_fmac_f32_dpp v81, v207, v77 quad_perm:[3,3,3,3] row_mask:0xf bank_mask:0xf
	v_fmac_f32_dpp v62, v208, v72 quad_perm:[0,0,0,0] row_mask:0xf bank_mask:0xf
	v_fmac_f32_dpp v63, v209, v73 quad_perm:[0,0,0,0] row_mask:0xf bank_mask:0xf
	v_fmac_f32_dpp v80, v210, v66 quad_perm:[0,0,0,0] row_mask:0xf bank_mask:0xf
	v_fmac_f32_dpp v81, v211, v67 quad_perm:[0,0,0,0] row_mask:0xf bank_mask:0xf
	v_mov_b32_e32 v82, v62
	v_mov_b32_e32 v83, v80
	v_mov_b32_e32 v80, v63
	v_pk_add_f32 v[62:63], v[82:83], v[80:81]
	s_nop 0
	v_pk_add_f32 v[62:63], v[62:63], v[62:63] op_sel:[0,1] op_sel_hi:[1,0]
	s_nop 0
	v_pk_add_f32 v[48:49], v[48:49], v[62:63] neg_lo:[0,1] neg_hi:[0,1]
	ds_read_b128 v[196:199], v228 offset:48640
	ds_read_b128 v[200:203], v228 offset:48704
	ds_read_b128 v[204:207], v228 offset:48768
	ds_read_b128 v[208:211], v228 offset:48832
	s_waitcnt lgkmcnt(4)
; DI void gdn_pre(const Params& p, int ch, char* smem) {
;     ...
; #pragma unroll
;   for (int i = 1; i < 64; ++i) {
;     f32x2 sa = {0.f, 0.f}, sb = {0.f, 0.f};
;     const f32x2* arow = (const f32x2*)(Amat + i * 64);
; #pragma unroll
;     for (int k = 0; k < (i >> 1); ++k) {
;       const f32x2 a2 = arow[k];
;       if (k & 1) sb = __builtin_elementwise_fma(a2, c2[k], sb);
;       else sa = __builtin_elementwise_fma(a2, c2[k], sa);
;     }
;     float tot = (sa[0] + sa[1]) + (sb[0] + sb[1]);
;     if (i & 1) tot += Amat[i * 64 + i - 1] * c2[(i - 1) >> 1][0];
;     c2[i >> 1][i & 1] -= tot;
;     __builtin_amdgcn_sched_barrier(0);
;   }
	v_mul_f32_dpp v62, v212, v0 quad_perm:[0,0,0,0] row_mask:0xf bank_mask:0xf
	v_mul_f32_dpp v63, v213, v1 quad_perm:[0,0,0,0] row_mask:0xf bank_mask:0xf
	v_mul_f32_dpp v80, v214, v6 quad_perm:[0,0,0,0] row_mask:0xf bank_mask:0xf
	v_mul_f32_dpp v81, v215, v7 quad_perm:[0,0,0,0] row_mask:0xf bank_mask:0xf
	v_fmac_f32_dpp v62, v212, v8 quad_perm:[1,1,1,1] row_mask:0xf bank_mask:0xf
	v_fmac_f32_dpp v63, v213, v9 quad_perm:[1,1,1,1] row_mask:0xf bank_mask:0xf
	v_mov_b32_e32 v84, v80
	v_fmac_f32_dpp v84, v214, v10 quad_perm:[1,1,1,1] row_mask:0xf bank_mask:0xf
	v_mov_b32_e32 v85, v81
	v_fmac_f32_dpp v85, v215, v11 quad_perm:[1,1,1,1] row_mask:0xf bank_mask:0xf
	v_fmac_f32_dpp v62, v212, v12 quad_perm:[2,2,2,2] row_mask:0xf bank_mask:0xf
	v_fmac_f32_dpp v63, v213, v13 quad_perm:[2,2,2,2] row_mask:0xf bank_mask:0xf
	v_mov_b32_e32 v88, v84
	v_fmac_f32_dpp v88, v214, v16 quad_perm:[2,2,2,2] row_mask:0xf bank_mask:0xf
	v_mov_b32_e32 v89, v85
	v_fmac_f32_dpp v89, v215, v17 quad_perm:[2,2,2,2] row_mask:0xf bank_mask:0xf
	v_fmac_f32_dpp v62, v212, v20 quad_perm:[3,3,3,3] row_mask:0xf bank_mask:0xf
	v_fmac_f32_dpp v63, v213, v21 quad_perm:[3,3,3,3] row_mask:0xf bank_mask:0xf
	v_mov_b32_e32 v92, v88
	v_fmac_f32_dpp v92, v214, v22 quad_perm:[3,3,3,3] row_mask:0xf bank_mask:0xf
	v_mov_b32_e32 v93, v89
	v_fmac_f32_dpp v93, v215, v23 quad_perm:[3,3,3,3] row_mask:0xf bank_mask:0xf
	v_fmac_f32_dpp v62, v216, v24 quad_perm:[0,0,0,0] row_mask:0xf bank_mask:0xf
	v_fmac_f32_dpp v63, v217, v25 quad_perm:[0,0,0,0] row_mask:0xf bank_mask:0xf
	v_fmac_f32_dpp v92, v218, v26 quad_perm:[0,0,0,0] row_mask:0xf bank_mask:0xf
	v_fmac_f32_dpp v93, v219, v27 quad_perm:[0,0,0,0] row_mask:0xf bank_mask:0xf
	v_fmac_f32_dpp v62, v216, v36 quad_perm:[1,1,1,1] row_mask:0xf bank_mask:0xf
	v_fmac_f32_dpp v63, v217, v37 quad_perm:[1,1,1,1] row_mask:0xf bank_mask:0xf
	v_fmac_f32_dpp v92, v218, v38 quad_perm:[1,1,1,1] row_mask:0xf bank_mask:0xf
	v_fmac_f32_dpp v93, v219, v39 quad_perm:[1,1,1,1] row_mask:0xf bank_mask:0xf
	v_fmac_f32_dpp v62, v216, v42 quad_perm:[2,2,2,2] row_mask:0xf bank_mask:0xf
	v_fmac_f32_dpp v63, v217, v43 quad_perm:[2,2,2,2] row_mask:0xf bank_mask:0xf
	v_fmac_f32_dpp v92, v218, v46 quad_perm:[2,2,2,2] row_mask:0xf bank_mask:0xf
	v_fmac_f32_dpp v93, v219, v47 quad_perm:[2,2,2,2] row_mask:0xf bank_mask:0xf
	v_fmac_f32_dpp v62, v216, v50 quad_perm:[3,3,3,3] row_mask:0xf bank_mask:0xf
	v_fmac_f32_dpp v63, v217, v51 quad_perm:[3,3,3,3] row_mask:0xf bank_mask:0xf
	v_fmac_f32_dpp v92, v218, v54 quad_perm:[3,3,3,3] row_mask:0xf bank_mask:0xf
	v_fmac_f32_dpp v93, v219, v55 quad_perm:[3,3,3,3] row_mask:0xf bank_mask:0xf
	v_fmac_f32_dpp v62, v220, v56 quad_perm:[0,0,0,0] row_mask:0xf bank_mask:0xf
	v_fmac_f32_dpp v63, v221, v57 quad_perm:[0,0,0,0] row_mask:0xf bank_mask:0xf
	v_fmac_f32_dpp v92, v222, v60 quad_perm:[0,0,0,0] row_mask:0xf bank_mask:0xf
	v_fmac_f32_dpp v93, v223, v61 quad_perm:[0,0,0,0] row_mask:0xf bank_mask:0xf
	v_fmac_f32_dpp v62, v220, v64 quad_perm:[1,1,1,1] row_mask:0xf bank_mask:0xf
	v_fmac_f32_dpp v63, v221, v65 quad_perm:[1,1,1,1] row_mask:0xf bank_mask:0xf
	v_fmac_f32_dpp v92, v222, v68 quad_perm:[1,1,1,1] row_mask:0xf bank_mask:0xf
	v_fmac_f32_dpp v93, v223, v69 quad_perm:[1,1,1,1] row_mask:0xf bank_mask:0xf
	v_fmac_f32_dpp v62, v220, v70 quad_perm:[2,2,2,2] row_mask:0xf bank_mask:0xf
	v_fmac_f32_dpp v63, v221, v71 quad_perm:[2,2,2,2] row_mask:0xf bank_mask:0xf
	v_mov_b32_e32 v80, v92
	v_fmac_f32_dpp v80, v222, v74 quad_perm:[2,2,2,2] row_mask:0xf bank_mask:0xf
	v_mov_b32_e32 v81, v93
	v_fmac_f32_dpp v81, v223, v75 quad_perm:[2,2,2,2] row_mask:0xf bank_mask:0xf
	v_fmac_f32_dpp v62, v220, v78 quad_perm:[3,3,3,3] row_mask:0xf bank_mask:0xf
	v_fmac_f32_dpp v63, v221, v79 quad_perm:[3,3,3,3] row_mask:0xf bank_mask:0xf
	v_fmac_f32_dpp v80, v222, v76 quad_perm:[3,3,3,3] row_mask:0xf bank_mask:0xf
	v_fmac_f32_dpp v81, v223, v77 quad_perm:[3,3,3,3] row_mask:0xf bank_mask:0xf
	v_fmac_f32_dpp v62, v224, v72 quad_perm:[0,0,0,0] row_mask:0xf bank_mask:0xf
	v_fmac_f32_dpp v63, v225, v73 quad_perm:[0,0,0,0] row_mask:0xf bank_mask:0xf
	v_fmac_f32_dpp v80, v226, v66 quad_perm:[0,0,0,0] row_mask:0xf bank_mask:0xf
	v_fmac_f32_dpp v81, v227, v67 quad_perm:[0,0,0,0] row_mask:0xf bank_mask:0xf
	v_mov_b32_e32 v82, v62
	v_mov_b32_e32 v83, v80
	v_mov_b32_e32 v80, v63
	v_pk_add_f32 v[62:63], v[82:83], v[80:81]
	s_nop 0
	v_add_f32_e32 v31, v62, v63
	v_fmac_f32_dpp v31, v224, v48 quad_perm:[1,1,1,1] row_mask:0xf bank_mask:0xf
	v_sub_f32_e32 v49, v58, v31
	ds_read_b128 v[212:215], v228 offset:48896
	ds_read_b128 v[216:219], v228 offset:48960
	ds_read_b128 v[220:223], v228 offset:49024
	ds_read_b128 v[224:227], v228 offset:49088
	s_waitcnt lgkmcnt(4)
; DI void gdn_pre(const Params& p, int ch, char* smem) {
;     ...
; #pragma unroll
;   for (int i = 1; i < 64; ++i) {
;     f32x2 sa = {0.f, 0.f}, sb = {0.f, 0.f};
;     const f32x2* arow = (const f32x2*)(Amat + i * 64);
; #pragma unroll
;     for (int k = 0; k < (i >> 1); ++k) {
;       const f32x2 a2 = arow[k];
;       if (k & 1) sb = __builtin_elementwise_fma(a2, c2[k], sb);
;       else sa = __builtin_elementwise_fma(a2, c2[k], sa);
;     }
;     float tot = (sa[0] + sa[1]) + (sb[0] + sb[1]);
;     if (i & 1) tot += Amat[i * 64 + i - 1] * c2[(i - 1) >> 1][0];
;     c2[i >> 1][i & 1] -= tot;
;     __builtin_amdgcn_sched_barrier(0);
;   }
	v_mul_f32_dpp v58, v196, v0 quad_perm:[0,0,0,0] row_mask:0xf bank_mask:0xf
	v_mul_f32_dpp v59, v197, v1 quad_perm:[0,0,0,0] row_mask:0xf bank_mask:0xf
	v_mul_f32_dpp v62, v198, v6 quad_perm:[0,0,0,0] row_mask:0xf bank_mask:0xf
	v_mul_f32_dpp v63, v199, v7 quad_perm:[0,0,0,0] row_mask:0xf bank_mask:0xf
	v_fmac_f32_dpp v58, v196, v8 quad_perm:[1,1,1,1] row_mask:0xf bank_mask:0xf
	v_fmac_f32_dpp v59, v197, v9 quad_perm:[1,1,1,1] row_mask:0xf bank_mask:0xf
	v_fmac_f32_dpp v62, v198, v10 quad_perm:[1,1,1,1] row_mask:0xf bank_mask:0xf
	v_fmac_f32_dpp v63, v199, v11 quad_perm:[1,1,1,1] row_mask:0xf bank_mask:0xf
	v_fmac_f32_dpp v58, v196, v12 quad_perm:[2,2,2,2] row_mask:0xf bank_mask:0xf
	v_fmac_f32_dpp v59, v197, v13 quad_perm:[2,2,2,2] row_mask:0xf bank_mask:0xf
	v_fmac_f32_dpp v62, v198, v16 quad_perm:[2,2,2,2] row_mask:0xf bank_mask:0xf
	v_fmac_f32_dpp v63, v199, v17 quad_perm:[2,2,2,2] row_mask:0xf bank_mask:0xf
	v_fmac_f32_dpp v58, v196, v20 quad_perm:[3,3,3,3] row_mask:0xf bank_mask:0xf
	v_fmac_f32_dpp v59, v197, v21 quad_perm:[3,3,3,3] row_mask:0xf bank_mask:0xf
	v_fmac_f32_dpp v62, v198, v22 quad_perm:[3,3,3,3] row_mask:0xf bank_mask:0xf
	v_fmac_f32_dpp v63, v199, v23 quad_perm:[3,3,3,3] row_mask:0xf bank_mask:0xf
	v_fmac_f32_dpp v58, v200, v24 quad_perm:[0,0,0,0] row_mask:0xf bank_mask:0xf
	v_fmac_f32_dpp v59, v201, v25 quad_perm:[0,0,0,0] row_mask:0xf bank_mask:0xf
	v_fmac_f32_dpp v62, v202, v26 quad_perm:[0,0,0,0] row_mask:0xf bank_mask:0xf
	v_fmac_f32_dpp v63, v203, v27 quad_perm:[0,0,0,0] row_mask:0xf bank_mask:0xf
	v_fmac_f32_dpp v58, v200, v36 quad_perm:[1,1,1,1] row_mask:0xf bank_mask:0xf
	v_fmac_f32_dpp v59, v201, v37 quad_perm:[1,1,1,1] row_mask:0xf bank_mask:0xf
	v_fmac_f32_dpp v62, v202, v38 quad_perm:[1,1,1,1] row_mask:0xf bank_mask:0xf
	v_fmac_f32_dpp v63, v203, v39 quad_perm:[1,1,1,1] row_mask:0xf bank_mask:0xf
	v_fmac_f32_dpp v58, v200, v42 quad_perm:[2,2,2,2] row_mask:0xf bank_mask:0xf
	v_fmac_f32_dpp v59, v201, v43 quad_perm:[2,2,2,2] row_mask:0xf bank_mask:0xf
	v_fmac_f32_dpp v62, v202, v46 quad_perm:[2,2,2,2] row_mask:0xf bank_mask:0xf
	v_fmac_f32_dpp v63, v203, v47 quad_perm:[2,2,2,2] row_mask:0xf bank_mask:0xf
	v_fmac_f32_dpp v58, v200, v50 quad_perm:[3,3,3,3] row_mask:0xf bank_mask:0xf
	v_fmac_f32_dpp v59, v201, v51 quad_perm:[3,3,3,3] row_mask:0xf bank_mask:0xf
	v_fmac_f32_dpp v62, v202, v54 quad_perm:[3,3,3,3] row_mask:0xf bank_mask:0xf
	v_fmac_f32_dpp v63, v203, v55 quad_perm:[3,3,3,3] row_mask:0xf bank_mask:0xf
	v_fmac_f32_dpp v58, v204, v56 quad_perm:[0,0,0,0] row_mask:0xf bank_mask:0xf
	v_fmac_f32_dpp v59, v205, v57 quad_perm:[0,0,0,0] row_mask:0xf bank_mask:0xf
	v_fmac_f32_dpp v62, v206, v60 quad_perm:[0,0,0,0] row_mask:0xf bank_mask:0xf
	v_fmac_f32_dpp v63, v207, v61 quad_perm:[0,0,0,0] row_mask:0xf bank_mask:0xf
	v_fmac_f32_dpp v58, v204, v64 quad_perm:[1,1,1,1] row_mask:0xf bank_mask:0xf
	v_fmac_f32_dpp v59, v205, v65 quad_perm:[1,1,1,1] row_mask:0xf bank_mask:0xf
	v_fmac_f32_dpp v62, v206, v68 quad_perm:[1,1,1,1] row_mask:0xf bank_mask:0xf
	v_fmac_f32_dpp v63, v207, v69 quad_perm:[1,1,1,1] row_mask:0xf bank_mask:0xf
	v_fmac_f32_dpp v58, v204, v70 quad_perm:[2,2,2,2] row_mask:0xf bank_mask:0xf
	v_fmac_f32_dpp v59, v205, v71 quad_perm:[2,2,2,2] row_mask:0xf bank_mask:0xf
	v_fmac_f32_dpp v62, v206, v74 quad_perm:[2,2,2,2] row_mask:0xf bank_mask:0xf
	v_fmac_f32_dpp v63, v207, v75 quad_perm:[2,2,2,2] row_mask:0xf bank_mask:0xf
	v_fmac_f32_dpp v58, v204, v78 quad_perm:[3,3,3,3] row_mask:0xf bank_mask:0xf
	v_fmac_f32_dpp v59, v205, v79 quad_perm:[3,3,3,3] row_mask:0xf bank_mask:0xf
	v_fmac_f32_dpp v62, v206, v76 quad_perm:[3,3,3,3] row_mask:0xf bank_mask:0xf
	v_fmac_f32_dpp v63, v207, v77 quad_perm:[3,3,3,3] row_mask:0xf bank_mask:0xf
	v_fmac_f32_dpp v58, v208, v72 quad_perm:[0,0,0,0] row_mask:0xf bank_mask:0xf
	v_fmac_f32_dpp v59, v209, v73 quad_perm:[0,0,0,0] row_mask:0xf bank_mask:0xf
	v_fmac_f32_dpp v62, v210, v66 quad_perm:[0,0,0,0] row_mask:0xf bank_mask:0xf
	v_fmac_f32_dpp v63, v211, v67 quad_perm:[0,0,0,0] row_mask:0xf bank_mask:0xf
	v_fmac_f32_dpp v58, v208, v48 quad_perm:[1,1,1,1] row_mask:0xf bank_mask:0xf
	v_fmac_f32_dpp v59, v209, v49 quad_perm:[1,1,1,1] row_mask:0xf bank_mask:0xf
	v_mov_b32_e32 v80, v62
	v_mov_b32_e32 v81, v58
	v_mov_b32_e32 v58, v63
	v_pk_add_f32 v[58:59], v[80:81], v[58:59]
	s_nop 0
	v_pk_add_f32 v[58:59], v[58:59], v[58:59] op_sel:[0,1] op_sel_hi:[1,0]
	s_nop 0
	v_pk_add_f32 v[40:41], v[40:41], v[58:59] neg_lo:[0,1] neg_hi:[0,1]
	ds_read_b128 v[196:199], v228 offset:49152
	ds_read_b128 v[200:203], v228 offset:49216
	ds_read_b128 v[204:207], v228 offset:49280
	ds_read_b128 v[208:211], v228 offset:49344
	s_waitcnt lgkmcnt(4)
; DI void gdn_pre(const Params& p, int ch, char* smem) {
;     ...
; #pragma unroll
;   for (int i = 1; i < 64; ++i) {
;     f32x2 sa = {0.f, 0.f}, sb = {0.f, 0.f};
;     const f32x2* arow = (const f32x2*)(Amat + i * 64);
; #pragma unroll
;     for (int k = 0; k < (i >> 1); ++k) {
;       const f32x2 a2 = arow[k];
;       if (k & 1) sb = __builtin_elementwise_fma(a2, c2[k], sb);
;       else sa = __builtin_elementwise_fma(a2, c2[k], sa);
;     }
;     float tot = (sa[0] + sa[1]) + (sb[0] + sb[1]);
;     if (i & 1) tot += Amat[i * 64 + i - 1] * c2[(i - 1) >> 1][0];
;     c2[i >> 1][i & 1] -= tot;
;     __builtin_amdgcn_sched_barrier(0);
;   }
	v_mul_f32_dpp v58, v212, v0 quad_perm:[0,0,0,0] row_mask:0xf bank_mask:0xf
	v_mul_f32_dpp v59, v213, v1 quad_perm:[0,0,0,0] row_mask:0xf bank_mask:0xf
	v_mul_f32_dpp v62, v214, v6 quad_perm:[0,0,0,0] row_mask:0xf bank_mask:0xf
	v_mul_f32_dpp v63, v215, v7 quad_perm:[0,0,0,0] row_mask:0xf bank_mask:0xf
	v_fmac_f32_dpp v58, v212, v8 quad_perm:[1,1,1,1] row_mask:0xf bank_mask:0xf
	v_fmac_f32_dpp v59, v213, v9 quad_perm:[1,1,1,1] row_mask:0xf bank_mask:0xf
	v_fmac_f32_dpp v62, v214, v10 quad_perm:[1,1,1,1] row_mask:0xf bank_mask:0xf
	v_fmac_f32_dpp v63, v215, v11 quad_perm:[1,1,1,1] row_mask:0xf bank_mask:0xf
	v_fmac_f32_dpp v58, v212, v12 quad_perm:[2,2,2,2] row_mask:0xf bank_mask:0xf
	v_fmac_f32_dpp v59, v213, v13 quad_perm:[2,2,2,2] row_mask:0xf bank_mask:0xf
	v_fmac_f32_dpp v62, v214, v16 quad_perm:[2,2,2,2] row_mask:0xf bank_mask:0xf
	v_fmac_f32_dpp v63, v215, v17 quad_perm:[2,2,2,2] row_mask:0xf bank_mask:0xf
	v_fmac_f32_dpp v58, v212, v20 quad_perm:[3,3,3,3] row_mask:0xf bank_mask:0xf
	v_fmac_f32_dpp v59, v213, v21 quad_perm:[3,3,3,3] row_mask:0xf bank_mask:0xf
	v_fmac_f32_dpp v62, v214, v22 quad_perm:[3,3,3,3] row_mask:0xf bank_mask:0xf
	v_fmac_f32_dpp v63, v215, v23 quad_perm:[3,3,3,3] row_mask:0xf bank_mask:0xf
	v_fmac_f32_dpp v58, v216, v24 quad_perm:[0,0,0,0] row_mask:0xf bank_mask:0xf
	v_fmac_f32_dpp v59, v217, v25 quad_perm:[0,0,0,0] row_mask:0xf bank_mask:0xf
	v_fmac_f32_dpp v62, v218, v26 quad_perm:[0,0,0,0] row_mask:0xf bank_mask:0xf
	v_fmac_f32_dpp v63, v219, v27 quad_perm:[0,0,0,0] row_mask:0xf bank_mask:0xf
	v_fmac_f32_dpp v58, v216, v36 quad_perm:[1,1,1,1] row_mask:0xf bank_mask:0xf
	v_fmac_f32_dpp v59, v217, v37 quad_perm:[1,1,1,1] row_mask:0xf bank_mask:0xf
	v_fmac_f32_dpp v62, v218, v38 quad_perm:[1,1,1,1] row_mask:0xf bank_mask:0xf
	v_fmac_f32_dpp v63, v219, v39 quad_perm:[1,1,1,1] row_mask:0xf bank_mask:0xf
	v_fmac_f32_dpp v58, v216, v42 quad_perm:[2,2,2,2] row_mask:0xf bank_mask:0xf
	v_fmac_f32_dpp v59, v217, v43 quad_perm:[2,2,2,2] row_mask:0xf bank_mask:0xf
	v_fmac_f32_dpp v62, v218, v46 quad_perm:[2,2,2,2] row_mask:0xf bank_mask:0xf
	v_fmac_f32_dpp v63, v219, v47 quad_perm:[2,2,2,2] row_mask:0xf bank_mask:0xf
	v_fmac_f32_dpp v58, v216, v50 quad_perm:[3,3,3,3] row_mask:0xf bank_mask:0xf
	v_fmac_f32_dpp v59, v217, v51 quad_perm:[3,3,3,3] row_mask:0xf bank_mask:0xf
	v_fmac_f32_dpp v62, v218, v54 quad_perm:[3,3,3,3] row_mask:0xf bank_mask:0xf
	v_fmac_f32_dpp v63, v219, v55 quad_perm:[3,3,3,3] row_mask:0xf bank_mask:0xf
	v_fmac_f32_dpp v58, v220, v56 quad_perm:[0,0,0,0] row_mask:0xf bank_mask:0xf
	v_fmac_f32_dpp v59, v221, v57 quad_perm:[0,0,0,0] row_mask:0xf bank_mask:0xf
	v_fmac_f32_dpp v62, v222, v60 quad_perm:[0,0,0,0] row_mask:0xf bank_mask:0xf
	v_fmac_f32_dpp v63, v223, v61 quad_perm:[0,0,0,0] row_mask:0xf bank_mask:0xf
	v_fmac_f32_dpp v58, v220, v64 quad_perm:[1,1,1,1] row_mask:0xf bank_mask:0xf
	v_fmac_f32_dpp v59, v221, v65 quad_perm:[1,1,1,1] row_mask:0xf bank_mask:0xf
	v_fmac_f32_dpp v62, v222, v68 quad_perm:[1,1,1,1] row_mask:0xf bank_mask:0xf
	v_fmac_f32_dpp v63, v223, v69 quad_perm:[1,1,1,1] row_mask:0xf bank_mask:0xf
	v_fmac_f32_dpp v58, v220, v70 quad_perm:[2,2,2,2] row_mask:0xf bank_mask:0xf
	v_fmac_f32_dpp v59, v221, v71 quad_perm:[2,2,2,2] row_mask:0xf bank_mask:0xf
	v_fmac_f32_dpp v62, v222, v74 quad_perm:[2,2,2,2] row_mask:0xf bank_mask:0xf
	v_fmac_f32_dpp v63, v223, v75 quad_perm:[2,2,2,2] row_mask:0xf bank_mask:0xf
	v_fmac_f32_dpp v58, v220, v78 quad_perm:[3,3,3,3] row_mask:0xf bank_mask:0xf
	v_fmac_f32_dpp v59, v221, v79 quad_perm:[3,3,3,3] row_mask:0xf bank_mask:0xf
	v_fmac_f32_dpp v62, v222, v76 quad_perm:[3,3,3,3] row_mask:0xf bank_mask:0xf
	v_fmac_f32_dpp v63, v223, v77 quad_perm:[3,3,3,3] row_mask:0xf bank_mask:0xf
	v_fmac_f32_dpp v58, v224, v72 quad_perm:[0,0,0,0] row_mask:0xf bank_mask:0xf
	v_fmac_f32_dpp v59, v225, v73 quad_perm:[0,0,0,0] row_mask:0xf bank_mask:0xf
	v_fmac_f32_dpp v62, v226, v66 quad_perm:[0,0,0,0] row_mask:0xf bank_mask:0xf
	v_fmac_f32_dpp v63, v227, v67 quad_perm:[0,0,0,0] row_mask:0xf bank_mask:0xf
	v_fmac_f32_dpp v58, v224, v48 quad_perm:[1,1,1,1] row_mask:0xf bank_mask:0xf
	v_fmac_f32_dpp v59, v225, v49 quad_perm:[1,1,1,1] row_mask:0xf bank_mask:0xf
	v_mov_b32_e32 v80, v62
	v_mov_b32_e32 v81, v58
	v_mov_b32_e32 v58, v63
	v_pk_add_f32 v[58:59], v[80:81], v[58:59]
	s_nop 0
	v_add_f32_e32 v19, v58, v59
	v_fmac_f32_dpp v19, v226, v40 quad_perm:[1,1,1,1] row_mask:0xf bank_mask:0xf
	v_sub_f32_e32 v41, v52, v19
	ds_read_b128 v[212:215], v228 offset:49408
	ds_read_b128 v[216:219], v228 offset:49472
	ds_read_b128 v[220:223], v228 offset:49536
	ds_read_b128 v[224:227], v228 offset:49600
	s_waitcnt lgkmcnt(4)
; DI void gdn_pre(const Params& p, int ch, char* smem) {
;     ...
; #pragma unroll
;   for (int i = 1; i < 64; ++i) {
;     f32x2 sa = {0.f, 0.f}, sb = {0.f, 0.f};
;     const f32x2* arow = (const f32x2*)(Amat + i * 64);
; #pragma unroll
;     for (int k = 0; k < (i >> 1); ++k) {
;       const f32x2 a2 = arow[k];
;       if (k & 1) sb = __builtin_elementwise_fma(a2, c2[k], sb);
;       else sa = __builtin_elementwise_fma(a2, c2[k], sa);
;     }
;     float tot = (sa[0] + sa[1]) + (sb[0] + sb[1]);
;     if (i & 1) tot += Amat[i * 64 + i - 1] * c2[(i - 1) >> 1][0];
;     c2[i >> 1][i & 1] -= tot;
;     __builtin_amdgcn_sched_barrier(0);
;   }
	v_mul_f32_dpp v52, v196, v0 quad_perm:[0,0,0,0] row_mask:0xf bank_mask:0xf
	v_mul_f32_dpp v53, v197, v1 quad_perm:[0,0,0,0] row_mask:0xf bank_mask:0xf
	v_mul_f32_dpp v58, v198, v6 quad_perm:[0,0,0,0] row_mask:0xf bank_mask:0xf
	v_mul_f32_dpp v59, v199, v7 quad_perm:[0,0,0,0] row_mask:0xf bank_mask:0xf
	v_fmac_f32_dpp v52, v196, v8 quad_perm:[1,1,1,1] row_mask:0xf bank_mask:0xf
	v_fmac_f32_dpp v53, v197, v9 quad_perm:[1,1,1,1] row_mask:0xf bank_mask:0xf
	v_fmac_f32_dpp v58, v198, v10 quad_perm:[1,1,1,1] row_mask:0xf bank_mask:0xf
	v_fmac_f32_dpp v59, v199, v11 quad_perm:[1,1,1,1] row_mask:0xf bank_mask:0xf
	v_fmac_f32_dpp v52, v196, v12 quad_perm:[2,2,2,2] row_mask:0xf bank_mask:0xf
	v_fmac_f32_dpp v53, v197, v13 quad_perm:[2,2,2,2] row_mask:0xf bank_mask:0xf
	v_fmac_f32_dpp v58, v198, v16 quad_perm:[2,2,2,2] row_mask:0xf bank_mask:0xf
	v_fmac_f32_dpp v59, v199, v17 quad_perm:[2,2,2,2] row_mask:0xf bank_mask:0xf
	v_fmac_f32_dpp v52, v196, v20 quad_perm:[3,3,3,3] row_mask:0xf bank_mask:0xf
	v_fmac_f32_dpp v53, v197, v21 quad_perm:[3,3,3,3] row_mask:0xf bank_mask:0xf
	v_fmac_f32_dpp v58, v198, v22 quad_perm:[3,3,3,3] row_mask:0xf bank_mask:0xf
	v_fmac_f32_dpp v59, v199, v23 quad_perm:[3,3,3,3] row_mask:0xf bank_mask:0xf
	v_fmac_f32_dpp v52, v200, v24 quad_perm:[0,0,0,0] row_mask:0xf bank_mask:0xf
	v_fmac_f32_dpp v53, v201, v25 quad_perm:[0,0,0,0] row_mask:0xf bank_mask:0xf
	v_fmac_f32_dpp v58, v202, v26 quad_perm:[0,0,0,0] row_mask:0xf bank_mask:0xf
	v_fmac_f32_dpp v59, v203, v27 quad_perm:[0,0,0,0] row_mask:0xf bank_mask:0xf
	v_fmac_f32_dpp v52, v200, v36 quad_perm:[1,1,1,1] row_mask:0xf bank_mask:0xf
	v_fmac_f32_dpp v53, v201, v37 quad_perm:[1,1,1,1] row_mask:0xf bank_mask:0xf
	v_fmac_f32_dpp v58, v202, v38 quad_perm:[1,1,1,1] row_mask:0xf bank_mask:0xf
	v_fmac_f32_dpp v59, v203, v39 quad_perm:[1,1,1,1] row_mask:0xf bank_mask:0xf
	v_fmac_f32_dpp v52, v200, v42 quad_perm:[2,2,2,2] row_mask:0xf bank_mask:0xf
	v_fmac_f32_dpp v53, v201, v43 quad_perm:[2,2,2,2] row_mask:0xf bank_mask:0xf
	v_fmac_f32_dpp v58, v202, v46 quad_perm:[2,2,2,2] row_mask:0xf bank_mask:0xf
	v_fmac_f32_dpp v59, v203, v47 quad_perm:[2,2,2,2] row_mask:0xf bank_mask:0xf
	v_fmac_f32_dpp v52, v200, v50 quad_perm:[3,3,3,3] row_mask:0xf bank_mask:0xf
	v_fmac_f32_dpp v53, v201, v51 quad_perm:[3,3,3,3] row_mask:0xf bank_mask:0xf
	v_fmac_f32_dpp v58, v202, v54 quad_perm:[3,3,3,3] row_mask:0xf bank_mask:0xf
	v_fmac_f32_dpp v59, v203, v55 quad_perm:[3,3,3,3] row_mask:0xf bank_mask:0xf
	v_fmac_f32_dpp v52, v204, v56 quad_perm:[0,0,0,0] row_mask:0xf bank_mask:0xf
	v_fmac_f32_dpp v53, v205, v57 quad_perm:[0,0,0,0] row_mask:0xf bank_mask:0xf
	v_fmac_f32_dpp v58, v206, v60 quad_perm:[0,0,0,0] row_mask:0xf bank_mask:0xf
	v_fmac_f32_dpp v59, v207, v61 quad_perm:[0,0,0,0] row_mask:0xf bank_mask:0xf
	v_fmac_f32_dpp v52, v204, v64 quad_perm:[1,1,1,1] row_mask:0xf bank_mask:0xf
	v_fmac_f32_dpp v53, v205, v65 quad_perm:[1,1,1,1] row_mask:0xf bank_mask:0xf
	v_fmac_f32_dpp v58, v206, v68 quad_perm:[1,1,1,1] row_mask:0xf bank_mask:0xf
	v_fmac_f32_dpp v59, v207, v69 quad_perm:[1,1,1,1] row_mask:0xf bank_mask:0xf
	v_fmac_f32_dpp v52, v204, v70 quad_perm:[2,2,2,2] row_mask:0xf bank_mask:0xf
	v_fmac_f32_dpp v53, v205, v71 quad_perm:[2,2,2,2] row_mask:0xf bank_mask:0xf
	v_fmac_f32_dpp v58, v206, v74 quad_perm:[2,2,2,2] row_mask:0xf bank_mask:0xf
	v_fmac_f32_dpp v59, v207, v75 quad_perm:[2,2,2,2] row_mask:0xf bank_mask:0xf
	v_fmac_f32_dpp v52, v204, v78 quad_perm:[3,3,3,3] row_mask:0xf bank_mask:0xf
	v_fmac_f32_dpp v53, v205, v79 quad_perm:[3,3,3,3] row_mask:0xf bank_mask:0xf
	v_fmac_f32_dpp v58, v206, v76 quad_perm:[3,3,3,3] row_mask:0xf bank_mask:0xf
	v_fmac_f32_dpp v59, v207, v77 quad_perm:[3,3,3,3] row_mask:0xf bank_mask:0xf
	v_fmac_f32_dpp v52, v208, v72 quad_perm:[0,0,0,0] row_mask:0xf bank_mask:0xf
	v_fmac_f32_dpp v53, v209, v73 quad_perm:[0,0,0,0] row_mask:0xf bank_mask:0xf
	v_fmac_f32_dpp v58, v210, v66 quad_perm:[0,0,0,0] row_mask:0xf bank_mask:0xf
	v_fmac_f32_dpp v59, v211, v67 quad_perm:[0,0,0,0] row_mask:0xf bank_mask:0xf
	v_fmac_f32_dpp v52, v208, v48 quad_perm:[1,1,1,1] row_mask:0xf bank_mask:0xf
	v_fmac_f32_dpp v53, v209, v49 quad_perm:[1,1,1,1] row_mask:0xf bank_mask:0xf
	v_fmac_f32_dpp v58, v210, v40 quad_perm:[1,1,1,1] row_mask:0xf bank_mask:0xf
	v_fmac_f32_dpp v59, v211, v41 quad_perm:[1,1,1,1] row_mask:0xf bank_mask:0xf
	v_mov_b32_e32 v62, v52
	v_mov_b32_e32 v63, v58
	v_mov_b32_e32 v58, v53
	v_pk_add_f32 v[52:53], v[62:63], v[58:59]
	s_nop 0
	v_pk_add_f32 v[52:53], v[52:53], v[52:53] op_sel:[0,1] op_sel_hi:[1,0]
	s_nop 0
	v_pk_add_f32 v[28:29], v[28:29], v[52:53] neg_lo:[0,1] neg_hi:[0,1]
	ds_read_b128 v[196:199], v228 offset:49664
	ds_read_b128 v[200:203], v228 offset:49728
	ds_read_b128 v[204:207], v228 offset:49792
	ds_read_b128 v[208:211], v228 offset:49856
	s_waitcnt lgkmcnt(4)
; DI void gdn_pre(const Params& p, int ch, char* smem) {
;     ...
; #pragma unroll
;   for (int i = 1; i < 64; ++i) {
;     f32x2 sa = {0.f, 0.f}, sb = {0.f, 0.f};
;     const f32x2* arow = (const f32x2*)(Amat + i * 64);
; #pragma unroll
;     for (int k = 0; k < (i >> 1); ++k) {
;       const f32x2 a2 = arow[k];
;       if (k & 1) sb = __builtin_elementwise_fma(a2, c2[k], sb);
;       else sa = __builtin_elementwise_fma(a2, c2[k], sa);
;     }
;     float tot = (sa[0] + sa[1]) + (sb[0] + sb[1]);
;     if (i & 1) tot += Amat[i * 64 + i - 1] * c2[(i - 1) >> 1][0];
;     c2[i >> 1][i & 1] -= tot;
;     __builtin_amdgcn_sched_barrier(0);
;   }
	v_mul_f32_dpp v52, v212, v0 quad_perm:[0,0,0,0] row_mask:0xf bank_mask:0xf
	v_mul_f32_dpp v53, v213, v1 quad_perm:[0,0,0,0] row_mask:0xf bank_mask:0xf
	v_mul_f32_dpp v58, v214, v6 quad_perm:[0,0,0,0] row_mask:0xf bank_mask:0xf
	v_mul_f32_dpp v59, v215, v7 quad_perm:[0,0,0,0] row_mask:0xf bank_mask:0xf
	v_fmac_f32_dpp v52, v212, v8 quad_perm:[1,1,1,1] row_mask:0xf bank_mask:0xf
	v_fmac_f32_dpp v53, v213, v9 quad_perm:[1,1,1,1] row_mask:0xf bank_mask:0xf
	v_fmac_f32_dpp v58, v214, v10 quad_perm:[1,1,1,1] row_mask:0xf bank_mask:0xf
	v_fmac_f32_dpp v59, v215, v11 quad_perm:[1,1,1,1] row_mask:0xf bank_mask:0xf
	v_fmac_f32_dpp v52, v212, v12 quad_perm:[2,2,2,2] row_mask:0xf bank_mask:0xf
	v_fmac_f32_dpp v53, v213, v13 quad_perm:[2,2,2,2] row_mask:0xf bank_mask:0xf
	v_fmac_f32_dpp v58, v214, v16 quad_perm:[2,2,2,2] row_mask:0xf bank_mask:0xf
	v_fmac_f32_dpp v59, v215, v17 quad_perm:[2,2,2,2] row_mask:0xf bank_mask:0xf
	v_fmac_f32_dpp v52, v212, v20 quad_perm:[3,3,3,3] row_mask:0xf bank_mask:0xf
	v_fmac_f32_dpp v53, v213, v21 quad_perm:[3,3,3,3] row_mask:0xf bank_mask:0xf
	v_fmac_f32_dpp v58, v214, v22 quad_perm:[3,3,3,3] row_mask:0xf bank_mask:0xf
	v_fmac_f32_dpp v59, v215, v23 quad_perm:[3,3,3,3] row_mask:0xf bank_mask:0xf
	v_fmac_f32_dpp v52, v216, v24 quad_perm:[0,0,0,0] row_mask:0xf bank_mask:0xf
	v_fmac_f32_dpp v53, v217, v25 quad_perm:[0,0,0,0] row_mask:0xf bank_mask:0xf
	v_fmac_f32_dpp v58, v218, v26 quad_perm:[0,0,0,0] row_mask:0xf bank_mask:0xf
	v_fmac_f32_dpp v59, v219, v27 quad_perm:[0,0,0,0] row_mask:0xf bank_mask:0xf
	v_fmac_f32_dpp v52, v216, v36 quad_perm:[1,1,1,1] row_mask:0xf bank_mask:0xf
	v_fmac_f32_dpp v53, v217, v37 quad_perm:[1,1,1,1] row_mask:0xf bank_mask:0xf
	v_fmac_f32_dpp v58, v218, v38 quad_perm:[1,1,1,1] row_mask:0xf bank_mask:0xf
	v_fmac_f32_dpp v59, v219, v39 quad_perm:[1,1,1,1] row_mask:0xf bank_mask:0xf
	v_fmac_f32_dpp v52, v216, v42 quad_perm:[2,2,2,2] row_mask:0xf bank_mask:0xf
	v_fmac_f32_dpp v53, v217, v43 quad_perm:[2,2,2,2] row_mask:0xf bank_mask:0xf
	v_fmac_f32_dpp v58, v218, v46 quad_perm:[2,2,2,2] row_mask:0xf bank_mask:0xf
	v_fmac_f32_dpp v59, v219, v47 quad_perm:[2,2,2,2] row_mask:0xf bank_mask:0xf
	v_fmac_f32_dpp v52, v216, v50 quad_perm:[3,3,3,3] row_mask:0xf bank_mask:0xf
	v_fmac_f32_dpp v53, v217, v51 quad_perm:[3,3,3,3] row_mask:0xf bank_mask:0xf
	v_fmac_f32_dpp v58, v218, v54 quad_perm:[3,3,3,3] row_mask:0xf bank_mask:0xf
	v_fmac_f32_dpp v59, v219, v55 quad_perm:[3,3,3,3] row_mask:0xf bank_mask:0xf
	v_fmac_f32_dpp v52, v220, v56 quad_perm:[0,0,0,0] row_mask:0xf bank_mask:0xf
	v_fmac_f32_dpp v53, v221, v57 quad_perm:[0,0,0,0] row_mask:0xf bank_mask:0xf
	v_fmac_f32_dpp v58, v222, v60 quad_perm:[0,0,0,0] row_mask:0xf bank_mask:0xf
	v_fmac_f32_dpp v59, v223, v61 quad_perm:[0,0,0,0] row_mask:0xf bank_mask:0xf
	v_fmac_f32_dpp v52, v220, v64 quad_perm:[1,1,1,1] row_mask:0xf bank_mask:0xf
	v_fmac_f32_dpp v53, v221, v65 quad_perm:[1,1,1,1] row_mask:0xf bank_mask:0xf
	v_fmac_f32_dpp v58, v222, v68 quad_perm:[1,1,1,1] row_mask:0xf bank_mask:0xf
	v_fmac_f32_dpp v59, v223, v69 quad_perm:[1,1,1,1] row_mask:0xf bank_mask:0xf
	v_fmac_f32_dpp v52, v220, v70 quad_perm:[2,2,2,2] row_mask:0xf bank_mask:0xf
	v_fmac_f32_dpp v53, v221, v71 quad_perm:[2,2,2,2] row_mask:0xf bank_mask:0xf
	v_fmac_f32_dpp v58, v222, v74 quad_perm:[2,2,2,2] row_mask:0xf bank_mask:0xf
	v_fmac_f32_dpp v59, v223, v75 quad_perm:[2,2,2,2] row_mask:0xf bank_mask:0xf
	v_fmac_f32_dpp v52, v220, v78 quad_perm:[3,3,3,3] row_mask:0xf bank_mask:0xf
	v_fmac_f32_dpp v53, v221, v79 quad_perm:[3,3,3,3] row_mask:0xf bank_mask:0xf
	v_fmac_f32_dpp v58, v222, v76 quad_perm:[3,3,3,3] row_mask:0xf bank_mask:0xf
	v_fmac_f32_dpp v59, v223, v77 quad_perm:[3,3,3,3] row_mask:0xf bank_mask:0xf
	v_fmac_f32_dpp v52, v224, v72 quad_perm:[0,0,0,0] row_mask:0xf bank_mask:0xf
	v_fmac_f32_dpp v53, v225, v73 quad_perm:[0,0,0,0] row_mask:0xf bank_mask:0xf
	v_fmac_f32_dpp v58, v226, v66 quad_perm:[0,0,0,0] row_mask:0xf bank_mask:0xf
	v_fmac_f32_dpp v59, v227, v67 quad_perm:[0,0,0,0] row_mask:0xf bank_mask:0xf
	v_fmac_f32_dpp v52, v224, v48 quad_perm:[1,1,1,1] row_mask:0xf bank_mask:0xf
	v_fmac_f32_dpp v53, v225, v49 quad_perm:[1,1,1,1] row_mask:0xf bank_mask:0xf
	v_fmac_f32_dpp v58, v226, v40 quad_perm:[1,1,1,1] row_mask:0xf bank_mask:0xf
	v_fmac_f32_dpp v59, v227, v41 quad_perm:[1,1,1,1] row_mask:0xf bank_mask:0xf
	v_mov_b32_e32 v62, v52
	v_mov_b32_e32 v63, v58
	v_mov_b32_e32 v58, v53
	v_pk_add_f32 v[52:53], v[62:63], v[58:59]
	s_nop 0
	v_add_f32_e32 v29, v52, v53
	v_fmac_f32_dpp v29, v224, v28 quad_perm:[2,2,2,2] row_mask:0xf bank_mask:0xf
	v_sub_f32_e32 v29, v44, v29
	ds_read_b128 v[212:215], v228 offset:49920
	ds_read_b128 v[216:219], v228 offset:49984
	ds_read_b128 v[220:223], v228 offset:50048
	ds_read_b128 v[224:227], v228 offset:50112
	s_waitcnt lgkmcnt(4)
; DI void gdn_pre(const Params& p, int ch, char* smem) {
;     ...
; #pragma unroll
;   for (int i = 1; i < 64; ++i) {
;     f32x2 sa = {0.f, 0.f}, sb = {0.f, 0.f};
;     const f32x2* arow = (const f32x2*)(Amat + i * 64);
; #pragma unroll
;     for (int k = 0; k < (i >> 1); ++k) {
;       const f32x2 a2 = arow[k];
;       if (k & 1) sb = __builtin_elementwise_fma(a2, c2[k], sb);
;       else sa = __builtin_elementwise_fma(a2, c2[k], sa);
;     }
;     float tot = (sa[0] + sa[1]) + (sb[0] + sb[1]);
;     if (i & 1) tot += Amat[i * 64 + i - 1] * c2[(i - 1) >> 1][0];
;     c2[i >> 1][i & 1] -= tot;
;     __builtin_amdgcn_sched_barrier(0);
;   }
	v_mul_f32_dpp v44, v196, v0 quad_perm:[0,0,0,0] row_mask:0xf bank_mask:0xf
	v_mul_f32_dpp v45, v197, v1 quad_perm:[0,0,0,0] row_mask:0xf bank_mask:0xf
	v_mul_f32_dpp v52, v198, v6 quad_perm:[0,0,0,0] row_mask:0xf bank_mask:0xf
	v_mul_f32_dpp v53, v199, v7 quad_perm:[0,0,0,0] row_mask:0xf bank_mask:0xf
	v_fmac_f32_dpp v44, v196, v8 quad_perm:[1,1,1,1] row_mask:0xf bank_mask:0xf
	v_fmac_f32_dpp v45, v197, v9 quad_perm:[1,1,1,1] row_mask:0xf bank_mask:0xf
	v_fmac_f32_dpp v52, v198, v10 quad_perm:[1,1,1,1] row_mask:0xf bank_mask:0xf
	v_fmac_f32_dpp v53, v199, v11 quad_perm:[1,1,1,1] row_mask:0xf bank_mask:0xf
	v_fmac_f32_dpp v44, v196, v12 quad_perm:[2,2,2,2] row_mask:0xf bank_mask:0xf
	v_fmac_f32_dpp v45, v197, v13 quad_perm:[2,2,2,2] row_mask:0xf bank_mask:0xf
	v_fmac_f32_dpp v52, v198, v16 quad_perm:[2,2,2,2] row_mask:0xf bank_mask:0xf
	v_fmac_f32_dpp v53, v199, v17 quad_perm:[2,2,2,2] row_mask:0xf bank_mask:0xf
	v_fmac_f32_dpp v44, v196, v20 quad_perm:[3,3,3,3] row_mask:0xf bank_mask:0xf
	v_fmac_f32_dpp v45, v197, v21 quad_perm:[3,3,3,3] row_mask:0xf bank_mask:0xf
	v_fmac_f32_dpp v52, v198, v22 quad_perm:[3,3,3,3] row_mask:0xf bank_mask:0xf
	v_fmac_f32_dpp v53, v199, v23 quad_perm:[3,3,3,3] row_mask:0xf bank_mask:0xf
	v_fmac_f32_dpp v44, v200, v24 quad_perm:[0,0,0,0] row_mask:0xf bank_mask:0xf
	v_fmac_f32_dpp v45, v201, v25 quad_perm:[0,0,0,0] row_mask:0xf bank_mask:0xf
	v_fmac_f32_dpp v52, v202, v26 quad_perm:[0,0,0,0] row_mask:0xf bank_mask:0xf
	v_fmac_f32_dpp v53, v203, v27 quad_perm:[0,0,0,0] row_mask:0xf bank_mask:0xf
	v_fmac_f32_dpp v44, v200, v36 quad_perm:[1,1,1,1] row_mask:0xf bank_mask:0xf
	v_fmac_f32_dpp v45, v201, v37 quad_perm:[1,1,1,1] row_mask:0xf bank_mask:0xf
	v_fmac_f32_dpp v52, v202, v38 quad_perm:[1,1,1,1] row_mask:0xf bank_mask:0xf
	v_fmac_f32_dpp v53, v203, v39 quad_perm:[1,1,1,1] row_mask:0xf bank_mask:0xf
	v_fmac_f32_dpp v44, v200, v42 quad_perm:[2,2,2,2] row_mask:0xf bank_mask:0xf
	v_fmac_f32_dpp v45, v201, v43 quad_perm:[2,2,2,2] row_mask:0xf bank_mask:0xf
	v_fmac_f32_dpp v52, v202, v46 quad_perm:[2,2,2,2] row_mask:0xf bank_mask:0xf
	v_fmac_f32_dpp v53, v203, v47 quad_perm:[2,2,2,2] row_mask:0xf bank_mask:0xf
	v_fmac_f32_dpp v44, v200, v50 quad_perm:[3,3,3,3] row_mask:0xf bank_mask:0xf
	v_fmac_f32_dpp v45, v201, v51 quad_perm:[3,3,3,3] row_mask:0xf bank_mask:0xf
	v_fmac_f32_dpp v52, v202, v54 quad_perm:[3,3,3,3] row_mask:0xf bank_mask:0xf
	v_fmac_f32_dpp v53, v203, v55 quad_perm:[3,3,3,3] row_mask:0xf bank_mask:0xf
	v_fmac_f32_dpp v44, v204, v56 quad_perm:[0,0,0,0] row_mask:0xf bank_mask:0xf
	v_fmac_f32_dpp v45, v205, v57 quad_perm:[0,0,0,0] row_mask:0xf bank_mask:0xf
	v_fmac_f32_dpp v52, v206, v60 quad_perm:[0,0,0,0] row_mask:0xf bank_mask:0xf
	v_fmac_f32_dpp v53, v207, v61 quad_perm:[0,0,0,0] row_mask:0xf bank_mask:0xf
	v_fmac_f32_dpp v44, v204, v64 quad_perm:[1,1,1,1] row_mask:0xf bank_mask:0xf
	v_fmac_f32_dpp v45, v205, v65 quad_perm:[1,1,1,1] row_mask:0xf bank_mask:0xf
	v_fmac_f32_dpp v52, v206, v68 quad_perm:[1,1,1,1] row_mask:0xf bank_mask:0xf
	v_fmac_f32_dpp v53, v207, v69 quad_perm:[1,1,1,1] row_mask:0xf bank_mask:0xf
	v_fmac_f32_dpp v44, v204, v70 quad_perm:[2,2,2,2] row_mask:0xf bank_mask:0xf
	v_fmac_f32_dpp v45, v205, v71 quad_perm:[2,2,2,2] row_mask:0xf bank_mask:0xf
	v_fmac_f32_dpp v52, v206, v74 quad_perm:[2,2,2,2] row_mask:0xf bank_mask:0xf
	v_fmac_f32_dpp v53, v207, v75 quad_perm:[2,2,2,2] row_mask:0xf bank_mask:0xf
	v_fmac_f32_dpp v44, v204, v78 quad_perm:[3,3,3,3] row_mask:0xf bank_mask:0xf
	v_fmac_f32_dpp v45, v205, v79 quad_perm:[3,3,3,3] row_mask:0xf bank_mask:0xf
	v_fmac_f32_dpp v52, v206, v76 quad_perm:[3,3,3,3] row_mask:0xf bank_mask:0xf
	v_fmac_f32_dpp v53, v207, v77 quad_perm:[3,3,3,3] row_mask:0xf bank_mask:0xf
	v_fmac_f32_dpp v44, v208, v72 quad_perm:[0,0,0,0] row_mask:0xf bank_mask:0xf
	v_fmac_f32_dpp v45, v209, v73 quad_perm:[0,0,0,0] row_mask:0xf bank_mask:0xf
	v_fmac_f32_dpp v52, v210, v66 quad_perm:[0,0,0,0] row_mask:0xf bank_mask:0xf
	v_fmac_f32_dpp v53, v211, v67 quad_perm:[0,0,0,0] row_mask:0xf bank_mask:0xf
	v_fmac_f32_dpp v44, v208, v48 quad_perm:[1,1,1,1] row_mask:0xf bank_mask:0xf
	v_fmac_f32_dpp v45, v209, v49 quad_perm:[1,1,1,1] row_mask:0xf bank_mask:0xf
	v_fmac_f32_dpp v52, v210, v40 quad_perm:[1,1,1,1] row_mask:0xf bank_mask:0xf
	v_fmac_f32_dpp v53, v211, v41 quad_perm:[1,1,1,1] row_mask:0xf bank_mask:0xf
	v_fmac_f32_dpp v44, v208, v28 quad_perm:[2,2,2,2] row_mask:0xf bank_mask:0xf
	v_fmac_f32_dpp v45, v209, v29 quad_perm:[2,2,2,2] row_mask:0xf bank_mask:0xf
	v_mov_b32_e32 v58, v52
	v_mov_b32_e32 v59, v44
	v_mov_b32_e32 v44, v53
	v_pk_add_f32 v[44:45], v[58:59], v[44:45]
	s_nop 0
	v_pk_add_f32 v[44:45], v[44:45], v[44:45] op_sel:[0,1] op_sel_hi:[1,0]
	s_nop 0
	v_pk_add_f32 v[14:15], v[14:15], v[44:45] neg_lo:[0,1] neg_hi:[0,1]
	ds_read_b128 v[196:199], v228 offset:50176
	ds_read_b128 v[200:203], v228 offset:50240
	ds_read_b128 v[204:207], v228 offset:50304
	ds_read_b128 v[208:211], v228 offset:50368
	s_waitcnt lgkmcnt(4)
; DI void gdn_pre(const Params& p, int ch, char* smem) {
;     ...
; #pragma unroll
;   for (int i = 1; i < 64; ++i) {
;     f32x2 sa = {0.f, 0.f}, sb = {0.f, 0.f};
;     const f32x2* arow = (const f32x2*)(Amat + i * 64);
; #pragma unroll
;     for (int k = 0; k < (i >> 1); ++k) {
;       const f32x2 a2 = arow[k];
;       if (k & 1) sb = __builtin_elementwise_fma(a2, c2[k], sb);
;       else sa = __builtin_elementwise_fma(a2, c2[k], sa);
;     }
;     float tot = (sa[0] + sa[1]) + (sb[0] + sb[1]);
;     if (i & 1) tot += Amat[i * 64 + i - 1] * c2[(i - 1) >> 1][0];
;     c2[i >> 1][i & 1] -= tot;
;     __builtin_amdgcn_sched_barrier(0);
;   }
	v_mul_f32_dpp v44, v212, v0 quad_perm:[0,0,0,0] row_mask:0xf bank_mask:0xf
	v_mul_f32_dpp v45, v213, v1 quad_perm:[0,0,0,0] row_mask:0xf bank_mask:0xf
	v_mul_f32_dpp v52, v214, v6 quad_perm:[0,0,0,0] row_mask:0xf bank_mask:0xf
	v_mul_f32_dpp v53, v215, v7 quad_perm:[0,0,0,0] row_mask:0xf bank_mask:0xf
	v_fmac_f32_dpp v44, v212, v8 quad_perm:[1,1,1,1] row_mask:0xf bank_mask:0xf
	v_fmac_f32_dpp v45, v213, v9 quad_perm:[1,1,1,1] row_mask:0xf bank_mask:0xf
	v_fmac_f32_dpp v52, v214, v10 quad_perm:[1,1,1,1] row_mask:0xf bank_mask:0xf
	v_fmac_f32_dpp v53, v215, v11 quad_perm:[1,1,1,1] row_mask:0xf bank_mask:0xf
	v_fmac_f32_dpp v44, v212, v12 quad_perm:[2,2,2,2] row_mask:0xf bank_mask:0xf
	v_fmac_f32_dpp v45, v213, v13 quad_perm:[2,2,2,2] row_mask:0xf bank_mask:0xf
	v_fmac_f32_dpp v52, v214, v16 quad_perm:[2,2,2,2] row_mask:0xf bank_mask:0xf
	v_fmac_f32_dpp v53, v215, v17 quad_perm:[2,2,2,2] row_mask:0xf bank_mask:0xf
	v_fmac_f32_dpp v44, v212, v20 quad_perm:[3,3,3,3] row_mask:0xf bank_mask:0xf
	v_fmac_f32_dpp v45, v213, v21 quad_perm:[3,3,3,3] row_mask:0xf bank_mask:0xf
	v_fmac_f32_dpp v52, v214, v22 quad_perm:[3,3,3,3] row_mask:0xf bank_mask:0xf
	v_fmac_f32_dpp v53, v215, v23 quad_perm:[3,3,3,3] row_mask:0xf bank_mask:0xf
	v_fmac_f32_dpp v44, v216, v24 quad_perm:[0,0,0,0] row_mask:0xf bank_mask:0xf
	v_fmac_f32_dpp v45, v217, v25 quad_perm:[0,0,0,0] row_mask:0xf bank_mask:0xf
	v_fmac_f32_dpp v52, v218, v26 quad_perm:[0,0,0,0] row_mask:0xf bank_mask:0xf
	v_fmac_f32_dpp v53, v219, v27 quad_perm:[0,0,0,0] row_mask:0xf bank_mask:0xf
	v_fmac_f32_dpp v44, v216, v36 quad_perm:[1,1,1,1] row_mask:0xf bank_mask:0xf
	v_fmac_f32_dpp v45, v217, v37 quad_perm:[1,1,1,1] row_mask:0xf bank_mask:0xf
	v_fmac_f32_dpp v52, v218, v38 quad_perm:[1,1,1,1] row_mask:0xf bank_mask:0xf
	v_fmac_f32_dpp v53, v219, v39 quad_perm:[1,1,1,1] row_mask:0xf bank_mask:0xf
	v_fmac_f32_dpp v44, v216, v42 quad_perm:[2,2,2,2] row_mask:0xf bank_mask:0xf
	v_fmac_f32_dpp v45, v217, v43 quad_perm:[2,2,2,2] row_mask:0xf bank_mask:0xf
	v_fmac_f32_dpp v52, v218, v46 quad_perm:[2,2,2,2] row_mask:0xf bank_mask:0xf
	v_fmac_f32_dpp v53, v219, v47 quad_perm:[2,2,2,2] row_mask:0xf bank_mask:0xf
	v_fmac_f32_dpp v44, v216, v50 quad_perm:[3,3,3,3] row_mask:0xf bank_mask:0xf
	v_fmac_f32_dpp v45, v217, v51 quad_perm:[3,3,3,3] row_mask:0xf bank_mask:0xf
	v_fmac_f32_dpp v52, v218, v54 quad_perm:[3,3,3,3] row_mask:0xf bank_mask:0xf
	v_fmac_f32_dpp v53, v219, v55 quad_perm:[3,3,3,3] row_mask:0xf bank_mask:0xf
	v_fmac_f32_dpp v44, v220, v56 quad_perm:[0,0,0,0] row_mask:0xf bank_mask:0xf
	v_fmac_f32_dpp v45, v221, v57 quad_perm:[0,0,0,0] row_mask:0xf bank_mask:0xf
	v_fmac_f32_dpp v52, v222, v60 quad_perm:[0,0,0,0] row_mask:0xf bank_mask:0xf
	v_fmac_f32_dpp v53, v223, v61 quad_perm:[0,0,0,0] row_mask:0xf bank_mask:0xf
	v_fmac_f32_dpp v44, v220, v64 quad_perm:[1,1,1,1] row_mask:0xf bank_mask:0xf
	v_fmac_f32_dpp v45, v221, v65 quad_perm:[1,1,1,1] row_mask:0xf bank_mask:0xf
	v_fmac_f32_dpp v52, v222, v68 quad_perm:[1,1,1,1] row_mask:0xf bank_mask:0xf
	v_fmac_f32_dpp v53, v223, v69 quad_perm:[1,1,1,1] row_mask:0xf bank_mask:0xf
	v_fmac_f32_dpp v44, v220, v70 quad_perm:[2,2,2,2] row_mask:0xf bank_mask:0xf
	v_fmac_f32_dpp v45, v221, v71 quad_perm:[2,2,2,2] row_mask:0xf bank_mask:0xf
	v_fmac_f32_dpp v52, v222, v74 quad_perm:[2,2,2,2] row_mask:0xf bank_mask:0xf
	v_fmac_f32_dpp v53, v223, v75 quad_perm:[2,2,2,2] row_mask:0xf bank_mask:0xf
	v_fmac_f32_dpp v44, v220, v78 quad_perm:[3,3,3,3] row_mask:0xf bank_mask:0xf
	v_fmac_f32_dpp v45, v221, v79 quad_perm:[3,3,3,3] row_mask:0xf bank_mask:0xf
	v_fmac_f32_dpp v52, v222, v76 quad_perm:[3,3,3,3] row_mask:0xf bank_mask:0xf
	v_fmac_f32_dpp v53, v223, v77 quad_perm:[3,3,3,3] row_mask:0xf bank_mask:0xf
	v_fmac_f32_dpp v44, v224, v72 quad_perm:[0,0,0,0] row_mask:0xf bank_mask:0xf
	v_fmac_f32_dpp v45, v225, v73 quad_perm:[0,0,0,0] row_mask:0xf bank_mask:0xf
	v_fmac_f32_dpp v52, v226, v66 quad_perm:[0,0,0,0] row_mask:0xf bank_mask:0xf
	v_fmac_f32_dpp v53, v227, v67 quad_perm:[0,0,0,0] row_mask:0xf bank_mask:0xf
	v_fmac_f32_dpp v44, v224, v48 quad_perm:[1,1,1,1] row_mask:0xf bank_mask:0xf
	v_fmac_f32_dpp v45, v225, v49 quad_perm:[1,1,1,1] row_mask:0xf bank_mask:0xf
	v_fmac_f32_dpp v52, v226, v40 quad_perm:[1,1,1,1] row_mask:0xf bank_mask:0xf
	v_fmac_f32_dpp v53, v227, v41 quad_perm:[1,1,1,1] row_mask:0xf bank_mask:0xf
	v_fmac_f32_dpp v44, v224, v28 quad_perm:[2,2,2,2] row_mask:0xf bank_mask:0xf
	v_fmac_f32_dpp v45, v225, v29 quad_perm:[2,2,2,2] row_mask:0xf bank_mask:0xf
	v_mov_b32_e32 v58, v52
	v_mov_b32_e32 v59, v44
	v_mov_b32_e32 v44, v53
	v_pk_add_f32 v[44:45], v[58:59], v[44:45]
	s_nop 0
	v_add_f32_e32 v15, v44, v45
	v_fmac_f32_dpp v15, v226, v14 quad_perm:[2,2,2,2] row_mask:0xf bank_mask:0xf
	v_sub_f32_e32 v15, v30, v15
	ds_read_b128 v[212:215], v228 offset:50432
	ds_read_b128 v[216:219], v228 offset:50496
	ds_read_b128 v[220:223], v228 offset:50560
	ds_read_b128 v[224:227], v228 offset:50624
	s_waitcnt lgkmcnt(4)
; DI void gdn_pre(const Params& p, int ch, char* smem) {
;     ...
; #pragma unroll
;   for (int i = 1; i < 64; ++i) {
;     f32x2 sa = {0.f, 0.f}, sb = {0.f, 0.f};
;     const f32x2* arow = (const f32x2*)(Amat + i * 64);
; #pragma unroll
;     for (int k = 0; k < (i >> 1); ++k) {
;       const f32x2 a2 = arow[k];
;       if (k & 1) sb = __builtin_elementwise_fma(a2, c2[k], sb);
;       else sa = __builtin_elementwise_fma(a2, c2[k], sa);
;     }
;     float tot = (sa[0] + sa[1]) + (sb[0] + sb[1]);
;     if (i & 1) tot += Amat[i * 64 + i - 1] * c2[(i - 1) >> 1][0];
;     c2[i >> 1][i & 1] -= tot;
;     __builtin_amdgcn_sched_barrier(0);
;   }
	v_mul_f32_dpp v30, v196, v0 quad_perm:[0,0,0,0] row_mask:0xf bank_mask:0xf
	v_mul_f32_dpp v31, v197, v1 quad_perm:[0,0,0,0] row_mask:0xf bank_mask:0xf
	v_mul_f32_dpp v44, v198, v6 quad_perm:[0,0,0,0] row_mask:0xf bank_mask:0xf
	v_mul_f32_dpp v45, v199, v7 quad_perm:[0,0,0,0] row_mask:0xf bank_mask:0xf
	v_fmac_f32_dpp v30, v196, v8 quad_perm:[1,1,1,1] row_mask:0xf bank_mask:0xf
	v_fmac_f32_dpp v31, v197, v9 quad_perm:[1,1,1,1] row_mask:0xf bank_mask:0xf
	v_fmac_f32_dpp v44, v198, v10 quad_perm:[1,1,1,1] row_mask:0xf bank_mask:0xf
	v_fmac_f32_dpp v45, v199, v11 quad_perm:[1,1,1,1] row_mask:0xf bank_mask:0xf
	v_fmac_f32_dpp v30, v196, v12 quad_perm:[2,2,2,2] row_mask:0xf bank_mask:0xf
	v_fmac_f32_dpp v31, v197, v13 quad_perm:[2,2,2,2] row_mask:0xf bank_mask:0xf
	v_fmac_f32_dpp v44, v198, v16 quad_perm:[2,2,2,2] row_mask:0xf bank_mask:0xf
	v_fmac_f32_dpp v45, v199, v17 quad_perm:[2,2,2,2] row_mask:0xf bank_mask:0xf
	v_fmac_f32_dpp v30, v196, v20 quad_perm:[3,3,3,3] row_mask:0xf bank_mask:0xf
	v_fmac_f32_dpp v31, v197, v21 quad_perm:[3,3,3,3] row_mask:0xf bank_mask:0xf
	v_fmac_f32_dpp v44, v198, v22 quad_perm:[3,3,3,3] row_mask:0xf bank_mask:0xf
	v_fmac_f32_dpp v45, v199, v23 quad_perm:[3,3,3,3] row_mask:0xf bank_mask:0xf
	v_fmac_f32_dpp v30, v200, v24 quad_perm:[0,0,0,0] row_mask:0xf bank_mask:0xf
	v_fmac_f32_dpp v31, v201, v25 quad_perm:[0,0,0,0] row_mask:0xf bank_mask:0xf
	v_fmac_f32_dpp v44, v202, v26 quad_perm:[0,0,0,0] row_mask:0xf bank_mask:0xf
	v_fmac_f32_dpp v45, v203, v27 quad_perm:[0,0,0,0] row_mask:0xf bank_mask:0xf
	v_fmac_f32_dpp v30, v200, v36 quad_perm:[1,1,1,1] row_mask:0xf bank_mask:0xf
	v_fmac_f32_dpp v31, v201, v37 quad_perm:[1,1,1,1] row_mask:0xf bank_mask:0xf
	v_fmac_f32_dpp v44, v202, v38 quad_perm:[1,1,1,1] row_mask:0xf bank_mask:0xf
	v_fmac_f32_dpp v45, v203, v39 quad_perm:[1,1,1,1] row_mask:0xf bank_mask:0xf
	v_fmac_f32_dpp v30, v200, v42 quad_perm:[2,2,2,2] row_mask:0xf bank_mask:0xf
	v_fmac_f32_dpp v31, v201, v43 quad_perm:[2,2,2,2] row_mask:0xf bank_mask:0xf
	v_fmac_f32_dpp v44, v202, v46 quad_perm:[2,2,2,2] row_mask:0xf bank_mask:0xf
	v_fmac_f32_dpp v45, v203, v47 quad_perm:[2,2,2,2] row_mask:0xf bank_mask:0xf
	v_fmac_f32_dpp v30, v200, v50 quad_perm:[3,3,3,3] row_mask:0xf bank_mask:0xf
	v_fmac_f32_dpp v31, v201, v51 quad_perm:[3,3,3,3] row_mask:0xf bank_mask:0xf
	v_fmac_f32_dpp v44, v202, v54 quad_perm:[3,3,3,3] row_mask:0xf bank_mask:0xf
	v_fmac_f32_dpp v45, v203, v55 quad_perm:[3,3,3,3] row_mask:0xf bank_mask:0xf
	v_fmac_f32_dpp v30, v204, v56 quad_perm:[0,0,0,0] row_mask:0xf bank_mask:0xf
	v_fmac_f32_dpp v31, v205, v57 quad_perm:[0,0,0,0] row_mask:0xf bank_mask:0xf
	v_fmac_f32_dpp v44, v206, v60 quad_perm:[0,0,0,0] row_mask:0xf bank_mask:0xf
	v_fmac_f32_dpp v45, v207, v61 quad_perm:[0,0,0,0] row_mask:0xf bank_mask:0xf
	v_fmac_f32_dpp v30, v204, v64 quad_perm:[1,1,1,1] row_mask:0xf bank_mask:0xf
	v_fmac_f32_dpp v31, v205, v65 quad_perm:[1,1,1,1] row_mask:0xf bank_mask:0xf
	v_fmac_f32_dpp v44, v206, v68 quad_perm:[1,1,1,1] row_mask:0xf bank_mask:0xf
	v_fmac_f32_dpp v45, v207, v69 quad_perm:[1,1,1,1] row_mask:0xf bank_mask:0xf
	v_fmac_f32_dpp v30, v204, v70 quad_perm:[2,2,2,2] row_mask:0xf bank_mask:0xf
	v_fmac_f32_dpp v31, v205, v71 quad_perm:[2,2,2,2] row_mask:0xf bank_mask:0xf
	v_fmac_f32_dpp v44, v206, v74 quad_perm:[2,2,2,2] row_mask:0xf bank_mask:0xf
	v_fmac_f32_dpp v45, v207, v75 quad_perm:[2,2,2,2] row_mask:0xf bank_mask:0xf
	v_fmac_f32_dpp v30, v204, v78 quad_perm:[3,3,3,3] row_mask:0xf bank_mask:0xf
	v_fmac_f32_dpp v31, v205, v79 quad_perm:[3,3,3,3] row_mask:0xf bank_mask:0xf
	v_fmac_f32_dpp v44, v206, v76 quad_perm:[3,3,3,3] row_mask:0xf bank_mask:0xf
	v_fmac_f32_dpp v45, v207, v77 quad_perm:[3,3,3,3] row_mask:0xf bank_mask:0xf
	v_fmac_f32_dpp v30, v208, v72 quad_perm:[0,0,0,0] row_mask:0xf bank_mask:0xf
	v_fmac_f32_dpp v31, v209, v73 quad_perm:[0,0,0,0] row_mask:0xf bank_mask:0xf
	v_fmac_f32_dpp v44, v210, v66 quad_perm:[0,0,0,0] row_mask:0xf bank_mask:0xf
	v_fmac_f32_dpp v45, v211, v67 quad_perm:[0,0,0,0] row_mask:0xf bank_mask:0xf
	v_fmac_f32_dpp v30, v208, v48 quad_perm:[1,1,1,1] row_mask:0xf bank_mask:0xf
	v_fmac_f32_dpp v31, v209, v49 quad_perm:[1,1,1,1] row_mask:0xf bank_mask:0xf
	v_fmac_f32_dpp v44, v210, v40 quad_perm:[1,1,1,1] row_mask:0xf bank_mask:0xf
	v_fmac_f32_dpp v45, v211, v41 quad_perm:[1,1,1,1] row_mask:0xf bank_mask:0xf
	v_fmac_f32_dpp v30, v208, v28 quad_perm:[2,2,2,2] row_mask:0xf bank_mask:0xf
	v_fmac_f32_dpp v31, v209, v29 quad_perm:[2,2,2,2] row_mask:0xf bank_mask:0xf
	v_fmac_f32_dpp v44, v210, v14 quad_perm:[2,2,2,2] row_mask:0xf bank_mask:0xf
	v_fmac_f32_dpp v45, v211, v15 quad_perm:[2,2,2,2] row_mask:0xf bank_mask:0xf
	v_mov_b32_e32 v52, v30
	v_mov_b32_e32 v53, v44
	v_mov_b32_e32 v44, v31
	v_pk_add_f32 v[30:31], v[52:53], v[44:45]
	s_nop 0
	v_pk_add_f32 v[30:31], v[30:31], v[30:31] op_sel:[0,1] op_sel_hi:[1,0]
	s_nop 0
	v_pk_add_f32 v[4:5], v[4:5], v[30:31] neg_lo:[0,1] neg_hi:[0,1]
	ds_read_b128 v[196:199], v228 offset:50688
	ds_read_b128 v[200:203], v228 offset:50752
	ds_read_b128 v[204:207], v228 offset:50816
	ds_read_b128 v[208:211], v228 offset:50880
	s_waitcnt lgkmcnt(4)
; DI void gdn_pre(const Params& p, int ch, char* smem) {
;     ...
; #pragma unroll
;   for (int i = 1; i < 64; ++i) {
;     f32x2 sa = {0.f, 0.f}, sb = {0.f, 0.f};
;     const f32x2* arow = (const f32x2*)(Amat + i * 64);
; #pragma unroll
;     for (int k = 0; k < (i >> 1); ++k) {
;       const f32x2 a2 = arow[k];
;       if (k & 1) sb = __builtin_elementwise_fma(a2, c2[k], sb);
;       else sa = __builtin_elementwise_fma(a2, c2[k], sa);
;     }
;     float tot = (sa[0] + sa[1]) + (sb[0] + sb[1]);
;     if (i & 1) tot += Amat[i * 64 + i - 1] * c2[(i - 1) >> 1][0];
;     c2[i >> 1][i & 1] -= tot;
;     __builtin_amdgcn_sched_barrier(0);
;   }
	v_mul_f32_dpp v30, v212, v0 quad_perm:[0,0,0,0] row_mask:0xf bank_mask:0xf
	v_mul_f32_dpp v31, v213, v1 quad_perm:[0,0,0,0] row_mask:0xf bank_mask:0xf
	v_mul_f32_dpp v44, v214, v6 quad_perm:[0,0,0,0] row_mask:0xf bank_mask:0xf
	v_mul_f32_dpp v45, v215, v7 quad_perm:[0,0,0,0] row_mask:0xf bank_mask:0xf
	v_fmac_f32_dpp v30, v212, v8 quad_perm:[1,1,1,1] row_mask:0xf bank_mask:0xf
	v_fmac_f32_dpp v31, v213, v9 quad_perm:[1,1,1,1] row_mask:0xf bank_mask:0xf
	v_fmac_f32_dpp v44, v214, v10 quad_perm:[1,1,1,1] row_mask:0xf bank_mask:0xf
	v_fmac_f32_dpp v45, v215, v11 quad_perm:[1,1,1,1] row_mask:0xf bank_mask:0xf
	v_fmac_f32_dpp v30, v212, v12 quad_perm:[2,2,2,2] row_mask:0xf bank_mask:0xf
	v_fmac_f32_dpp v31, v213, v13 quad_perm:[2,2,2,2] row_mask:0xf bank_mask:0xf
	v_fmac_f32_dpp v44, v214, v16 quad_perm:[2,2,2,2] row_mask:0xf bank_mask:0xf
	v_fmac_f32_dpp v45, v215, v17 quad_perm:[2,2,2,2] row_mask:0xf bank_mask:0xf
	v_fmac_f32_dpp v30, v212, v20 quad_perm:[3,3,3,3] row_mask:0xf bank_mask:0xf
	v_fmac_f32_dpp v31, v213, v21 quad_perm:[3,3,3,3] row_mask:0xf bank_mask:0xf
	v_fmac_f32_dpp v44, v214, v22 quad_perm:[3,3,3,3] row_mask:0xf bank_mask:0xf
	v_fmac_f32_dpp v45, v215, v23 quad_perm:[3,3,3,3] row_mask:0xf bank_mask:0xf
	v_fmac_f32_dpp v30, v216, v24 quad_perm:[0,0,0,0] row_mask:0xf bank_mask:0xf
	v_fmac_f32_dpp v31, v217, v25 quad_perm:[0,0,0,0] row_mask:0xf bank_mask:0xf
	v_fmac_f32_dpp v44, v218, v26 quad_perm:[0,0,0,0] row_mask:0xf bank_mask:0xf
	v_fmac_f32_dpp v45, v219, v27 quad_perm:[0,0,0,0] row_mask:0xf bank_mask:0xf
	v_fmac_f32_dpp v30, v216, v36 quad_perm:[1,1,1,1] row_mask:0xf bank_mask:0xf
	v_fmac_f32_dpp v31, v217, v37 quad_perm:[1,1,1,1] row_mask:0xf bank_mask:0xf
	v_fmac_f32_dpp v44, v218, v38 quad_perm:[1,1,1,1] row_mask:0xf bank_mask:0xf
	v_fmac_f32_dpp v45, v219, v39 quad_perm:[1,1,1,1] row_mask:0xf bank_mask:0xf
	v_fmac_f32_dpp v30, v216, v42 quad_perm:[2,2,2,2] row_mask:0xf bank_mask:0xf
	v_fmac_f32_dpp v31, v217, v43 quad_perm:[2,2,2,2] row_mask:0xf bank_mask:0xf
	v_fmac_f32_dpp v44, v218, v46 quad_perm:[2,2,2,2] row_mask:0xf bank_mask:0xf
	v_fmac_f32_dpp v45, v219, v47 quad_perm:[2,2,2,2] row_mask:0xf bank_mask:0xf
	v_fmac_f32_dpp v30, v216, v50 quad_perm:[3,3,3,3] row_mask:0xf bank_mask:0xf
	v_fmac_f32_dpp v31, v217, v51 quad_perm:[3,3,3,3] row_mask:0xf bank_mask:0xf
	v_fmac_f32_dpp v44, v218, v54 quad_perm:[3,3,3,3] row_mask:0xf bank_mask:0xf
	v_fmac_f32_dpp v45, v219, v55 quad_perm:[3,3,3,3] row_mask:0xf bank_mask:0xf
	v_fmac_f32_dpp v30, v220, v56 quad_perm:[0,0,0,0] row_mask:0xf bank_mask:0xf
	v_fmac_f32_dpp v31, v221, v57 quad_perm:[0,0,0,0] row_mask:0xf bank_mask:0xf
	v_fmac_f32_dpp v44, v222, v60 quad_perm:[0,0,0,0] row_mask:0xf bank_mask:0xf
	v_fmac_f32_dpp v45, v223, v61 quad_perm:[0,0,0,0] row_mask:0xf bank_mask:0xf
	v_fmac_f32_dpp v30, v220, v64 quad_perm:[1,1,1,1] row_mask:0xf bank_mask:0xf
	v_fmac_f32_dpp v31, v221, v65 quad_perm:[1,1,1,1] row_mask:0xf bank_mask:0xf
	v_fmac_f32_dpp v44, v222, v68 quad_perm:[1,1,1,1] row_mask:0xf bank_mask:0xf
	v_fmac_f32_dpp v45, v223, v69 quad_perm:[1,1,1,1] row_mask:0xf bank_mask:0xf
	v_fmac_f32_dpp v30, v220, v70 quad_perm:[2,2,2,2] row_mask:0xf bank_mask:0xf
	v_fmac_f32_dpp v31, v221, v71 quad_perm:[2,2,2,2] row_mask:0xf bank_mask:0xf
	v_fmac_f32_dpp v44, v222, v74 quad_perm:[2,2,2,2] row_mask:0xf bank_mask:0xf
	v_fmac_f32_dpp v45, v223, v75 quad_perm:[2,2,2,2] row_mask:0xf bank_mask:0xf
	v_fmac_f32_dpp v30, v220, v78 quad_perm:[3,3,3,3] row_mask:0xf bank_mask:0xf
	v_fmac_f32_dpp v31, v221, v79 quad_perm:[3,3,3,3] row_mask:0xf bank_mask:0xf
	v_fmac_f32_dpp v44, v222, v76 quad_perm:[3,3,3,3] row_mask:0xf bank_mask:0xf
	v_fmac_f32_dpp v45, v223, v77 quad_perm:[3,3,3,3] row_mask:0xf bank_mask:0xf
	v_fmac_f32_dpp v30, v224, v72 quad_perm:[0,0,0,0] row_mask:0xf bank_mask:0xf
	v_fmac_f32_dpp v31, v225, v73 quad_perm:[0,0,0,0] row_mask:0xf bank_mask:0xf
	v_fmac_f32_dpp v44, v226, v66 quad_perm:[0,0,0,0] row_mask:0xf bank_mask:0xf
	v_fmac_f32_dpp v45, v227, v67 quad_perm:[0,0,0,0] row_mask:0xf bank_mask:0xf
	v_fmac_f32_dpp v30, v224, v48 quad_perm:[1,1,1,1] row_mask:0xf bank_mask:0xf
	v_fmac_f32_dpp v31, v225, v49 quad_perm:[1,1,1,1] row_mask:0xf bank_mask:0xf
	v_fmac_f32_dpp v44, v226, v40 quad_perm:[1,1,1,1] row_mask:0xf bank_mask:0xf
	v_fmac_f32_dpp v45, v227, v41 quad_perm:[1,1,1,1] row_mask:0xf bank_mask:0xf
	v_fmac_f32_dpp v30, v224, v28 quad_perm:[2,2,2,2] row_mask:0xf bank_mask:0xf
	v_fmac_f32_dpp v31, v225, v29 quad_perm:[2,2,2,2] row_mask:0xf bank_mask:0xf
	v_fmac_f32_dpp v44, v226, v14 quad_perm:[2,2,2,2] row_mask:0xf bank_mask:0xf
	v_fmac_f32_dpp v45, v227, v15 quad_perm:[2,2,2,2] row_mask:0xf bank_mask:0xf
	v_mov_b32_e32 v52, v30
	v_mov_b32_e32 v53, v44
	v_mov_b32_e32 v44, v31
	v_pk_add_f32 v[30:31], v[52:53], v[44:45]
	s_nop 0
	v_add_f32_e32 v19, v30, v31
	v_fmac_f32_dpp v19, v224, v4 quad_perm:[3,3,3,3] row_mask:0xf bank_mask:0xf
	v_sub_f32_e32 v5, v18, v19
	ds_read_b128 v[212:215], v228 offset:50944
	ds_read_b128 v[216:219], v228 offset:51008
	ds_read_b128 v[220:223], v228 offset:51072
	ds_read_b128 v[224:227], v228 offset:51136
	s_waitcnt lgkmcnt(4)
; DI void gdn_pre(const Params& p, int ch, char* smem) {
;     ...
; #pragma unroll
;   for (int i = 1; i < 64; ++i) {
;     f32x2 sa = {0.f, 0.f}, sb = {0.f, 0.f};
;     const f32x2* arow = (const f32x2*)(Amat + i * 64);
; #pragma unroll
;     for (int k = 0; k < (i >> 1); ++k) {
;       const f32x2 a2 = arow[k];
;       if (k & 1) sb = __builtin_elementwise_fma(a2, c2[k], sb);
;       else sa = __builtin_elementwise_fma(a2, c2[k], sa);
;     }
;     float tot = (sa[0] + sa[1]) + (sb[0] + sb[1]);
;     if (i & 1) tot += Amat[i * 64 + i - 1] * c2[(i - 1) >> 1][0];
;     c2[i >> 1][i & 1] -= tot;
;     __builtin_amdgcn_sched_barrier(0);
;   }
	v_mul_f32_dpp v18, v196, v0 quad_perm:[0,0,0,0] row_mask:0xf bank_mask:0xf
	v_mul_f32_dpp v19, v197, v1 quad_perm:[0,0,0,0] row_mask:0xf bank_mask:0xf
	v_mul_f32_dpp v30, v198, v6 quad_perm:[0,0,0,0] row_mask:0xf bank_mask:0xf
	v_mul_f32_dpp v31, v199, v7 quad_perm:[0,0,0,0] row_mask:0xf bank_mask:0xf
	v_fmac_f32_dpp v18, v196, v8 quad_perm:[1,1,1,1] row_mask:0xf bank_mask:0xf
	v_fmac_f32_dpp v19, v197, v9 quad_perm:[1,1,1,1] row_mask:0xf bank_mask:0xf
	v_fmac_f32_dpp v30, v198, v10 quad_perm:[1,1,1,1] row_mask:0xf bank_mask:0xf
	v_fmac_f32_dpp v31, v199, v11 quad_perm:[1,1,1,1] row_mask:0xf bank_mask:0xf
	v_fmac_f32_dpp v18, v196, v12 quad_perm:[2,2,2,2] row_mask:0xf bank_mask:0xf
	v_fmac_f32_dpp v19, v197, v13 quad_perm:[2,2,2,2] row_mask:0xf bank_mask:0xf
	v_fmac_f32_dpp v30, v198, v16 quad_perm:[2,2,2,2] row_mask:0xf bank_mask:0xf
	v_fmac_f32_dpp v31, v199, v17 quad_perm:[2,2,2,2] row_mask:0xf bank_mask:0xf
	v_fmac_f32_dpp v18, v196, v20 quad_perm:[3,3,3,3] row_mask:0xf bank_mask:0xf
	v_fmac_f32_dpp v19, v197, v21 quad_perm:[3,3,3,3] row_mask:0xf bank_mask:0xf
	v_fmac_f32_dpp v30, v198, v22 quad_perm:[3,3,3,3] row_mask:0xf bank_mask:0xf
	v_fmac_f32_dpp v31, v199, v23 quad_perm:[3,3,3,3] row_mask:0xf bank_mask:0xf
	v_fmac_f32_dpp v18, v200, v24 quad_perm:[0,0,0,0] row_mask:0xf bank_mask:0xf
	v_fmac_f32_dpp v19, v201, v25 quad_perm:[0,0,0,0] row_mask:0xf bank_mask:0xf
	v_fmac_f32_dpp v30, v202, v26 quad_perm:[0,0,0,0] row_mask:0xf bank_mask:0xf
	v_fmac_f32_dpp v31, v203, v27 quad_perm:[0,0,0,0] row_mask:0xf bank_mask:0xf
	v_fmac_f32_dpp v18, v200, v36 quad_perm:[1,1,1,1] row_mask:0xf bank_mask:0xf
	v_fmac_f32_dpp v19, v201, v37 quad_perm:[1,1,1,1] row_mask:0xf bank_mask:0xf
	v_fmac_f32_dpp v30, v202, v38 quad_perm:[1,1,1,1] row_mask:0xf bank_mask:0xf
	v_fmac_f32_dpp v31, v203, v39 quad_perm:[1,1,1,1] row_mask:0xf bank_mask:0xf
	v_fmac_f32_dpp v18, v200, v42 quad_perm:[2,2,2,2] row_mask:0xf bank_mask:0xf
	v_fmac_f32_dpp v19, v201, v43 quad_perm:[2,2,2,2] row_mask:0xf bank_mask:0xf
	v_fmac_f32_dpp v30, v202, v46 quad_perm:[2,2,2,2] row_mask:0xf bank_mask:0xf
	v_fmac_f32_dpp v31, v203, v47 quad_perm:[2,2,2,2] row_mask:0xf bank_mask:0xf
	v_fmac_f32_dpp v18, v200, v50 quad_perm:[3,3,3,3] row_mask:0xf bank_mask:0xf
	v_fmac_f32_dpp v19, v201, v51 quad_perm:[3,3,3,3] row_mask:0xf bank_mask:0xf
	v_fmac_f32_dpp v30, v202, v54 quad_perm:[3,3,3,3] row_mask:0xf bank_mask:0xf
	v_fmac_f32_dpp v31, v203, v55 quad_perm:[3,3,3,3] row_mask:0xf bank_mask:0xf
	v_fmac_f32_dpp v18, v204, v56 quad_perm:[0,0,0,0] row_mask:0xf bank_mask:0xf
	v_fmac_f32_dpp v19, v205, v57 quad_perm:[0,0,0,0] row_mask:0xf bank_mask:0xf
	v_fmac_f32_dpp v30, v206, v60 quad_perm:[0,0,0,0] row_mask:0xf bank_mask:0xf
	v_fmac_f32_dpp v31, v207, v61 quad_perm:[0,0,0,0] row_mask:0xf bank_mask:0xf
	v_fmac_f32_dpp v18, v204, v64 quad_perm:[1,1,1,1] row_mask:0xf bank_mask:0xf
	v_fmac_f32_dpp v19, v205, v65 quad_perm:[1,1,1,1] row_mask:0xf bank_mask:0xf
	v_fmac_f32_dpp v30, v206, v68 quad_perm:[1,1,1,1] row_mask:0xf bank_mask:0xf
	v_fmac_f32_dpp v31, v207, v69 quad_perm:[1,1,1,1] row_mask:0xf bank_mask:0xf
	v_fmac_f32_dpp v18, v204, v70 quad_perm:[2,2,2,2] row_mask:0xf bank_mask:0xf
	v_fmac_f32_dpp v19, v205, v71 quad_perm:[2,2,2,2] row_mask:0xf bank_mask:0xf
	v_fmac_f32_dpp v30, v206, v74 quad_perm:[2,2,2,2] row_mask:0xf bank_mask:0xf
	v_fmac_f32_dpp v31, v207, v75 quad_perm:[2,2,2,2] row_mask:0xf bank_mask:0xf
	v_fmac_f32_dpp v18, v204, v78 quad_perm:[3,3,3,3] row_mask:0xf bank_mask:0xf
	v_fmac_f32_dpp v19, v205, v79 quad_perm:[3,3,3,3] row_mask:0xf bank_mask:0xf
	v_fmac_f32_dpp v30, v206, v76 quad_perm:[3,3,3,3] row_mask:0xf bank_mask:0xf
	v_fmac_f32_dpp v31, v207, v77 quad_perm:[3,3,3,3] row_mask:0xf bank_mask:0xf
	v_fmac_f32_dpp v18, v208, v72 quad_perm:[0,0,0,0] row_mask:0xf bank_mask:0xf
	v_fmac_f32_dpp v19, v209, v73 quad_perm:[0,0,0,0] row_mask:0xf bank_mask:0xf
	v_fmac_f32_dpp v30, v210, v66 quad_perm:[0,0,0,0] row_mask:0xf bank_mask:0xf
	v_fmac_f32_dpp v31, v211, v67 quad_perm:[0,0,0,0] row_mask:0xf bank_mask:0xf
	v_fmac_f32_dpp v18, v208, v48 quad_perm:[1,1,1,1] row_mask:0xf bank_mask:0xf
	v_fmac_f32_dpp v19, v209, v49 quad_perm:[1,1,1,1] row_mask:0xf bank_mask:0xf
	v_fmac_f32_dpp v30, v210, v40 quad_perm:[1,1,1,1] row_mask:0xf bank_mask:0xf
	v_fmac_f32_dpp v31, v211, v41 quad_perm:[1,1,1,1] row_mask:0xf bank_mask:0xf
	v_fmac_f32_dpp v18, v208, v28 quad_perm:[2,2,2,2] row_mask:0xf bank_mask:0xf
	v_fmac_f32_dpp v19, v209, v29 quad_perm:[2,2,2,2] row_mask:0xf bank_mask:0xf
	v_fmac_f32_dpp v30, v210, v14 quad_perm:[2,2,2,2] row_mask:0xf bank_mask:0xf
	v_fmac_f32_dpp v31, v211, v15 quad_perm:[2,2,2,2] row_mask:0xf bank_mask:0xf
	v_fmac_f32_dpp v18, v208, v4 quad_perm:[3,3,3,3] row_mask:0xf bank_mask:0xf
	v_fmac_f32_dpp v19, v209, v5 quad_perm:[3,3,3,3] row_mask:0xf bank_mask:0xf
	v_pk_add_f32 v[30:31], v[30:31], v[30:31] op_sel:[0,1] op_sel_hi:[1,0]
	v_pk_add_f32 v[18:19], v[18:19], v[18:19] op_sel:[0,1] op_sel_hi:[1,0]
	s_nop 0
	v_pk_add_f32 v[18:19], v[30:31], v[18:19]
	s_nop 0
	v_pk_add_f32 v[18:19], v[2:3], v[18:19] neg_lo:[0,1] neg_hi:[0,1]
	s_waitcnt lgkmcnt(0)
; DI void gdn_pre(const Params& p, int ch, char* smem) {
;     ...
; #pragma unroll
;   for (int i = 1; i < 64; ++i) {
;     f32x2 sa = {0.f, 0.f}, sb = {0.f, 0.f};
;     const f32x2* arow = (const f32x2*)(Amat + i * 64);
; #pragma unroll
;     for (int k = 0; k < (i >> 1); ++k) {
;       const f32x2 a2 = arow[k];
;       if (k & 1) sb = __builtin_elementwise_fma(a2, c2[k], sb);
;       else sa = __builtin_elementwise_fma(a2, c2[k], sa);
;     }
;     float tot = (sa[0] + sa[1]) + (sb[0] + sb[1]);
;     if (i & 1) tot += Amat[i * 64 + i - 1] * c2[(i - 1) >> 1][0];
;     c2[i >> 1][i & 1] -= tot;
;     __builtin_amdgcn_sched_barrier(0);
;   }
	v_mul_f32_dpp v30, v212, v0 quad_perm:[0,0,0,0] row_mask:0xf bank_mask:0xf
	v_mul_f32_dpp v31, v213, v1 quad_perm:[0,0,0,0] row_mask:0xf bank_mask:0xf
	v_mul_f32_dpp v44, v214, v6 quad_perm:[0,0,0,0] row_mask:0xf bank_mask:0xf
	v_mul_f32_dpp v45, v215, v7 quad_perm:[0,0,0,0] row_mask:0xf bank_mask:0xf
	v_fmac_f32_dpp v30, v212, v8 quad_perm:[1,1,1,1] row_mask:0xf bank_mask:0xf
	v_fmac_f32_dpp v31, v213, v9 quad_perm:[1,1,1,1] row_mask:0xf bank_mask:0xf
	v_fmac_f32_dpp v44, v214, v10 quad_perm:[1,1,1,1] row_mask:0xf bank_mask:0xf
	v_fmac_f32_dpp v45, v215, v11 quad_perm:[1,1,1,1] row_mask:0xf bank_mask:0xf
	v_fmac_f32_dpp v30, v212, v12 quad_perm:[2,2,2,2] row_mask:0xf bank_mask:0xf
	v_fmac_f32_dpp v31, v213, v13 quad_perm:[2,2,2,2] row_mask:0xf bank_mask:0xf
	v_fmac_f32_dpp v44, v214, v16 quad_perm:[2,2,2,2] row_mask:0xf bank_mask:0xf
	v_fmac_f32_dpp v45, v215, v17 quad_perm:[2,2,2,2] row_mask:0xf bank_mask:0xf
	v_fmac_f32_dpp v30, v212, v20 quad_perm:[3,3,3,3] row_mask:0xf bank_mask:0xf
	v_fmac_f32_dpp v31, v213, v21 quad_perm:[3,3,3,3] row_mask:0xf bank_mask:0xf
	v_fmac_f32_dpp v44, v214, v22 quad_perm:[3,3,3,3] row_mask:0xf bank_mask:0xf
	v_fmac_f32_dpp v45, v215, v23 quad_perm:[3,3,3,3] row_mask:0xf bank_mask:0xf
	v_fmac_f32_dpp v30, v216, v24 quad_perm:[0,0,0,0] row_mask:0xf bank_mask:0xf
	v_fmac_f32_dpp v31, v217, v25 quad_perm:[0,0,0,0] row_mask:0xf bank_mask:0xf
	v_fmac_f32_dpp v44, v218, v26 quad_perm:[0,0,0,0] row_mask:0xf bank_mask:0xf
	v_fmac_f32_dpp v45, v219, v27 quad_perm:[0,0,0,0] row_mask:0xf bank_mask:0xf
	v_fmac_f32_dpp v30, v216, v36 quad_perm:[1,1,1,1] row_mask:0xf bank_mask:0xf
	v_fmac_f32_dpp v31, v217, v37 quad_perm:[1,1,1,1] row_mask:0xf bank_mask:0xf
	v_fmac_f32_dpp v44, v218, v38 quad_perm:[1,1,1,1] row_mask:0xf bank_mask:0xf
	v_fmac_f32_dpp v45, v219, v39 quad_perm:[1,1,1,1] row_mask:0xf bank_mask:0xf
	v_fmac_f32_dpp v30, v216, v42 quad_perm:[2,2,2,2] row_mask:0xf bank_mask:0xf
	v_fmac_f32_dpp v31, v217, v43 quad_perm:[2,2,2,2] row_mask:0xf bank_mask:0xf
	v_fmac_f32_dpp v44, v218, v46 quad_perm:[2,2,2,2] row_mask:0xf bank_mask:0xf
	v_fmac_f32_dpp v45, v219, v47 quad_perm:[2,2,2,2] row_mask:0xf bank_mask:0xf
	v_fmac_f32_dpp v30, v216, v50 quad_perm:[3,3,3,3] row_mask:0xf bank_mask:0xf
	v_fmac_f32_dpp v31, v217, v51 quad_perm:[3,3,3,3] row_mask:0xf bank_mask:0xf
	v_fmac_f32_dpp v44, v218, v54 quad_perm:[3,3,3,3] row_mask:0xf bank_mask:0xf
	v_fmac_f32_dpp v45, v219, v55 quad_perm:[3,3,3,3] row_mask:0xf bank_mask:0xf
	v_fmac_f32_dpp v30, v220, v56 quad_perm:[0,0,0,0] row_mask:0xf bank_mask:0xf
	v_fmac_f32_dpp v31, v221, v57 quad_perm:[0,0,0,0] row_mask:0xf bank_mask:0xf
	v_fmac_f32_dpp v44, v222, v60 quad_perm:[0,0,0,0] row_mask:0xf bank_mask:0xf
	v_fmac_f32_dpp v45, v223, v61 quad_perm:[0,0,0,0] row_mask:0xf bank_mask:0xf
	v_fmac_f32_dpp v30, v220, v64 quad_perm:[1,1,1,1] row_mask:0xf bank_mask:0xf
	v_fmac_f32_dpp v31, v221, v65 quad_perm:[1,1,1,1] row_mask:0xf bank_mask:0xf
	v_fmac_f32_dpp v44, v222, v68 quad_perm:[1,1,1,1] row_mask:0xf bank_mask:0xf
	v_fmac_f32_dpp v45, v223, v69 quad_perm:[1,1,1,1] row_mask:0xf bank_mask:0xf
	v_fmac_f32_dpp v30, v220, v70 quad_perm:[2,2,2,2] row_mask:0xf bank_mask:0xf
	v_fmac_f32_dpp v31, v221, v71 quad_perm:[2,2,2,2] row_mask:0xf bank_mask:0xf
	v_fmac_f32_dpp v44, v222, v74 quad_perm:[2,2,2,2] row_mask:0xf bank_mask:0xf
	v_fmac_f32_dpp v45, v223, v75 quad_perm:[2,2,2,2] row_mask:0xf bank_mask:0xf
	v_fmac_f32_dpp v30, v220, v78 quad_perm:[3,3,3,3] row_mask:0xf bank_mask:0xf
	v_fmac_f32_dpp v31, v221, v79 quad_perm:[3,3,3,3] row_mask:0xf bank_mask:0xf
	v_fmac_f32_dpp v44, v222, v76 quad_perm:[3,3,3,3] row_mask:0xf bank_mask:0xf
	v_fmac_f32_dpp v45, v223, v77 quad_perm:[3,3,3,3] row_mask:0xf bank_mask:0xf
	v_fmac_f32_dpp v30, v224, v72 quad_perm:[0,0,0,0] row_mask:0xf bank_mask:0xf
	v_fmac_f32_dpp v31, v225, v73 quad_perm:[0,0,0,0] row_mask:0xf bank_mask:0xf
	v_fmac_f32_dpp v44, v226, v66 quad_perm:[0,0,0,0] row_mask:0xf bank_mask:0xf
	v_fmac_f32_dpp v45, v227, v67 quad_perm:[0,0,0,0] row_mask:0xf bank_mask:0xf
	v_fmac_f32_dpp v30, v224, v48 quad_perm:[1,1,1,1] row_mask:0xf bank_mask:0xf
	v_fmac_f32_dpp v31, v225, v49 quad_perm:[1,1,1,1] row_mask:0xf bank_mask:0xf
	v_fmac_f32_dpp v44, v226, v40 quad_perm:[1,1,1,1] row_mask:0xf bank_mask:0xf
	v_fmac_f32_dpp v45, v227, v41 quad_perm:[1,1,1,1] row_mask:0xf bank_mask:0xf
	v_fmac_f32_dpp v30, v224, v28 quad_perm:[2,2,2,2] row_mask:0xf bank_mask:0xf
	v_fmac_f32_dpp v31, v225, v29 quad_perm:[2,2,2,2] row_mask:0xf bank_mask:0xf
	v_fmac_f32_dpp v44, v226, v14 quad_perm:[2,2,2,2] row_mask:0xf bank_mask:0xf
	v_fmac_f32_dpp v45, v227, v15 quad_perm:[2,2,2,2] row_mask:0xf bank_mask:0xf
	v_fmac_f32_dpp v30, v224, v4 quad_perm:[3,3,3,3] row_mask:0xf bank_mask:0xf
	v_fmac_f32_dpp v31, v225, v5 quad_perm:[3,3,3,3] row_mask:0xf bank_mask:0xf
	v_add_f32_e32 v19, v44, v45
	v_add_f32_e32 v2, v30, v31
	v_add_f32_e32 v2, v19, v2
	v_fmac_f32_dpp v2, v226, v18 quad_perm:[3,3,3,3] row_mask:0xf bank_mask:0xf
	v_sub_f32_e32 v2, v3, v2
	s_and_saveexec_b64 s[0:1], vcc
	s_xor_b64 s[6:7], exec, s[0:1]
	s_cbranch_execz .LBB0_370
; DI bf16_t f2bf(float f) { return (bf16_t)(pk2(f, 0.f) & 0xffffu); }
; DI int fragoff(int row, int k, int KS) { return (((row >> 4) * KS + (k >> 5)) << 9) + (((((k >> 3) & 3) << 4) + (row & 15)) << 3) + (k & 7); }
; DI void gdn_pre(const Params& p, int ch, char* smem) {
;     ...
;   } else {
;     const int cc = tid - 128;
; #pragma unroll
;     for (int tt = 0; tt < 64; ++tt) o_w[fragoff(tt, cc, 4)] = f2bf(c2[tt >> 1][tt & 1]);
;   }
	v_lshlrev_b32_e32 v3, 4, v34
	v_cvt_pk_bf16_f32 v0, v0, s0
	s_movk_i32 s0, 0xfe00
	v_and_b32_e32 v19, 0x180, v3
	v_and_or_b32 v3, v3, s0, v32
	v_add_u32_e32 v32, 0xfffff800, v3
	v_or_b32_e32 v30, v32, v19
	v_ashrrev_i32_e32 v31, 31, v30
	v_lshl_add_u64 v[44:45], v[30:31], 1, s[34:35]
	v_ashrrev_i32_e32 v31, 31, v32
	global_store_short v[44:45], v0, off
	v_cvt_pk_bf16_f32 v35, v1, s0
	v_lshl_add_u64 v[0:1], v[30:31], 1, s[34:35]
	v_cvt_pk_bf16_f32 v6, v6, s0
	global_store_short v[0:1], v6, off offset:32
	v_cvt_pk_bf16_f32 v6, v7, s0
	global_store_short v[0:1], v6, off offset:48
	v_cvt_pk_bf16_f32 v6, v8, s0
	global_store_short v[0:1], v6, off offset:64
	v_cvt_pk_bf16_f32 v6, v9, s0
	global_store_short v[0:1], v6, off offset:80
	v_cvt_pk_bf16_f32 v6, v10, s0
	global_store_short v[0:1], v6, off offset:96
	v_cvt_pk_bf16_f32 v6, v11, s0
	global_store_short v[0:1], v6, off offset:112
	v_cvt_pk_bf16_f32 v6, v12, s0
	global_store_short v[0:1], v6, off offset:128
	v_cvt_pk_bf16_f32 v6, v13, s0
	global_store_short v[0:1], v6, off offset:144
	v_cvt_pk_bf16_f32 v6, v16, s0
	global_store_short v[0:1], v6, off offset:160
	v_cvt_pk_bf16_f32 v6, v17, s0
	global_store_short v[0:1], v6, off offset:176
	v_cvt_pk_bf16_f32 v6, v20, s0
	global_store_short v[0:1], v6, off offset:192
	v_cvt_pk_bf16_f32 v6, v21, s0
	global_store_short v[0:1], v6, off offset:208
	v_cvt_pk_bf16_f32 v6, v22, s0
	global_store_short v[0:1], v6, off offset:224
	v_cvt_pk_bf16_f32 v6, v23, s0
	global_store_short v[0:1], v35, off offset:16
	global_store_short v[0:1], v6, off offset:240
	v_or_b32_e32 v0, v3, v19
	v_ashrrev_i32_e32 v1, 31, v0
	v_cvt_pk_bf16_f32 v8, v24, s0
	v_lshl_add_u64 v[6:7], v[0:1], 1, s[34:35]
	v_ashrrev_i32_e32 v1, 31, v3
	global_store_short v[6:7], v8, off
	v_cvt_pk_bf16_f32 v6, v25, s0
	v_lshl_add_u64 v[0:1], v[0:1], 1, s[34:35]
	global_store_short v[0:1], v6, off offset:16
	v_cvt_pk_bf16_f32 v6, v26, s0
	global_store_short v[0:1], v6, off offset:32
	v_cvt_pk_bf16_f32 v6, v27, s0
	global_store_short v[0:1], v6, off offset:48
	v_cvt_pk_bf16_f32 v6, v36, s0
	global_store_short v[0:1], v6, off offset:64
	v_cvt_pk_bf16_f32 v6, v37, s0
	global_store_short v[0:1], v6, off offset:80
	v_cvt_pk_bf16_f32 v6, v38, s0
	global_store_short v[0:1], v6, off offset:96
	v_cvt_pk_bf16_f32 v6, v39, s0
	global_store_short v[0:1], v6, off offset:112
	v_cvt_pk_bf16_f32 v6, v42, s0
	global_store_short v[0:1], v6, off offset:128
	v_cvt_pk_bf16_f32 v6, v43, s0
	global_store_short v[0:1], v6, off offset:144
	v_cvt_pk_bf16_f32 v6, v46, s0
	global_store_short v[0:1], v6, off offset:160
	v_cvt_pk_bf16_f32 v6, v47, s0
	global_store_short v[0:1], v6, off offset:176
	v_cvt_pk_bf16_f32 v6, v50, s0
	global_store_short v[0:1], v6, off offset:192
	v_cvt_pk_bf16_f32 v6, v51, s0
	global_store_short v[0:1], v6, off offset:208
	v_cvt_pk_bf16_f32 v6, v54, s0
	global_store_short v[0:1], v6, off offset:224
	v_cvt_pk_bf16_f32 v6, v55, s0
	v_add_u32_e32 v9, 0x800, v3
	global_store_short v[0:1], v6, off offset:240
	v_or_b32_e32 v0, v9, v19
	v_ashrrev_i32_e32 v1, 31, v0
	v_cvt_pk_bf16_f32 v8, v56, s0
	v_lshl_add_u64 v[6:7], v[0:1], 1, s[34:35]
	v_ashrrev_i32_e32 v1, 31, v9
	global_store_short v[6:7], v8, off
	v_cvt_pk_bf16_f32 v6, v57, s0
	v_lshl_add_u64 v[0:1], v[0:1], 1, s[34:35]
	global_store_short v[0:1], v6, off offset:16
	v_cvt_pk_bf16_f32 v6, v60, s0
	global_store_short v[0:1], v6, off offset:32
	v_cvt_pk_bf16_f32 v6, v61, s0
	global_store_short v[0:1], v6, off offset:48
	v_cvt_pk_bf16_f32 v6, v64, s0
	global_store_short v[0:1], v6, off offset:64
	v_cvt_pk_bf16_f32 v6, v65, s0
	global_store_short v[0:1], v6, off offset:80
	v_cvt_pk_bf16_f32 v6, v68, s0
	global_store_short v[0:1], v6, off offset:96
	v_cvt_pk_bf16_f32 v6, v69, s0
	global_store_short v[0:1], v6, off offset:112
	v_cvt_pk_bf16_f32 v6, v70, s0
	global_store_short v[0:1], v6, off offset:128
	v_cvt_pk_bf16_f32 v6, v71, s0
	global_store_short v[0:1], v6, off offset:144
	v_cvt_pk_bf16_f32 v6, v74, s0
	global_store_short v[0:1], v6, off offset:160
	v_cvt_pk_bf16_f32 v6, v75, s0
	global_store_short v[0:1], v6, off offset:176
	v_cvt_pk_bf16_f32 v6, v78, s0
	global_store_short v[0:1], v6, off offset:192
	v_cvt_pk_bf16_f32 v6, v79, s0
	global_store_short v[0:1], v6, off offset:208
	v_cvt_pk_bf16_f32 v6, v76, s0
	global_store_short v[0:1], v6, off offset:224
	v_cvt_pk_bf16_f32 v6, v77, s0
	v_add_u32_e32 v3, 0x1000, v3
	global_store_short v[0:1], v6, off offset:240
	v_or_b32_e32 v0, v3, v19
	v_ashrrev_i32_e32 v1, 31, v0
	v_lshl_add_u64 v[6:7], v[0:1], 1, s[34:35]
	v_ashrrev_i32_e32 v1, 31, v3
	v_cvt_pk_bf16_f32 v8, v72, s0
	v_lshl_add_u64 v[0:1], v[0:1], 1, s[34:35]
	v_cvt_pk_bf16_f32 v3, v66, s0
	global_store_short v[6:7], v8, off
	global_store_short v[0:1], v3, off offset:32
	v_cvt_pk_bf16_f32 v3, v67, s0
	global_store_short v[0:1], v3, off offset:48
	v_cvt_pk_bf16_f32 v3, v48, s0
	global_store_short v[0:1], v3, off offset:64
	v_cvt_pk_bf16_f32 v3, v49, s0
	global_store_short v[0:1], v3, off offset:80
	v_cvt_pk_bf16_f32 v3, v40, s0
	global_store_short v[0:1], v3, off offset:96
	v_cvt_pk_bf16_f32 v3, v41, s0
	global_store_short v[0:1], v3, off offset:112
	v_cvt_pk_bf16_f32 v3, v28, s0
	global_store_short v[0:1], v3, off offset:128
	v_cvt_pk_bf16_f32 v3, v29, s0
	global_store_short v[0:1], v3, off offset:144
	v_cvt_pk_bf16_f32 v3, v14, s0
	global_store_short v[0:1], v3, off offset:160
	v_cvt_pk_bf16_f32 v3, v15, s0
	global_store_short v[0:1], v3, off offset:176
	v_cvt_pk_bf16_f32 v3, v4, s0
	global_store_short v[0:1], v3, off offset:192
	v_cvt_pk_bf16_f32 v3, v5, s0
	v_cvt_pk_bf16_f32 v6, v73, s0
	global_store_short v[0:1], v3, off offset:208
	v_cvt_pk_bf16_f32 v3, v18, s0
	v_cvt_pk_bf16_f32 v2, v2, s0
	global_store_short v[0:1], v6, off offset:16
	global_store_short v[0:1], v3, off offset:224
	global_store_short v[0:1], v2, off offset:240
